# v20 + software-pipelined LDS fragment reads in all 25 GEMM k-loops (ping-pong fragment registers v236-v253)
# speedup vs baseline: 1.1251x; 1.0111x over previous
; DEV int stage_next(int s) { return (s == 2 * GS_STAGE) ? 0 : s + GS_STAGE; }
; template <int WAIT0>
; DEV void gk_main(f32x16 (&acc)[2][2], const GTile& t, int s0) {
;     ...
;   vm_wait_bar<WAIT0>();
;   int stc = s0, std_ = stage_next(stage_next(s0));
; #pragma nounroll
;   for (int kt = 0; kt < nk - 2; ++kt) {
;     GK_DMA(std_, kt + 2);
;     GK_COMPUTE(stc);
;     vm_wait_bar<6>();
;     stc = stage_next(stc); std_ = stage_next(std_);
;   }
.LBB0_75:
	s_add_i32 s21, s19, s20
	v_lshl_add_u64 v[84:85], v[64:65], 0, s[6:7]
	s_mov_b32 m0, s21
	v_lshl_add_u64 v[86:87], v[66:67], 0, s[6:7]
	global_load_lds_dwordx4 v[84:85], off
	s_add_i32 m0, s21, 0x2000
	v_lshl_add_u64 v[88:89], v[68:69], 0, s[6:7]
	global_load_lds_dwordx4 v[86:87], off
	s_add_i32 m0, s21, 0x4000
	v_lshl_add_u64 v[90:91], v[70:71], 0, s[6:7]
	global_load_lds_dwordx4 v[88:89], off
	s_add_i32 m0, s21, 0x6000
	v_lshl_add_u64 v[92:93], v[72:73], 0, s[6:7]
	global_load_lds_dwordx4 v[90:91], off
	s_add_i32 m0, s21, 0x8000
	v_lshl_add_u64 v[94:95], v[74:75], 0, s[6:7]
	global_load_lds_dwordx4 v[92:93], off
	s_add_i32 m0, s21, 0xa000
	s_add_i32 s27, s18, 0
	global_load_lds_dwordx4 v[94:95], off
	v_add_u32_e32 v100, s27, v82
	v_add_u32_e32 v101, s27, v83
	ds_read_b128 v[84:87], v101 offset:16384
	ds_read_b128 v[88:91], v100
	ds_read_b128 v[92:95], v100 offset:4096
	s_waitcnt lgkmcnt(0)
	v_add_u32_e32 v100, s27, v80
	s_add_i32 s21, s18, 0xc000
	s_cmp_lg_u32 s18, 0x18000
	s_cselect_b32 s18, s21, 0
	s_add_i32 s21, s20, 0xc000
	s_cmp_lg_u32 s20, 0x18000
	s_cselect_b32 s20, s21, 0
	ds_read_b128 v[236:239], v101 offset:20480
	v_mfma_f32_32x32x16_bf16 v[48:63], v[84:87], v[88:91], v[48:63]
	v_mfma_f32_32x32x16_bf16 v[16:31], v[84:87], v[92:95], v[16:31]
	v_add_u32_e32 v101, s27, v81
	s_add_u32 s6, s6, 0x80
	s_addc_u32 s7, s7, 0
	s_cmpk_lg_i32 s6, 0x700
	s_waitcnt lgkmcnt(0)
	ds_read_b128 v[84:87], v101 offset:16384
	ds_read_b128 v[240:243], v100
	ds_read_b128 v[244:247], v100 offset:4096
	v_mfma_f32_32x32x16_bf16 v[32:47], v[236:239], v[88:91], v[32:47]
	v_mfma_f32_32x32x16_bf16 v[0:15], v[236:239], v[92:95], v[0:15]
	v_add_u32_e32 v100, s27, v78
	s_waitcnt lgkmcnt(0)
	ds_read_b128 v[236:239], v101 offset:20480
	v_mfma_f32_32x32x16_bf16 v[48:63], v[84:87], v[240:243], v[48:63]
	v_mfma_f32_32x32x16_bf16 v[16:31], v[84:87], v[244:247], v[16:31]
	v_add_u32_e32 v101, s27, v79
	s_waitcnt lgkmcnt(0)
	ds_read_b128 v[84:87], v101 offset:16384
	ds_read_b128 v[88:91], v100
	ds_read_b128 v[92:95], v100 offset:4096
	v_mfma_f32_32x32x16_bf16 v[32:47], v[236:239], v[240:243], v[32:47]
	v_mfma_f32_32x32x16_bf16 v[0:15], v[236:239], v[244:247], v[0:15]
	v_add_u32_e32 v100, s27, v76
	s_waitcnt lgkmcnt(0)
	ds_read_b128 v[236:239], v101 offset:20480
	v_mfma_f32_32x32x16_bf16 v[48:63], v[84:87], v[88:91], v[48:63]
	v_mfma_f32_32x32x16_bf16 v[16:31], v[84:87], v[92:95], v[16:31]
	v_add_u32_e32 v101, s27, v77
	s_waitcnt lgkmcnt(0)
	ds_read_b128 v[84:87], v101 offset:16384
	ds_read_b128 v[240:243], v100
	ds_read_b128 v[244:247], v100 offset:4096
	v_mfma_f32_32x32x16_bf16 v[32:47], v[236:239], v[88:91], v[32:47]
	v_mfma_f32_32x32x16_bf16 v[0:15], v[236:239], v[92:95], v[0:15]
	s_waitcnt lgkmcnt(0)
	ds_read_b128 v[236:239], v101 offset:20480
	v_mfma_f32_32x32x16_bf16 v[48:63], v[84:87], v[240:243], v[48:63]
	v_mfma_f32_32x32x16_bf16 v[16:31], v[84:87], v[244:247], v[16:31]
	s_waitcnt vmcnt(6) lgkmcnt(0)
	s_barrier
	s_waitcnt lgkmcnt(0)
	v_mfma_f32_32x32x16_bf16 v[32:47], v[236:239], v[240:243], v[32:47]
	v_mfma_f32_32x32x16_bf16 v[0:15], v[236:239], v[244:247], v[0:15]
	s_cbranch_scc1 .LBB0_75
; DEV int stage_next(int s) { return (s == 2 * GS_STAGE) ? 0 : s + GS_STAGE; }
; template <int WAIT0>
; DEV void gk_main(f32x16 (&acc)[2][2], const GTile& t, int s0) {
;     ...
;   GK_COMPUTE(stc);
;   vm_wait_bar<0>();
;   stc = stage_next(stc);
;   GK_COMPUTE(stc);
;   vm_wait_bar<0>();
	s_add_i32 s6, s18, 0
	v_add_u32_e32 v84, s6, v83
	ds_read_b128 v[64:67], v84 offset:16384
	v_add_u32_e32 v72, s6, v82
	ds_read_b128 v[68:71], v72
	ds_read_b128 v[72:75], v72 offset:4096
	s_waitcnt lgkmcnt(0)
	v_mfma_f32_32x32x16_bf16 v[48:63], v[64:67], v[68:71], v[48:63]
	v_mfma_f32_32x32x16_bf16 v[16:31], v[64:67], v[72:75], v[16:31]
	ds_read_b128 v[64:67], v84 offset:20480
	v_add_u32_e32 v84, s6, v81
	s_waitcnt lgkmcnt(0)
	v_mfma_f32_32x32x16_bf16 v[32:47], v[64:67], v[68:71], v[32:47]
	v_mfma_f32_32x32x16_bf16 v[0:15], v[64:67], v[72:75], v[0:15]
	ds_read_b128 v[64:67], v84 offset:16384
	v_add_u32_e32 v72, s6, v80
	ds_read_b128 v[68:71], v72
	ds_read_b128 v[72:75], v72 offset:4096
	s_waitcnt lgkmcnt(0)
	v_mfma_f32_32x32x16_bf16 v[48:63], v[64:67], v[68:71], v[48:63]
	v_mfma_f32_32x32x16_bf16 v[16:31], v[64:67], v[72:75], v[16:31]
	ds_read_b128 v[64:67], v84 offset:20480
	v_add_u32_e32 v84, s6, v79
	s_waitcnt lgkmcnt(0)
	v_mfma_f32_32x32x16_bf16 v[32:47], v[64:67], v[68:71], v[32:47]
	v_mfma_f32_32x32x16_bf16 v[0:15], v[64:67], v[72:75], v[0:15]
	ds_read_b128 v[64:67], v84 offset:16384
	v_add_u32_e32 v72, s6, v78
	ds_read_b128 v[68:71], v72
	ds_read_b128 v[72:75], v72 offset:4096
	s_waitcnt lgkmcnt(0)
	v_mfma_f32_32x32x16_bf16 v[48:63], v[64:67], v[68:71], v[48:63]
	v_mfma_f32_32x32x16_bf16 v[16:31], v[64:67], v[72:75], v[16:31]
	ds_read_b128 v[64:67], v84 offset:20480
	v_add_u32_e32 v84, s6, v77
	s_waitcnt lgkmcnt(0)
	v_mfma_f32_32x32x16_bf16 v[32:47], v[64:67], v[68:71], v[32:47]
	v_mfma_f32_32x32x16_bf16 v[0:15], v[64:67], v[72:75], v[0:15]
	ds_read_b128 v[64:67], v84 offset:16384
	v_add_u32_e32 v72, s6, v76
	ds_read_b128 v[68:71], v72
	ds_read_b128 v[72:75], v72 offset:4096
	s_add_i32 s6, s18, 0xc000
	s_cmp_lg_u32 s18, 0x18000
	s_cselect_b32 s6, s6, 0
	s_waitcnt lgkmcnt(0)
	v_mfma_f32_32x32x16_bf16 v[48:63], v[64:67], v[68:71], v[48:63]
	s_add_i32 s6, s6, 0
	v_add_u32_e32 v83, s6, v83
	v_add_u32_e32 v81, s6, v81
	v_add_u32_e32 v79, s6, v79
	v_add_u32_e32 v77, s6, v77
	v_mfma_f32_32x32x16_bf16 v[16:31], v[64:67], v[72:75], v[16:31]
	ds_read_b128 v[64:67], v84 offset:20480
	s_waitcnt vmcnt(0) lgkmcnt(0)
	s_barrier
	s_waitcnt lgkmcnt(0)
	v_mfma_f32_32x32x16_bf16 v[32:47], v[64:67], v[68:71], v[32:47]
	v_mfma_f32_32x32x16_bf16 v[0:15], v[64:67], v[72:75], v[0:15]
	ds_read_b128 v[64:67], v83 offset:16384
	v_add_u32_e32 v72, s6, v82
	ds_read_b128 v[68:71], v72
	ds_read_b128 v[72:75], v72 offset:4096
	s_waitcnt lgkmcnt(0)
	v_mfma_f32_32x32x16_bf16 v[48:63], v[64:67], v[68:71], v[48:63]
	v_mfma_f32_32x32x16_bf16 v[16:31], v[64:67], v[72:75], v[16:31]
	ds_read_b128 v[64:67], v83 offset:20480
	s_waitcnt lgkmcnt(0)
	v_mfma_f32_32x32x16_bf16 v[32:47], v[64:67], v[68:71], v[32:47]
	v_mfma_f32_32x32x16_bf16 v[0:15], v[64:67], v[72:75], v[0:15]
	ds_read_b128 v[64:67], v81 offset:16384
	v_add_u32_e32 v72, s6, v80
	ds_read_b128 v[68:71], v72
	ds_read_b128 v[72:75], v72 offset:4096
	s_waitcnt lgkmcnt(0)
	v_mfma_f32_32x32x16_bf16 v[48:63], v[64:67], v[68:71], v[48:63]
	v_mfma_f32_32x32x16_bf16 v[16:31], v[64:67], v[72:75], v[16:31]
	ds_read_b128 v[64:67], v81 offset:20480
	s_waitcnt lgkmcnt(0)
	v_mfma_f32_32x32x16_bf16 v[32:47], v[64:67], v[68:71], v[32:47]
	v_mfma_f32_32x32x16_bf16 v[0:15], v[64:67], v[72:75], v[0:15]
	ds_read_b128 v[64:67], v79 offset:16384
	v_add_u32_e32 v72, s6, v78
	ds_read_b128 v[68:71], v72
	ds_read_b128 v[72:75], v72 offset:4096
	s_waitcnt lgkmcnt(0)
	v_mfma_f32_32x32x16_bf16 v[48:63], v[64:67], v[68:71], v[48:63]
	v_mfma_f32_32x32x16_bf16 v[16:31], v[64:67], v[72:75], v[16:31]
	ds_read_b128 v[64:67], v79 offset:20480
	s_waitcnt lgkmcnt(0)
	v_mfma_f32_32x32x16_bf16 v[32:47], v[64:67], v[68:71], v[32:47]
	v_mfma_f32_32x32x16_bf16 v[0:15], v[64:67], v[72:75], v[0:15]
	ds_read_b128 v[64:67], v77 offset:16384
	v_add_u32_e32 v72, s6, v76
	ds_read_b128 v[68:71], v72
	ds_read_b128 v[72:75], v72 offset:4096
	s_mov_b64 s[6:7], 0
	s_waitcnt lgkmcnt(0)
	v_mfma_f32_32x32x16_bf16 v[48:63], v[64:67], v[68:71], v[48:63]
	v_mfma_f32_32x32x16_bf16 v[16:31], v[64:67], v[72:75], v[16:31]
	ds_read_b128 v[64:67], v77 offset:20480
	s_waitcnt vmcnt(0) lgkmcnt(0)
	s_barrier
	s_waitcnt lgkmcnt(0)
	v_mfma_f32_32x32x16_bf16 v[32:47], v[64:67], v[68:71], v[32:47]
	v_mfma_f32_32x32x16_bf16 v[0:15], v[64:67], v[72:75], v[0:15]

; DEV int stage_next(int s) { return (s == 2 * GS_STAGE) ? 0 : s + GS_STAGE; }
; template <int WAIT0>
; DEV void gk_main(f32x16 (&acc)[2][2], const GTile& t, int s0) {
;     ...
;   vm_wait_bar<WAIT0>();
;   int stc = s0, std_ = stage_next(stage_next(s0));
; #pragma nounroll
;   for (int kt = 0; kt < nk - 2; ++kt) {
;     GK_DMA(std_, kt + 2);
;     GK_COMPUTE(stc);
;     vm_wait_bar<6>();
;     stc = stage_next(stc); std_ = stage_next(std_);
;   }
.LBB0_79:
	s_add_i32 s21, s19, s20
	v_lshl_add_u64 v[84:85], v[64:65], 0, s[6:7]
	s_mov_b32 m0, s21
	v_lshl_add_u64 v[86:87], v[66:67], 0, s[6:7]
	global_load_lds_dwordx4 v[84:85], off
	s_add_i32 m0, s21, 0x2000
	v_lshl_add_u64 v[88:89], v[68:69], 0, s[6:7]
	global_load_lds_dwordx4 v[86:87], off
	s_add_i32 m0, s21, 0x4000
	v_lshl_add_u64 v[90:91], v[70:71], 0, s[6:7]
	global_load_lds_dwordx4 v[88:89], off
	s_add_i32 m0, s21, 0x6000
	v_lshl_add_u64 v[92:93], v[72:73], 0, s[6:7]
	global_load_lds_dwordx4 v[90:91], off
	s_add_i32 m0, s21, 0x8000
	v_lshl_add_u64 v[94:95], v[74:75], 0, s[6:7]
	global_load_lds_dwordx4 v[92:93], off
	s_add_i32 m0, s21, 0xa000
	s_add_i32 s27, s18, 0
	global_load_lds_dwordx4 v[94:95], off
	v_add_u32_e32 v100, s27, v82
	v_add_u32_e32 v101, s27, v83
	ds_read_b128 v[84:87], v101 offset:16384
	ds_read_b128 v[88:91], v100
	ds_read_b128 v[92:95], v100 offset:4096
	s_waitcnt lgkmcnt(0)
	v_add_u32_e32 v100, s27, v80
	s_add_i32 s21, s18, 0xc000
	s_cmp_lg_u32 s18, 0x18000
	s_cselect_b32 s18, s21, 0
	s_add_i32 s21, s20, 0xc000
	s_cmp_lg_u32 s20, 0x18000
	s_cselect_b32 s20, s21, 0
	ds_read_b128 v[236:239], v101 offset:20480
	v_mfma_f32_32x32x16_bf16 v[48:63], v[84:87], v[88:91], v[48:63]
	v_mfma_f32_32x32x16_bf16 v[16:31], v[84:87], v[92:95], v[16:31]
	v_add_u32_e32 v101, s27, v81
	s_add_u32 s6, s6, 0x80
	s_addc_u32 s7, s7, 0
	s_cmpk_lg_i32 s6, 0x700
	s_waitcnt lgkmcnt(0)
	ds_read_b128 v[84:87], v101 offset:16384
	ds_read_b128 v[240:243], v100
	ds_read_b128 v[244:247], v100 offset:4096
	v_mfma_f32_32x32x16_bf16 v[32:47], v[236:239], v[88:91], v[32:47]
	v_mfma_f32_32x32x16_bf16 v[0:15], v[236:239], v[92:95], v[0:15]
	v_add_u32_e32 v100, s27, v78
	s_waitcnt lgkmcnt(0)
	ds_read_b128 v[236:239], v101 offset:20480
	v_mfma_f32_32x32x16_bf16 v[48:63], v[84:87], v[240:243], v[48:63]
	v_mfma_f32_32x32x16_bf16 v[16:31], v[84:87], v[244:247], v[16:31]
	v_add_u32_e32 v101, s27, v79
	s_waitcnt lgkmcnt(0)
	ds_read_b128 v[84:87], v101 offset:16384
	ds_read_b128 v[88:91], v100
	ds_read_b128 v[92:95], v100 offset:4096
	v_mfma_f32_32x32x16_bf16 v[32:47], v[236:239], v[240:243], v[32:47]
	v_mfma_f32_32x32x16_bf16 v[0:15], v[236:239], v[244:247], v[0:15]
	v_add_u32_e32 v100, s27, v76
	s_waitcnt lgkmcnt(0)
	ds_read_b128 v[236:239], v101 offset:20480
	v_mfma_f32_32x32x16_bf16 v[48:63], v[84:87], v[88:91], v[48:63]
	v_mfma_f32_32x32x16_bf16 v[16:31], v[84:87], v[92:95], v[16:31]
	v_add_u32_e32 v101, s27, v77
	s_waitcnt lgkmcnt(0)
	ds_read_b128 v[84:87], v101 offset:16384
	ds_read_b128 v[240:243], v100
	ds_read_b128 v[244:247], v100 offset:4096
	v_mfma_f32_32x32x16_bf16 v[32:47], v[236:239], v[88:91], v[32:47]
	v_mfma_f32_32x32x16_bf16 v[0:15], v[236:239], v[92:95], v[0:15]
	s_waitcnt lgkmcnt(0)
	ds_read_b128 v[236:239], v101 offset:20480
	v_mfma_f32_32x32x16_bf16 v[48:63], v[84:87], v[240:243], v[48:63]
	v_mfma_f32_32x32x16_bf16 v[16:31], v[84:87], v[244:247], v[16:31]
	s_waitcnt vmcnt(6) lgkmcnt(0)
	s_barrier
	s_waitcnt lgkmcnt(0)
	v_mfma_f32_32x32x16_bf16 v[32:47], v[236:239], v[240:243], v[32:47]
	v_mfma_f32_32x32x16_bf16 v[0:15], v[236:239], v[244:247], v[0:15]
	s_cbranch_scc1 .LBB0_79
; DEV int stage_next(int s) { return (s == 2 * GS_STAGE) ? 0 : s + GS_STAGE; }
; template <int WAIT0>
; DEV void gk_main(f32x16 (&acc)[2][2], const GTile& t, int s0) {
;     ...
;   GK_COMPUTE(stc);
;   vm_wait_bar<0>();
;   stc = stage_next(stc);
;   GK_COMPUTE(stc);
;   vm_wait_bar<0>();
	s_add_i32 s6, s18, 0
	v_add_u32_e32 v84, s6, v83
	ds_read_b128 v[64:67], v84 offset:16384
	v_add_u32_e32 v72, s6, v82
	ds_read_b128 v[68:71], v72
	ds_read_b128 v[72:75], v72 offset:4096
	s_waitcnt lgkmcnt(0)
	v_mfma_f32_32x32x16_bf16 v[48:63], v[64:67], v[68:71], v[48:63]
	v_mfma_f32_32x32x16_bf16 v[16:31], v[64:67], v[72:75], v[16:31]
	ds_read_b128 v[64:67], v84 offset:20480
	v_add_u32_e32 v84, s6, v81
	s_waitcnt lgkmcnt(0)
	v_mfma_f32_32x32x16_bf16 v[32:47], v[64:67], v[68:71], v[32:47]
	v_mfma_f32_32x32x16_bf16 v[0:15], v[64:67], v[72:75], v[0:15]
	ds_read_b128 v[64:67], v84 offset:16384
	v_add_u32_e32 v72, s6, v80
	ds_read_b128 v[68:71], v72
	ds_read_b128 v[72:75], v72 offset:4096
	s_waitcnt lgkmcnt(0)
	v_mfma_f32_32x32x16_bf16 v[48:63], v[64:67], v[68:71], v[48:63]
	v_mfma_f32_32x32x16_bf16 v[16:31], v[64:67], v[72:75], v[16:31]
	ds_read_b128 v[64:67], v84 offset:20480
	v_add_u32_e32 v84, s6, v79
	s_waitcnt lgkmcnt(0)
	v_mfma_f32_32x32x16_bf16 v[32:47], v[64:67], v[68:71], v[32:47]
	v_mfma_f32_32x32x16_bf16 v[0:15], v[64:67], v[72:75], v[0:15]
	ds_read_b128 v[64:67], v84 offset:16384
	v_add_u32_e32 v72, s6, v78
	ds_read_b128 v[68:71], v72
	ds_read_b128 v[72:75], v72 offset:4096
	s_waitcnt lgkmcnt(0)
	v_mfma_f32_32x32x16_bf16 v[48:63], v[64:67], v[68:71], v[48:63]
	v_mfma_f32_32x32x16_bf16 v[16:31], v[64:67], v[72:75], v[16:31]
	ds_read_b128 v[64:67], v84 offset:20480
	v_add_u32_e32 v84, s6, v77
	s_waitcnt lgkmcnt(0)
	v_mfma_f32_32x32x16_bf16 v[32:47], v[64:67], v[68:71], v[32:47]
	v_mfma_f32_32x32x16_bf16 v[0:15], v[64:67], v[72:75], v[0:15]
	ds_read_b128 v[64:67], v84 offset:16384
	v_add_u32_e32 v72, s6, v76
	ds_read_b128 v[68:71], v72
	ds_read_b128 v[72:75], v72 offset:4096
	s_add_i32 s6, s18, 0xc000
	s_cmp_lg_u32 s18, 0x18000
	s_cselect_b32 s6, s6, 0
	s_waitcnt lgkmcnt(0)
	v_mfma_f32_32x32x16_bf16 v[48:63], v[64:67], v[68:71], v[48:63]
	s_add_i32 s6, s6, 0
	v_add_u32_e32 v83, s6, v83
	v_add_u32_e32 v81, s6, v81
	v_add_u32_e32 v79, s6, v79
	v_add_u32_e32 v77, s6, v77
	v_mfma_f32_32x32x16_bf16 v[16:31], v[64:67], v[72:75], v[16:31]
	ds_read_b128 v[64:67], v84 offset:20480
	s_waitcnt vmcnt(0) lgkmcnt(0)
	s_barrier
	s_waitcnt lgkmcnt(0)
	v_mfma_f32_32x32x16_bf16 v[32:47], v[64:67], v[68:71], v[32:47]
	v_mfma_f32_32x32x16_bf16 v[0:15], v[64:67], v[72:75], v[0:15]
	ds_read_b128 v[64:67], v83 offset:16384
	v_add_u32_e32 v72, s6, v82
	ds_read_b128 v[68:71], v72
	ds_read_b128 v[72:75], v72 offset:4096
	s_waitcnt lgkmcnt(0)
	v_mfma_f32_32x32x16_bf16 v[48:63], v[64:67], v[68:71], v[48:63]
	v_mfma_f32_32x32x16_bf16 v[16:31], v[64:67], v[72:75], v[16:31]
	ds_read_b128 v[64:67], v83 offset:20480
	s_waitcnt lgkmcnt(0)
	v_mfma_f32_32x32x16_bf16 v[32:47], v[64:67], v[68:71], v[32:47]
	v_mfma_f32_32x32x16_bf16 v[0:15], v[64:67], v[72:75], v[0:15]
	ds_read_b128 v[64:67], v81 offset:16384
	v_add_u32_e32 v72, s6, v80
	ds_read_b128 v[68:71], v72
	ds_read_b128 v[72:75], v72 offset:4096
	s_waitcnt lgkmcnt(0)
	v_mfma_f32_32x32x16_bf16 v[48:63], v[64:67], v[68:71], v[48:63]
	v_mfma_f32_32x32x16_bf16 v[16:31], v[64:67], v[72:75], v[16:31]
	ds_read_b128 v[64:67], v81 offset:20480
	s_waitcnt lgkmcnt(0)
	v_mfma_f32_32x32x16_bf16 v[32:47], v[64:67], v[68:71], v[32:47]
	v_mfma_f32_32x32x16_bf16 v[0:15], v[64:67], v[72:75], v[0:15]
	ds_read_b128 v[64:67], v79 offset:16384
	v_add_u32_e32 v72, s6, v78
	ds_read_b128 v[68:71], v72
	ds_read_b128 v[72:75], v72 offset:4096
	s_waitcnt lgkmcnt(0)
	v_mfma_f32_32x32x16_bf16 v[48:63], v[64:67], v[68:71], v[48:63]
	v_mfma_f32_32x32x16_bf16 v[16:31], v[64:67], v[72:75], v[16:31]
	ds_read_b128 v[64:67], v79 offset:20480
	s_waitcnt lgkmcnt(0)
	v_mfma_f32_32x32x16_bf16 v[32:47], v[64:67], v[68:71], v[32:47]
	v_mfma_f32_32x32x16_bf16 v[0:15], v[64:67], v[72:75], v[0:15]
	ds_read_b128 v[64:67], v77 offset:16384
	v_add_u32_e32 v72, s6, v76
	ds_read_b128 v[68:71], v72
	ds_read_b128 v[72:75], v72 offset:4096
	s_waitcnt lgkmcnt(0)
	v_mfma_f32_32x32x16_bf16 v[48:63], v[64:67], v[68:71], v[48:63]
	v_mfma_f32_32x32x16_bf16 v[16:31], v[64:67], v[72:75], v[16:31]
	ds_read_b128 v[64:67], v77 offset:20480
	s_waitcnt vmcnt(0) lgkmcnt(0)
	s_barrier
	s_waitcnt lgkmcnt(0)
	v_mfma_f32_32x32x16_bf16 v[32:47], v[64:67], v[68:71], v[32:47]
	v_mfma_f32_32x32x16_bf16 v[0:15], v[64:67], v[72:75], v[0:15]

; DEV int stage_next(int s) { return (s == 2 * GS_STAGE) ? 0 : s + GS_STAGE; }
; template <int WAIT0>
; DEV void gk_main(f32x16 (&acc)[2][2], const GTile& t, int s0) {
;     ...
;   vm_wait_bar<WAIT0>();
;   int stc = s0, std_ = stage_next(stage_next(s0));
; #pragma nounroll
;   for (int kt = 0; kt < nk - 2; ++kt) {
;     GK_DMA(std_, kt + 2);
;     GK_COMPUTE(stc);
;     vm_wait_bar<6>();
;     stc = stage_next(stc); std_ = stage_next(std_);
;   }
.LBB0_87:
	s_add_i32 s21, s19, s20
	v_lshl_add_u64 v[84:85], v[64:65], 0, s[6:7]
	s_mov_b32 m0, s21
	v_lshl_add_u64 v[86:87], v[66:67], 0, s[6:7]
	global_load_lds_dwordx4 v[84:85], off
	s_add_i32 m0, s21, 0x2000
	v_lshl_add_u64 v[88:89], v[68:69], 0, s[6:7]
	global_load_lds_dwordx4 v[86:87], off
	s_add_i32 m0, s21, 0x4000
	v_lshl_add_u64 v[90:91], v[70:71], 0, s[6:7]
	global_load_lds_dwordx4 v[88:89], off
	s_add_i32 m0, s21, 0x6000
	v_lshl_add_u64 v[92:93], v[72:73], 0, s[6:7]
	global_load_lds_dwordx4 v[90:91], off
	s_add_i32 m0, s21, 0x8000
	v_lshl_add_u64 v[94:95], v[74:75], 0, s[6:7]
	global_load_lds_dwordx4 v[92:93], off
	s_add_i32 m0, s21, 0xa000
	s_add_i32 s27, s18, 0
	global_load_lds_dwordx4 v[94:95], off
	v_add_u32_e32 v100, s27, v82
	v_add_u32_e32 v101, s27, v83
	ds_read_b128 v[84:87], v101 offset:16384
	ds_read_b128 v[88:91], v100
	ds_read_b128 v[92:95], v100 offset:4096
	s_waitcnt lgkmcnt(0)
	v_add_u32_e32 v100, s27, v80
	s_add_i32 s21, s18, 0xc000
	s_cmp_lg_u32 s18, 0x18000
	s_cselect_b32 s18, s21, 0
	s_add_i32 s21, s20, 0xc000
	s_cmp_lg_u32 s20, 0x18000
	s_cselect_b32 s20, s21, 0
	ds_read_b128 v[236:239], v101 offset:20480
	v_mfma_f32_32x32x16_bf16 v[48:63], v[84:87], v[88:91], v[48:63]
	v_mfma_f32_32x32x16_bf16 v[16:31], v[84:87], v[92:95], v[16:31]
	v_add_u32_e32 v101, s27, v81
	s_add_u32 s6, s6, 0x80
	s_addc_u32 s7, s7, 0
	s_cmpk_lg_i32 s6, 0x700
	s_waitcnt lgkmcnt(0)
	ds_read_b128 v[84:87], v101 offset:16384
	ds_read_b128 v[240:243], v100
	ds_read_b128 v[244:247], v100 offset:4096
	v_mfma_f32_32x32x16_bf16 v[32:47], v[236:239], v[88:91], v[32:47]
	v_mfma_f32_32x32x16_bf16 v[0:15], v[236:239], v[92:95], v[0:15]
	v_add_u32_e32 v100, s27, v78
	s_waitcnt lgkmcnt(0)
	ds_read_b128 v[236:239], v101 offset:20480
	v_mfma_f32_32x32x16_bf16 v[48:63], v[84:87], v[240:243], v[48:63]
	v_mfma_f32_32x32x16_bf16 v[16:31], v[84:87], v[244:247], v[16:31]
	v_add_u32_e32 v101, s27, v79
	s_waitcnt lgkmcnt(0)
	ds_read_b128 v[84:87], v101 offset:16384
	ds_read_b128 v[88:91], v100
	ds_read_b128 v[92:95], v100 offset:4096
	v_mfma_f32_32x32x16_bf16 v[32:47], v[236:239], v[240:243], v[32:47]
	v_mfma_f32_32x32x16_bf16 v[0:15], v[236:239], v[244:247], v[0:15]
	v_add_u32_e32 v100, s27, v76
	s_waitcnt lgkmcnt(0)
	ds_read_b128 v[236:239], v101 offset:20480
	v_mfma_f32_32x32x16_bf16 v[48:63], v[84:87], v[88:91], v[48:63]
	v_mfma_f32_32x32x16_bf16 v[16:31], v[84:87], v[92:95], v[16:31]
	v_add_u32_e32 v101, s27, v77
	s_waitcnt lgkmcnt(0)
	ds_read_b128 v[84:87], v101 offset:16384
	ds_read_b128 v[240:243], v100
	ds_read_b128 v[244:247], v100 offset:4096
	v_mfma_f32_32x32x16_bf16 v[32:47], v[236:239], v[88:91], v[32:47]
	v_mfma_f32_32x32x16_bf16 v[0:15], v[236:239], v[92:95], v[0:15]
	s_waitcnt lgkmcnt(0)
	ds_read_b128 v[236:239], v101 offset:20480
	v_mfma_f32_32x32x16_bf16 v[48:63], v[84:87], v[240:243], v[48:63]
	v_mfma_f32_32x32x16_bf16 v[16:31], v[84:87], v[244:247], v[16:31]
	s_waitcnt vmcnt(6) lgkmcnt(0)
	s_barrier
	s_waitcnt lgkmcnt(0)
	v_mfma_f32_32x32x16_bf16 v[32:47], v[236:239], v[240:243], v[32:47]
	v_mfma_f32_32x32x16_bf16 v[0:15], v[236:239], v[244:247], v[0:15]
	s_cbranch_scc1 .LBB0_87
; DEV int stage_next(int s) { return (s == 2 * GS_STAGE) ? 0 : s + GS_STAGE; }
; template <int WAIT0>
; DEV void gk_main(f32x16 (&acc)[2][2], const GTile& t, int s0) {
;     ...
;   GK_COMPUTE(stc);
;   vm_wait_bar<0>();
;   stc = stage_next(stc);
;   GK_COMPUTE(stc);
;   vm_wait_bar<0>();
; template <int WAIT_E, int WAIT_O, class TileFn, class EpiFn>
; DEV void gemm_seq(int ntiles, TileFn tf, EpiFn epi) {
;     ...
;   for (int i = 0; i < ntiles; ++i) {
;     f32x16 acc[2][2]; acc_zero(acc);
;     if (i == 0) gk_main<6>(acc, cur, s0);
;     else if (i & 1) gk_main<WAIT_O>(acc, cur, s0);
;     else gk_main<WAIT_E>(acc, cur, s0);
;     const int sn = stage_next(s0);
;     if (i + 1 < ntiles) { cur = tf(i + 1); gk_issue2(cur, sn); }
;     epi(i, acc, s0);
;     s0 = sn;
;   }
	s_add_i32 s6, s18, 0
	v_add_u32_e32 v84, s6, v83
	ds_read_b128 v[64:67], v84 offset:16384
	v_add_u32_e32 v72, s6, v82
	ds_read_b128 v[68:71], v72
	ds_read_b128 v[72:75], v72 offset:4096
	s_waitcnt lgkmcnt(0)
	v_mfma_f32_32x32x16_bf16 v[48:63], v[64:67], v[68:71], v[48:63]
	v_mfma_f32_32x32x16_bf16 v[16:31], v[64:67], v[72:75], v[16:31]
	ds_read_b128 v[64:67], v84 offset:20480
	v_add_u32_e32 v84, s6, v81
	s_waitcnt lgkmcnt(0)
	v_mfma_f32_32x32x16_bf16 v[32:47], v[64:67], v[68:71], v[32:47]
	v_mfma_f32_32x32x16_bf16 v[0:15], v[64:67], v[72:75], v[0:15]
	ds_read_b128 v[64:67], v84 offset:16384
	v_add_u32_e32 v72, s6, v80
	ds_read_b128 v[68:71], v72
	ds_read_b128 v[72:75], v72 offset:4096
	s_waitcnt lgkmcnt(0)
	v_mfma_f32_32x32x16_bf16 v[48:63], v[64:67], v[68:71], v[48:63]
	v_mfma_f32_32x32x16_bf16 v[16:31], v[64:67], v[72:75], v[16:31]
	ds_read_b128 v[64:67], v84 offset:20480
	v_add_u32_e32 v84, s6, v79
	s_waitcnt lgkmcnt(0)
	v_mfma_f32_32x32x16_bf16 v[32:47], v[64:67], v[68:71], v[32:47]
	v_mfma_f32_32x32x16_bf16 v[0:15], v[64:67], v[72:75], v[0:15]
	ds_read_b128 v[64:67], v84 offset:16384
	v_add_u32_e32 v72, s6, v78
	ds_read_b128 v[68:71], v72
	ds_read_b128 v[72:75], v72 offset:4096
	s_waitcnt lgkmcnt(0)
	v_mfma_f32_32x32x16_bf16 v[48:63], v[64:67], v[68:71], v[48:63]
	v_mfma_f32_32x32x16_bf16 v[16:31], v[64:67], v[72:75], v[16:31]
	ds_read_b128 v[64:67], v84 offset:20480
	v_add_u32_e32 v84, s6, v77
	s_waitcnt lgkmcnt(0)
	v_mfma_f32_32x32x16_bf16 v[32:47], v[64:67], v[68:71], v[32:47]
	v_mfma_f32_32x32x16_bf16 v[0:15], v[64:67], v[72:75], v[0:15]
	ds_read_b128 v[64:67], v84 offset:16384
	v_add_u32_e32 v72, s6, v76
	ds_read_b128 v[68:71], v72
	ds_read_b128 v[72:75], v72 offset:4096
	s_add_i32 s6, s18, 0xc000
	s_cmp_lg_u32 s18, 0x18000
	s_cselect_b32 s6, s6, 0
	s_waitcnt lgkmcnt(0)
	v_mfma_f32_32x32x16_bf16 v[48:63], v[64:67], v[68:71], v[48:63]
	s_add_i32 s6, s6, 0
	v_add_u32_e32 v83, s6, v83
	v_add_u32_e32 v81, s6, v81
	v_add_u32_e32 v79, s6, v79
	v_add_u32_e32 v77, s6, v77
	v_mfma_f32_32x32x16_bf16 v[16:31], v[64:67], v[72:75], v[16:31]
	ds_read_b128 v[64:67], v84 offset:20480
	s_waitcnt vmcnt(0) lgkmcnt(0)
	s_barrier
	s_waitcnt lgkmcnt(0)
	v_mfma_f32_32x32x16_bf16 v[32:47], v[64:67], v[68:71], v[32:47]
	v_mfma_f32_32x32x16_bf16 v[0:15], v[64:67], v[72:75], v[0:15]
	ds_read_b128 v[64:67], v83 offset:16384
	v_add_u32_e32 v72, s6, v82
	ds_read_b128 v[68:71], v72
	ds_read_b128 v[72:75], v72 offset:4096
	s_waitcnt lgkmcnt(0)
	v_mfma_f32_32x32x16_bf16 v[48:63], v[64:67], v[68:71], v[48:63]
	v_mfma_f32_32x32x16_bf16 v[16:31], v[64:67], v[72:75], v[16:31]
	ds_read_b128 v[64:67], v83 offset:20480
	s_waitcnt lgkmcnt(0)
	v_mfma_f32_32x32x16_bf16 v[32:47], v[64:67], v[68:71], v[32:47]
	v_mfma_f32_32x32x16_bf16 v[0:15], v[64:67], v[72:75], v[0:15]
	ds_read_b128 v[64:67], v81 offset:16384
	v_add_u32_e32 v72, s6, v80
	ds_read_b128 v[68:71], v72
	ds_read_b128 v[72:75], v72 offset:4096
	s_waitcnt lgkmcnt(0)
	v_mfma_f32_32x32x16_bf16 v[48:63], v[64:67], v[68:71], v[48:63]
	v_mfma_f32_32x32x16_bf16 v[16:31], v[64:67], v[72:75], v[16:31]
	ds_read_b128 v[64:67], v81 offset:20480
	s_waitcnt lgkmcnt(0)
	v_mfma_f32_32x32x16_bf16 v[32:47], v[64:67], v[68:71], v[32:47]
	v_mfma_f32_32x32x16_bf16 v[0:15], v[64:67], v[72:75], v[0:15]
	ds_read_b128 v[64:67], v79 offset:16384
	v_add_u32_e32 v72, s6, v78
	ds_read_b128 v[68:71], v72
	ds_read_b128 v[72:75], v72 offset:4096
	s_waitcnt lgkmcnt(0)
	v_mfma_f32_32x32x16_bf16 v[48:63], v[64:67], v[68:71], v[48:63]
	v_mfma_f32_32x32x16_bf16 v[16:31], v[64:67], v[72:75], v[16:31]
	ds_read_b128 v[64:67], v79 offset:20480
	s_waitcnt lgkmcnt(0)
	v_mfma_f32_32x32x16_bf16 v[32:47], v[64:67], v[68:71], v[32:47]
	v_mfma_f32_32x32x16_bf16 v[0:15], v[64:67], v[72:75], v[0:15]
	ds_read_b128 v[64:67], v77 offset:16384
	v_add_u32_e32 v72, s6, v76
	ds_read_b128 v[68:71], v72
	ds_read_b128 v[72:75], v72 offset:4096
	s_waitcnt lgkmcnt(0)
	v_mfma_f32_32x32x16_bf16 v[48:63], v[64:67], v[68:71], v[48:63]
	v_mfma_f32_32x32x16_bf16 v[16:31], v[64:67], v[72:75], v[16:31]
	ds_read_b128 v[64:67], v77 offset:20480
	s_waitcnt vmcnt(0) lgkmcnt(0)
	s_barrier
	s_waitcnt lgkmcnt(0)
	v_mfma_f32_32x32x16_bf16 v[32:47], v[64:67], v[68:71], v[32:47]
	v_mfma_f32_32x32x16_bf16 v[0:15], v[64:67], v[72:75], v[0:15]
	s_add_i32 s18, s17, 1
	s_cmp_eq_u32 s17, 11
	s_cbranch_scc1 .LBB0_83

; DEV bf16_t f2bf(float f) { return (bf16_t)(pk2(f, 0.f) & 0xffffu); }
; DEV int stage_next(int s) { return (s == 2 * GS_STAGE) ? 0 : s + GS_STAGE; }
; #define FOR_ACC _Pragma("unroll") for (int nb = 0; nb < 2; ++nb) _Pragma("unroll") for (int mb = 0; mb < 2; ++mb) _Pragma("unroll") for (int rq = 0; rq < 4; ++rq)
; template <int WAIT0>
; DEV void gk_main(f32x16 (&acc)[2][2], const GTile& t, int s0) {
;     ...
;   vm_wait_bar<WAIT0>();
;   int stc = s0, std_ = stage_next(stage_next(s0));
; #pragma nounroll
;   for (int kt = 0; kt < nk - 2; ++kt) {
;     GK_DMA(std_, kt + 2);
;     GK_COMPUTE(stc);
;     vm_wait_bar<6>();
;     stc = stage_next(stc); std_ = stage_next(std_);
;   }
;   GK_COMPUTE(stc);
;   vm_wait_bar<0>();
;   stc = stage_next(stc);
;   GK_COMPUTE(stc);
;   vm_wait_bar<0>();
; DEV void fold_unit(const Params& P, int u) {
;     ...
;   gemm_seq<6, 6>(1, [&](int) { return GTile{A, 2048, Bt, 256, 256}; }, [&](int, f32x16 (&acc)[2][2], int) {
;     FOR_ACC {
;       const int j = jt * 128 + 64 * wm + 32 * mb + l32, n = 64 * wn + 32 * nb + 8 * rq + 4 * hi;
; #pragma unroll
;       for (int e = 0; e < 4; ++e) wpt[((size_t)l * 2048 + hh * 256 + n + e) * 1024 + j] = f2bf(acc[nb][mb][4 * rq + e]);
;     }
.LBB0_96:
	s_add_i32 s39, s38, s24
	v_lshl_add_u64 v[92:93], v[64:65], 0, s[22:23]
	s_mov_b32 m0, s39
	v_lshl_add_u64 v[94:95], v[66:67], 0, s[22:23]
	global_load_lds_dwordx4 v[92:93], off
	s_add_i32 m0, s39, 0x2000
	v_lshl_add_u64 v[96:97], v[68:69], 0, s[22:23]
	global_load_lds_dwordx4 v[94:95], off
	s_add_i32 m0, s39, 0x4000
	v_lshl_add_u64 v[98:99], v[70:71], 0, s[22:23]
	global_load_lds_dwordx4 v[96:97], off
	s_add_i32 m0, s39, 0x6000
	v_lshl_add_u64 v[100:101], v[72:73], 0, s[22:23]
	global_load_lds_dwordx4 v[98:99], off
	s_add_i32 m0, s39, 0x8000
	v_lshl_add_u64 v[102:103], v[74:75], 0, s[22:23]
	global_load_lds_dwordx4 v[100:101], off
	s_add_i32 m0, s39, 0xa000
	s_add_i32 s40, s25, 0
	global_load_lds_dwordx4 v[102:103], off
	v_add_u32_e32 v252, s40, v89
	v_add_u32_e32 v91, s40, v88
	ds_read_b128 v[92:95], v252 offset:16384
	ds_read_b128 v[96:99], v91
	ds_read_b128 v[100:103], v91 offset:4096
	ds_read_b128 v[104:107], v252 offset:20480
	s_waitcnt lgkmcnt(0)
	v_add_u32_e32 v108, s40, v87
	v_add_u32_e32 v91, s40, v86
	s_add_i32 s39, s25, 0xc000
	s_cmp_lg_u32 s25, 0x18000
	s_cselect_b32 s25, s39, 0
	s_add_i32 s39, s24, 0xc000
	s_cmp_lg_u32 s24, 0x18000
	s_cselect_b32 s24, s39, 0
	s_add_u32 s22, s22, 0x80
	s_addc_u32 s23, s23, 0
	s_cmpk_lg_i32 s22, 0x100
	ds_read_b128 v[236:239], v108 offset:16384
	ds_read_b128 v[240:243], v91
	ds_read_b128 v[244:247], v91 offset:4096
	ds_read_b128 v[248:251], v108 offset:20480
	v_mfma_f32_32x32x16_bf16 v[48:63], v[92:95], v[96:99], v[48:63]
	v_mfma_f32_32x32x16_bf16 v[32:47], v[92:95], v[100:103], v[32:47]
	v_mfma_f32_32x32x16_bf16 v[16:31], v[104:107], v[96:99], v[16:31]
	v_mfma_f32_32x32x16_bf16 v[0:15], v[104:107], v[100:103], v[0:15]
	v_add_u32_e32 v108, s40, v85
	v_add_u32_e32 v91, s40, v84
	s_waitcnt lgkmcnt(0)
	ds_read_b128 v[92:95], v108 offset:16384
	ds_read_b128 v[96:99], v91
	ds_read_b128 v[100:103], v91 offset:4096
	ds_read_b128 v[104:107], v108 offset:20480
	v_mfma_f32_32x32x16_bf16 v[48:63], v[236:239], v[240:243], v[48:63]
	v_mfma_f32_32x32x16_bf16 v[32:47], v[236:239], v[244:247], v[32:47]
	v_mfma_f32_32x32x16_bf16 v[16:31], v[248:251], v[240:243], v[16:31]
	v_mfma_f32_32x32x16_bf16 v[0:15], v[248:251], v[244:247], v[0:15]
	v_add_u32_e32 v108, s40, v83
	v_add_u32_e32 v91, s40, v80
	s_waitcnt lgkmcnt(0)
	ds_read_b128 v[236:239], v108 offset:16384
	ds_read_b128 v[240:243], v91
	ds_read_b128 v[244:247], v91 offset:4096
	ds_read_b128 v[248:251], v108 offset:20480
	v_mfma_f32_32x32x16_bf16 v[48:63], v[92:95], v[96:99], v[48:63]
	v_mfma_f32_32x32x16_bf16 v[32:47], v[92:95], v[100:103], v[32:47]
	v_mfma_f32_32x32x16_bf16 v[16:31], v[104:107], v[96:99], v[16:31]
	v_mfma_f32_32x32x16_bf16 v[0:15], v[104:107], v[100:103], v[0:15]
	s_waitcnt vmcnt(6) lgkmcnt(0)
	s_barrier
	s_waitcnt lgkmcnt(0)
	v_mfma_f32_32x32x16_bf16 v[48:63], v[236:239], v[240:243], v[48:63]
	v_mfma_f32_32x32x16_bf16 v[32:47], v[236:239], v[244:247], v[32:47]
	v_mfma_f32_32x32x16_bf16 v[16:31], v[248:251], v[240:243], v[16:31]
	v_mfma_f32_32x32x16_bf16 v[0:15], v[248:251], v[244:247], v[0:15]
	s_cbranch_scc1 .LBB0_96
	v_add_u32_e32 v72, 0x4000, v79
	v_or_b32_e32 v64, v72, v90
	v_add_u32_e32 v73, s35, v64
	ds_read_b128 v[64:67], v73
	v_add_u32_e32 v74, s35, v88
	ds_read_b128 v[68:71], v74
	ds_read_b128 v[90:93], v74 offset:4096
	ds_read_b128 v[94:97], v73 offset:4096
	v_or_b32_e32 v73, v72, v76
	v_or_b32_e32 v74, v72, v77
	s_waitcnt lgkmcnt(0)
	v_mfma_f32_32x32x16_bf16 v[16:31], v[94:97], v[68:71], v[16:31]
	v_or_b32_e32 v76, v72, v78
	v_add_u32_e32 v72, s35, v80
	v_add_u32_e32 v76, s35, v76
	v_add_u32_e32 v88, 0, v88
	v_add_u32_e32 v154, 0, v87
	v_add_u32_e32 v80, 0, v80
	s_lshl_b64 s[20:21], s[20:21], 11
	v_mfma_f32_32x32x16_bf16 v[48:63], v[64:67], v[68:71], v[48:63]
	v_add_u32_e32 v68, s35, v74
	s_or_b64 s[20:21], s[20:21], s[8:9]
	s_add_i32 s36, s36, s86
	s_add_i32 s30, s30, s31
	s_add_i32 s33, s33, s34
	s_cmpk_gt_i32 s36, 0x7f
	v_mfma_f32_32x32x16_bf16 v[32:47], v[64:67], v[90:93], v[32:47]
	v_add_u32_e32 v64, s35, v86
	ds_read_b128 v[98:101], v64
	ds_read_b128 v[102:105], v64 offset:4096
	v_add_u32_e32 v64, s35, v73
	ds_read_b128 v[106:109], v64
	ds_read_b128 v[110:113], v64 offset:4096
	v_add_u32_e32 v64, s35, v84
	ds_read_b128 v[114:117], v64
	ds_read_b128 v[64:67], v64 offset:4096
	ds_read_b128 v[118:121], v68
	ds_read_b128 v[68:71], v68 offset:4096
	s_waitcnt lgkmcnt(0)
	v_mfma_f32_32x32x16_bf16 v[48:63], v[106:109], v[98:101], v[48:63]
	ds_read_b128 v[122:125], v72
	ds_read_b128 v[72:75], v72 offset:4096
	ds_read_b128 v[126:129], v76
	ds_read_b128 v[76:79], v76 offset:4096
	s_waitcnt vmcnt(0) lgkmcnt(0)
	s_barrier
	ds_read_b128 v[130:133], v88
	ds_read_b128 v[134:137], v88 offset:4096
	v_add_u32_e32 v88, 0, v89
	v_mfma_f32_32x32x16_bf16 v[48:63], v[118:121], v[114:117], v[48:63]
	ds_read_b128 v[138:141], v88 offset:16384
	ds_read_b128 v[142:145], v88 offset:20480
	v_add_u32_e32 v86, 0, v86
	ds_read_b128 v[146:149], v86
	ds_read_b128 v[150:153], v86 offset:4096
	ds_read_b128 v[86:89], v154 offset:16384
	ds_read_b128 v[154:157], v154 offset:20480
	v_add_u32_e32 v84, 0, v84
	ds_read_b128 v[158:161], v84
	ds_read_b128 v[162:165], v84 offset:4096
	v_add_u32_e32 v84, 0, v85
	s_waitcnt lgkmcnt(0)
	v_mfma_f32_32x32x16_bf16 v[48:63], v[126:129], v[122:125], v[48:63]
	ds_read_b128 v[166:169], v84 offset:16384
	ds_read_b128 v[170:173], v84 offset:20480
	ds_read_b128 v[182:185], v80
	ds_read_b128 v[186:189], v80 offset:4096
	v_add_u32_e32 v80, 0, v83
	ds_read_b128 v[190:193], v80 offset:16384
	ds_read_b128 v[194:197], v80 offset:20480
	v_ashrrev_i32_e32 v83, 1, v82
	v_and_b32_e32 v80, 0x5f, v82
	v_and_b32_e32 v83, 0xffffffc0, v83
	v_mfma_f32_32x32x16_bf16 v[48:63], v[138:141], v[130:133], v[48:63]
	v_lshrrev_b32_e32 v82, 3, v82
	v_and_or_b32 v84, v82, 4, v83
	v_or_b32_e32 v80, s37, v80
	v_ashrrev_i32_e32 v85, 31, v84
	v_lshlrev_b32_e32 v80, 1, v80
	v_lshl_add_u64 v[174:175], s[20:21], 0, v[84:85]
	v_lshl_add_u64 v[82:83], s[2:3], 0, v[80:81]
	v_mfma_f32_32x32x16_bf16 v[32:47], v[106:109], v[102:105], v[32:47]
	v_lshlrev_b64 v[174:175], 11, v[174:175]
	v_lshl_add_u64 v[198:199], v[82:83], 0, v[174:175]
	s_waitcnt vmcnt(0) lgkmcnt(0)
	s_barrier
; DEV bf16_t f2bf(float f) { return (bf16_t)(pk2(f, 0.f) & 0xffffu); }
; #define FOR_ACC _Pragma("unroll") for (int nb = 0; nb < 2; ++nb) _Pragma("unroll") for (int mb = 0; mb < 2; ++mb) _Pragma("unroll") for (int rq = 0; rq < 4; ++rq)
; DEV void fold_unit(const Params& P, int u) {
;     ...
;     FOR_ACC {
;       const int j = jt * 128 + 64 * wm + 32 * mb + l32, n = 64 * wn + 32 * nb + 8 * rq + 4 * hi;
; #pragma unroll
;       for (int e = 0; e < 4; ++e) wpt[((size_t)l * 2048 + hh * 256 + n + e) * 1024 + j] = f2bf(acc[nb][mb][4 * rq + e]);
;     }
	v_mfma_f32_32x32x16_bf16 v[48:63], v[86:89], v[146:149], v[48:63]
	v_mfma_f32_32x32x16_bf16 v[32:47], v[118:121], v[64:67], v[32:47]
	s_waitcnt lgkmcnt(0)
	v_mfma_f32_32x32x16_bf16 v[48:63], v[166:169], v[158:161], v[48:63]
	v_mfma_f32_32x32x16_bf16 v[32:47], v[126:129], v[72:75], v[32:47]
	v_mfma_f32_32x32x16_bf16 v[48:63], v[190:193], v[182:185], v[48:63]
	v_mfma_f32_32x32x16_bf16 v[16:31], v[110:113], v[98:101], v[16:31]
	s_nop 10
	v_cvt_pk_bf16_f32 v48, v48, s0
	global_store_short v[198:199], v48, off
	v_cvt_pk_bf16_f32 v48, v49, s0
	global_store_short v[198:199], v48, off offset:2048
	v_or_b32_e32 v48, 0x1000, v174
	v_mov_b32_e32 v49, v175
	v_cvt_pk_bf16_f32 v50, v50, s0
	v_mfma_f32_32x32x16_bf16 v[32:47], v[138:141], v[134:137], v[32:47]
	v_or_b32_e32 v174, 0x1800, v174
	v_cvt_pk_bf16_f32 v80, v51, s0
	v_cvt_pk_bf16_f32 v52, v52, s0
	v_cvt_pk_bf16_f32 v54, v54, s0
	v_cvt_pk_bf16_f32 v56, v56, s0
	v_cvt_pk_bf16_f32 v58, v58, s0
	v_cvt_pk_bf16_f32 v60, v60, s0
	v_mfma_f32_32x32x16_bf16 v[16:31], v[68:71], v[114:117], v[16:31]
	v_cvt_pk_bf16_f32 v62, v62, s0
	v_mfma_f32_32x32x16_bf16 v[0:15], v[94:97], v[90:93], v[0:15]
	v_lshl_add_u64 v[90:91], v[82:83], 0, v[48:49]
	global_store_short v[90:91], v50, off
	v_lshl_add_u64 v[50:51], v[82:83], 0, v[174:175]
	global_store_short v[50:51], v80, off
	v_or_b32_e32 v50, 8, v84
	v_ashrrev_i32_e32 v51, 31, v50
	v_lshl_add_u64 v[50:51], s[20:21], 0, v[50:51]
	v_mfma_f32_32x32x16_bf16 v[32:47], v[86:89], v[150:153], v[32:47]
	v_lshlrev_b64 v[50:51], 11, v[50:51]
	v_lshl_add_u64 v[90:91], v[82:83], 0, v[50:51]
	global_store_short v[90:91], v52, off
	v_cvt_pk_bf16_f32 v80, v53, s0
	v_or_b32_e32 v52, 0x800, v50
	v_mov_b32_e32 v53, v51
	v_or_b32_e32 v92, 0x1000, v50
	v_mfma_f32_32x32x16_bf16 v[16:31], v[76:79], v[122:125], v[16:31]
	v_mov_b32_e32 v93, v51
	v_lshl_add_u64 v[52:53], v[82:83], 0, v[52:53]
	v_lshl_add_u64 v[92:93], v[82:83], 0, v[92:93]
	v_or_b32_e32 v50, 0x1800, v50
	global_store_short v[52:53], v80, off
	global_store_short v[92:93], v54, off
	v_cvt_pk_bf16_f32 v54, v55, s0
	v_lshl_add_u64 v[50:51], v[82:83], 0, v[50:51]
	v_mfma_f32_32x32x16_bf16 v[32:47], v[166:169], v[162:165], v[32:47]
	global_store_short v[50:51], v54, off
	v_or_b32_e32 v54, 16, v84
	v_ashrrev_i32_e32 v55, 31, v54
	v_lshl_add_u64 v[54:55], s[20:21], 0, v[54:55]
	v_lshlrev_b64 v[54:55], 11, v[54:55]
	v_lshl_add_u64 v[94:95], v[82:83], 0, v[54:55]
	global_store_short v[94:95], v56, off
	v_mfma_f32_32x32x16_bf16 v[16:31], v[142:145], v[130:133], v[16:31]
	v_cvt_pk_bf16_f32 v80, v57, s0
	v_or_b32_e32 v56, 0x800, v54
	v_mov_b32_e32 v57, v55
	v_or_b32_e32 v96, 0x1000, v54
	v_mov_b32_e32 v97, v55
	v_lshl_add_u64 v[56:57], v[82:83], 0, v[56:57]
	v_lshl_add_u64 v[96:97], v[82:83], 0, v[96:97]
	v_or_b32_e32 v54, 0x1800, v54
	global_store_short v[56:57], v80, off
	global_store_short v[96:97], v58, off
	v_cvt_pk_bf16_f32 v58, v59, s0
	v_lshl_add_u64 v[54:55], v[82:83], 0, v[54:55]
	v_mfma_f32_32x32x16_bf16 v[32:47], v[190:193], v[186:189], v[32:47]
	global_store_short v[54:55], v58, off
	v_or_b32_e32 v58, 24, v84
	v_ashrrev_i32_e32 v59, 31, v58
	v_lshl_add_u64 v[58:59], s[20:21], 0, v[58:59]
	v_lshlrev_b64 v[58:59], 11, v[58:59]
	v_lshl_add_u64 v[86:87], v[82:83], 0, v[58:59]
	global_store_short v[86:87], v60, off
	v_mfma_f32_32x32x16_bf16 v[0:15], v[110:113], v[102:105], v[0:15]
	v_cvt_pk_bf16_f32 v80, v61, s0
	v_or_b32_e32 v60, 0x800, v58
	v_mov_b32_e32 v61, v59
	v_or_b32_e32 v88, 0x1000, v58
	v_mov_b32_e32 v89, v59
	v_lshl_add_u64 v[60:61], v[82:83], 0, v[60:61]
	v_lshl_add_u64 v[88:89], v[82:83], 0, v[88:89]
	v_mfma_f32_32x32x16_bf16 v[16:31], v[154:157], v[146:149], v[16:31]
	v_or_b32_e32 v58, 0x1800, v58
	global_store_short v[60:61], v80, off
	global_store_short v[88:89], v62, off
	v_cvt_pk_bf16_f32 v62, v63, s0
	v_lshl_add_u64 v[58:59], v[82:83], 0, v[58:59]
	v_cvt_pk_bf16_f32 v32, v32, s0
	global_store_short v[58:59], v62, off
	v_lshl_add_u64 v[62:63], v[82:83], 0, 64
	global_store_short v[198:199], v32, off offset:64
	v_cvt_pk_bf16_f32 v32, v33, s0
	global_store_short v[198:199], v32, off offset:2112
	v_cvt_pk_bf16_f32 v34, v34, s0
	v_lshl_add_u64 v[32:33], v[62:63], 0, v[48:49]
	global_store_short v[32:33], v34, off
	v_cvt_pk_bf16_f32 v34, v35, s0
	v_lshl_add_u64 v[32:33], v[62:63], 0, v[174:175]
	global_store_short v[32:33], v34, off
	v_cvt_pk_bf16_f32 v32, v36, s0
	v_mfma_f32_32x32x16_bf16 v[16:31], v[170:173], v[158:161], v[16:31]
	global_store_short v[90:91], v32, off offset:64
	v_cvt_pk_bf16_f32 v32, v37, s0
	global_store_short v[52:53], v32, off offset:64
	v_cvt_pk_bf16_f32 v32, v38, s0
	global_store_short v[92:93], v32, off offset:64
	v_cvt_pk_bf16_f32 v32, v39, s0
	global_store_short v[50:51], v32, off offset:64
	v_mfma_f32_32x32x16_bf16 v[0:15], v[68:71], v[64:67], v[0:15]
	v_cvt_pk_bf16_f32 v32, v40, s0
	global_store_short v[94:95], v32, off offset:64
	v_cvt_pk_bf16_f32 v32, v41, s0
	global_store_short v[56:57], v32, off offset:64
	v_cvt_pk_bf16_f32 v32, v42, s0
	global_store_short v[96:97], v32, off offset:64
	v_cvt_pk_bf16_f32 v32, v43, s0
	global_store_short v[54:55], v32, off offset:64
; DEV bf16_t f2bf(float f) { return (bf16_t)(pk2(f, 0.f) & 0xffffu); }
; #define FOR_ACC _Pragma("unroll") for (int nb = 0; nb < 2; ++nb) _Pragma("unroll") for (int mb = 0; mb < 2; ++mb) _Pragma("unroll") for (int rq = 0; rq < 4; ++rq)
; DEV void fold_unit(const Params& P, int u) {
;     ...
;     FOR_ACC {
;       const int j = jt * 128 + 64 * wm + 32 * mb + l32, n = 64 * wn + 32 * nb + 8 * rq + 4 * hi;
; #pragma unroll
;       for (int e = 0; e < 4; ++e) wpt[((size_t)l * 2048 + hh * 256 + n + e) * 1024 + j] = f2bf(acc[nb][mb][4 * rq + e]);
;     }
	v_cvt_pk_bf16_f32 v32, v44, s0
	v_mfma_f32_32x32x16_bf16 v[16:31], v[194:197], v[182:185], v[16:31]
	global_store_short v[86:87], v32, off offset:64
	v_cvt_pk_bf16_f32 v32, v45, s0
	global_store_short v[60:61], v32, off offset:64
	v_cvt_pk_bf16_f32 v32, v46, s0
	global_store_short v[88:89], v32, off offset:64
	v_cvt_pk_bf16_f32 v32, v47, s0
	global_store_short v[58:59], v32, off offset:64
	v_mfma_f32_32x32x16_bf16 v[0:15], v[76:79], v[72:75], v[0:15]
	v_or_b32_e32 v32, 32, v84
	v_ashrrev_i32_e32 v33, 31, v32
	v_lshl_add_u64 v[32:33], s[20:21], 0, v[32:33]
	v_lshlrev_b64 v[32:33], 11, v[32:33]
	v_cvt_pk_bf16_f32 v16, v16, s0
	v_lshl_add_u64 v[34:35], v[82:83], 0, v[32:33]
	global_store_short v[34:35], v16, off
	v_mfma_f32_32x32x16_bf16 v[0:15], v[142:145], v[134:137], v[0:15]
	v_cvt_pk_bf16_f32 v36, v17, s0
	v_or_b32_e32 v16, 0x800, v32
	v_mov_b32_e32 v17, v33
	v_lshl_add_u64 v[16:17], v[82:83], 0, v[16:17]
	global_store_short v[16:17], v36, off
	v_or_b32_e32 v36, 0x1000, v32
	v_mov_b32_e32 v37, v33
	v_cvt_pk_bf16_f32 v18, v18, s0
	v_lshl_add_u64 v[36:37], v[82:83], 0, v[36:37]
	v_or_b32_e32 v32, 0x1800, v32
	global_store_short v[36:37], v18, off
	v_cvt_pk_bf16_f32 v38, v19, s0
	v_lshl_add_u64 v[18:19], v[82:83], 0, v[32:33]
	v_or_b32_e32 v32, 40, v84
	v_ashrrev_i32_e32 v33, 31, v32
	v_lshl_add_u64 v[32:33], s[20:21], 0, v[32:33]
	v_mfma_f32_32x32x16_bf16 v[0:15], v[154:157], v[150:153], v[0:15]
	v_lshlrev_b64 v[32:33], 11, v[32:33]
	global_store_short v[18:19], v38, off
	v_cvt_pk_bf16_f32 v20, v20, s0
	v_lshl_add_u64 v[38:39], v[82:83], 0, v[32:33]
	global_store_short v[38:39], v20, off
	v_cvt_pk_bf16_f32 v40, v21, s0
	v_or_b32_e32 v20, 0x800, v32
	v_mov_b32_e32 v21, v33
	v_lshl_add_u64 v[20:21], v[82:83], 0, v[20:21]
	global_store_short v[20:21], v40, off
	v_or_b32_e32 v40, 0x1000, v32
	v_mov_b32_e32 v41, v33
	v_cvt_pk_bf16_f32 v22, v22, s0
	v_lshl_add_u64 v[40:41], v[82:83], 0, v[40:41]
	v_or_b32_e32 v32, 0x1800, v32
	global_store_short v[40:41], v22, off
	v_cvt_pk_bf16_f32 v42, v23, s0
	v_lshl_add_u64 v[22:23], v[82:83], 0, v[32:33]
	v_or_b32_e32 v32, 48, v84
	v_ashrrev_i32_e32 v33, 31, v32
	v_mfma_f32_32x32x16_bf16 v[0:15], v[170:173], v[162:165], v[0:15]
	v_lshl_add_u64 v[32:33], s[20:21], 0, v[32:33]
	v_lshlrev_b64 v[32:33], 11, v[32:33]
	global_store_short v[22:23], v42, off
	v_cvt_pk_bf16_f32 v24, v24, s0
	v_lshl_add_u64 v[42:43], v[82:83], 0, v[32:33]
	global_store_short v[42:43], v24, off
	v_cvt_pk_bf16_f32 v44, v25, s0
	v_or_b32_e32 v24, 0x800, v32
	v_mov_b32_e32 v25, v33
	v_lshl_add_u64 v[24:25], v[82:83], 0, v[24:25]
	global_store_short v[24:25], v44, off
	v_or_b32_e32 v44, 0x1000, v32
	v_mov_b32_e32 v45, v33
	v_cvt_pk_bf16_f32 v26, v26, s0
	v_lshl_add_u64 v[44:45], v[82:83], 0, v[44:45]
	v_or_b32_e32 v32, 0x1800, v32
	global_store_short v[44:45], v26, off
	v_cvt_pk_bf16_f32 v46, v27, s0
	v_lshl_add_u64 v[26:27], v[82:83], 0, v[32:33]
	v_or_b32_e32 v32, 56, v84
	v_mfma_f32_32x32x16_bf16 v[0:15], v[194:197], v[186:189], v[0:15]
	v_ashrrev_i32_e32 v33, 31, v32
	v_lshl_add_u64 v[32:33], s[20:21], 0, v[32:33]
	v_lshlrev_b64 v[32:33], 11, v[32:33]
	global_store_short v[26:27], v46, off
	v_cvt_pk_bf16_f32 v28, v28, s0
	v_lshl_add_u64 v[46:47], v[82:83], 0, v[32:33]
	global_store_short v[46:47], v28, off
	v_cvt_pk_bf16_f32 v48, v29, s0
	v_or_b32_e32 v28, 0x800, v32
	v_mov_b32_e32 v29, v33
	v_lshl_add_u64 v[28:29], v[82:83], 0, v[28:29]
	global_store_short v[28:29], v48, off
	v_or_b32_e32 v48, 0x1000, v32
	v_mov_b32_e32 v49, v33
	v_cvt_pk_bf16_f32 v30, v30, s0
	v_lshl_add_u64 v[48:49], v[82:83], 0, v[48:49]
	v_or_b32_e32 v32, 0x1800, v32
	global_store_short v[48:49], v30, off
	v_cvt_pk_bf16_f32 v50, v31, s0
	v_lshl_add_u64 v[30:31], v[82:83], 0, v[32:33]
	v_cvt_pk_bf16_f32 v0, v0, s0
	global_store_short v[30:31], v50, off
	global_store_short v[34:35], v0, off offset:64
	v_cvt_pk_bf16_f32 v0, v1, s0
	global_store_short v[16:17], v0, off offset:64
	v_cvt_pk_bf16_f32 v0, v2, s0
	global_store_short v[36:37], v0, off offset:64
	v_cvt_pk_bf16_f32 v0, v3, s0
	global_store_short v[18:19], v0, off offset:64
	v_cvt_pk_bf16_f32 v0, v4, s0
	global_store_short v[38:39], v0, off offset:64
	v_cvt_pk_bf16_f32 v0, v5, s0
	global_store_short v[20:21], v0, off offset:64
	v_cvt_pk_bf16_f32 v0, v6, s0
	global_store_short v[40:41], v0, off offset:64
	v_cvt_pk_bf16_f32 v0, v7, s0
	global_store_short v[22:23], v0, off offset:64
	v_cvt_pk_bf16_f32 v0, v8, s0
	global_store_short v[42:43], v0, off offset:64
	v_cvt_pk_bf16_f32 v0, v9, s0
	global_store_short v[24:25], v0, off offset:64
	v_cvt_pk_bf16_f32 v0, v10, s0
	global_store_short v[44:45], v0, off offset:64
	v_cvt_pk_bf16_f32 v0, v11, s0
	global_store_short v[26:27], v0, off offset:64
	v_cvt_pk_bf16_f32 v0, v12, s0
	global_store_short v[46:47], v0, off offset:64
	v_cvt_pk_bf16_f32 v0, v13, s0
	global_store_short v[28:29], v0, off offset:64
	v_cvt_pk_bf16_f32 v0, v14, s0
	global_store_short v[48:49], v0, off offset:64
	v_cvt_pk_bf16_f32 v0, v15, s0
	global_store_short v[30:31], v0, off offset:64
	s_waitcnt vmcnt(0)
	s_cbranch_scc0 .LBB0_95

; DEV int stage_next(int s) { return (s == 2 * GS_STAGE) ? 0 : s + GS_STAGE; }
; template <int WAIT0>
; DEV void gk_main(f32x16 (&acc)[2][2], const GTile& t, int s0) {
;     ...
;   vm_wait_bar<WAIT0>();
;   int stc = s0, std_ = stage_next(stage_next(s0));
; #pragma nounroll
;   for (int kt = 0; kt < nk - 2; ++kt) {
;     GK_DMA(std_, kt + 2);
;     GK_COMPUTE(stc);
;     vm_wait_bar<6>();
;     stc = stage_next(stc); std_ = stage_next(std_);
;   }
.LBB0_276:
	s_add_i32 s12, s10, s11
	v_lshl_add_u64 v[84:85], v[74:75], 0, s[6:7]
	s_mov_b32 m0, s12
	s_nop 0
	global_load_lds_dwordx4 v[84:85], off
	v_lshl_add_u64 v[84:85], v[72:73], 0, s[6:7]
	s_add_i32 m0, s12, 0x2000
	s_nop 0
	global_load_lds_dwordx4 v[84:85], off
	s_add_i32 m0, s12, 0x4000
	v_lshl_add_u64 v[84:85], v[70:71], 0, s[6:7]
	global_load_lds_dwordx4 v[84:85], off
	v_lshl_add_u64 v[84:85], v[68:69], 0, s[6:7]
	s_add_i32 m0, s12, 0x6000
	s_nop 0
	global_load_lds_dwordx4 v[84:85], off
	v_lshl_add_u64 v[84:85], v[66:67], 0, s[6:7]
	s_add_i32 m0, s12, 0x8000
	s_nop 0
	global_load_lds_dwordx4 v[84:85], off
	v_lshl_add_u64 v[84:85], v[64:65], 0, s[6:7]
	s_add_i32 m0, s12, 0xa000
	s_add_i32 s12, s3, 0
	global_load_lds_dwordx4 v[84:85], off
	v_add_u32_e32 v252, s12, v82
	v_add_u32_e32 v253, s12, v83
	ds_read_b128 v[84:87], v252
	ds_read_b128 v[88:91], v252 offset:4096
	ds_read_b128 v[92:95], v253 offset:16384
	ds_read_b128 v[96:99], v253 offset:20480
	s_waitcnt lgkmcnt(0)
	v_add_u32_e32 v252, s12, v80
	v_add_u32_e32 v253, s12, v81
	ds_read_b128 v[236:239], v252
	ds_read_b128 v[240:243], v252 offset:4096
	ds_read_b128 v[244:247], v253 offset:16384
	ds_read_b128 v[248:251], v253 offset:20480
	v_mfma_f32_32x32x16_bf16 v[48:63], v[92:95], v[84:87], v[48:63]
	v_mfma_f32_32x32x16_bf16 v[16:31], v[92:95], v[88:91], v[16:31]
	v_mfma_f32_32x32x16_bf16 v[32:47], v[96:99], v[84:87], v[32:47]
	v_mfma_f32_32x32x16_bf16 v[0:15], v[96:99], v[88:91], v[0:15]
	s_waitcnt lgkmcnt(0)
	v_add_u32_e32 v252, s12, v78
	v_add_u32_e32 v253, s12, v79
	ds_read_b128 v[84:87], v252
	ds_read_b128 v[88:91], v252 offset:4096
	ds_read_b128 v[92:95], v253 offset:16384
	ds_read_b128 v[96:99], v253 offset:20480
	v_mfma_f32_32x32x16_bf16 v[48:63], v[244:247], v[236:239], v[48:63]
	v_mfma_f32_32x32x16_bf16 v[16:31], v[244:247], v[240:243], v[16:31]
	v_mfma_f32_32x32x16_bf16 v[32:47], v[248:251], v[236:239], v[32:47]
	v_mfma_f32_32x32x16_bf16 v[0:15], v[248:251], v[240:243], v[0:15]
	s_waitcnt lgkmcnt(0)
	v_add_u32_e32 v252, s12, v76
	v_add_u32_e32 v253, s12, v77
	ds_read_b128 v[236:239], v252
	ds_read_b128 v[240:243], v252 offset:4096
	ds_read_b128 v[244:247], v253 offset:16384
	ds_read_b128 v[248:251], v253 offset:20480
	v_mfma_f32_32x32x16_bf16 v[48:63], v[92:95], v[84:87], v[48:63]
	v_mfma_f32_32x32x16_bf16 v[16:31], v[92:95], v[88:91], v[16:31]
	v_mfma_f32_32x32x16_bf16 v[32:47], v[96:99], v[84:87], v[32:47]
	v_mfma_f32_32x32x16_bf16 v[0:15], v[96:99], v[88:91], v[0:15]
	s_add_i32 s12, s3, 0xc000
	s_cmp_lg_u32 s3, 0x18000
	s_cselect_b32 s3, s12, 0
	s_waitcnt lgkmcnt(0)
	v_mfma_f32_32x32x16_bf16 v[48:63], v[244:247], v[236:239], v[48:63]
	s_add_i32 s12, s11, 0xc000
	s_cmp_lg_u32 s11, 0x18000
	s_waitcnt vmcnt(6) lgkmcnt(0)
	s_barrier
	s_cselect_b32 s11, s12, 0
	s_add_u32 s6, s6, 0x80
	v_mfma_f32_32x32x16_bf16 v[16:31], v[244:247], v[240:243], v[16:31]
	s_addc_u32 s7, s7, 0
	s_cmpk_lg_i32 s6, 0x700
	v_mfma_f32_32x32x16_bf16 v[32:47], v[248:251], v[236:239], v[32:47]
	v_mfma_f32_32x32x16_bf16 v[0:15], v[248:251], v[240:243], v[0:15]
	s_cbranch_scc1 .LBB0_276
; DEV int stage_next(int s) { return (s == 2 * GS_STAGE) ? 0 : s + GS_STAGE; }
; template <int WAIT0>
; DEV void gk_main(f32x16 (&acc)[2][2], const GTile& t, int s0) {
;     ...
;   GK_COMPUTE(stc);
;   vm_wait_bar<0>();
;   stc = stage_next(stc);
;   GK_COMPUTE(stc);
;   vm_wait_bar<0>();
	s_add_i32 s6, s3, 0
	v_add_u32_e32 v84, s6, v83
	ds_read_b128 v[64:67], v84 offset:16384
	v_add_u32_e32 v72, s6, v82
	ds_read_b128 v[68:71], v72
	ds_read_b128 v[72:75], v72 offset:4096
	s_waitcnt lgkmcnt(0)
	v_mfma_f32_32x32x16_bf16 v[48:63], v[64:67], v[68:71], v[48:63]
	v_mfma_f32_32x32x16_bf16 v[16:31], v[64:67], v[72:75], v[16:31]
	ds_read_b128 v[64:67], v84 offset:20480
	v_add_u32_e32 v84, s6, v81
	s_waitcnt lgkmcnt(0)
	v_mfma_f32_32x32x16_bf16 v[32:47], v[64:67], v[68:71], v[32:47]
	v_mfma_f32_32x32x16_bf16 v[0:15], v[64:67], v[72:75], v[0:15]
	ds_read_b128 v[64:67], v84 offset:16384
	v_add_u32_e32 v72, s6, v80
	ds_read_b128 v[68:71], v72
	ds_read_b128 v[72:75], v72 offset:4096
	s_waitcnt lgkmcnt(0)
	v_mfma_f32_32x32x16_bf16 v[48:63], v[64:67], v[68:71], v[48:63]
	v_mfma_f32_32x32x16_bf16 v[16:31], v[64:67], v[72:75], v[16:31]
	ds_read_b128 v[64:67], v84 offset:20480
	v_add_u32_e32 v84, s6, v79
	s_waitcnt lgkmcnt(0)
	v_mfma_f32_32x32x16_bf16 v[32:47], v[64:67], v[68:71], v[32:47]
	v_mfma_f32_32x32x16_bf16 v[0:15], v[64:67], v[72:75], v[0:15]
	ds_read_b128 v[64:67], v84 offset:16384
	v_add_u32_e32 v72, s6, v78
	ds_read_b128 v[68:71], v72
	ds_read_b128 v[72:75], v72 offset:4096
	s_waitcnt lgkmcnt(0)
	v_mfma_f32_32x32x16_bf16 v[48:63], v[64:67], v[68:71], v[48:63]
	v_mfma_f32_32x32x16_bf16 v[16:31], v[64:67], v[72:75], v[16:31]
	ds_read_b128 v[64:67], v84 offset:20480
	v_add_u32_e32 v84, s6, v77
	s_waitcnt lgkmcnt(0)
	v_mfma_f32_32x32x16_bf16 v[32:47], v[64:67], v[68:71], v[32:47]
	v_mfma_f32_32x32x16_bf16 v[0:15], v[64:67], v[72:75], v[0:15]
	ds_read_b128 v[64:67], v84 offset:16384
	v_add_u32_e32 v72, s6, v76
	ds_read_b128 v[68:71], v72
	ds_read_b128 v[72:75], v72 offset:4096
	s_add_i32 s6, s3, 0xc000
	s_cmp_lg_u32 s3, 0x18000
	s_cselect_b32 s3, s6, 0
	s_waitcnt lgkmcnt(0)
	v_mfma_f32_32x32x16_bf16 v[48:63], v[64:67], v[68:71], v[48:63]
	s_add_i32 s3, s3, 0
	v_add_u32_e32 v83, s3, v83
	v_add_u32_e32 v81, s3, v81
	v_add_u32_e32 v79, s3, v79
	v_add_u32_e32 v77, s3, v77
	s_mov_b64 s[6:7], 0
	v_mfma_f32_32x32x16_bf16 v[16:31], v[64:67], v[72:75], v[16:31]
	ds_read_b128 v[64:67], v84 offset:20480
	s_waitcnt vmcnt(0) lgkmcnt(0)
	s_barrier
	s_waitcnt lgkmcnt(0)
	v_mfma_f32_32x32x16_bf16 v[32:47], v[64:67], v[68:71], v[32:47]
	v_mfma_f32_32x32x16_bf16 v[0:15], v[64:67], v[72:75], v[0:15]
	ds_read_b128 v[64:67], v83 offset:16384
	v_add_u32_e32 v72, s3, v82
	ds_read_b128 v[68:71], v72
	ds_read_b128 v[72:75], v72 offset:4096
	s_waitcnt lgkmcnt(0)
	v_mfma_f32_32x32x16_bf16 v[48:63], v[64:67], v[68:71], v[48:63]
	v_mfma_f32_32x32x16_bf16 v[16:31], v[64:67], v[72:75], v[16:31]
	ds_read_b128 v[64:67], v83 offset:20480
	s_waitcnt lgkmcnt(0)
	v_mfma_f32_32x32x16_bf16 v[32:47], v[64:67], v[68:71], v[32:47]
	v_mfma_f32_32x32x16_bf16 v[0:15], v[64:67], v[72:75], v[0:15]
	ds_read_b128 v[64:67], v81 offset:16384
	v_add_u32_e32 v72, s3, v80
	ds_read_b128 v[68:71], v72
	ds_read_b128 v[72:75], v72 offset:4096
	s_waitcnt lgkmcnt(0)
	v_mfma_f32_32x32x16_bf16 v[48:63], v[64:67], v[68:71], v[48:63]
	v_mfma_f32_32x32x16_bf16 v[16:31], v[64:67], v[72:75], v[16:31]
	ds_read_b128 v[64:67], v81 offset:20480
	s_waitcnt lgkmcnt(0)
	v_mfma_f32_32x32x16_bf16 v[32:47], v[64:67], v[68:71], v[32:47]
	v_mfma_f32_32x32x16_bf16 v[0:15], v[64:67], v[72:75], v[0:15]
	ds_read_b128 v[64:67], v79 offset:16384
	v_add_u32_e32 v72, s3, v78
	ds_read_b128 v[68:71], v72
	ds_read_b128 v[72:75], v72 offset:4096
	s_waitcnt lgkmcnt(0)
	v_mfma_f32_32x32x16_bf16 v[48:63], v[64:67], v[68:71], v[48:63]
	v_mfma_f32_32x32x16_bf16 v[16:31], v[64:67], v[72:75], v[16:31]
	ds_read_b128 v[64:67], v79 offset:20480
	s_waitcnt lgkmcnt(0)
	v_mfma_f32_32x32x16_bf16 v[32:47], v[64:67], v[68:71], v[32:47]
	v_mfma_f32_32x32x16_bf16 v[0:15], v[64:67], v[72:75], v[0:15]
	ds_read_b128 v[64:67], v77 offset:16384
	v_add_u32_e32 v72, s3, v76
	ds_read_b128 v[68:71], v72
	ds_read_b128 v[72:75], v72 offset:4096
	s_waitcnt lgkmcnt(0)
	v_mfma_f32_32x32x16_bf16 v[48:63], v[64:67], v[68:71], v[48:63]
	v_mfma_f32_32x32x16_bf16 v[16:31], v[64:67], v[72:75], v[16:31]
	ds_read_b128 v[64:67], v77 offset:20480
	s_waitcnt vmcnt(0) lgkmcnt(0)
	s_barrier
	s_waitcnt lgkmcnt(0)
	v_mfma_f32_32x32x16_bf16 v[32:47], v[64:67], v[68:71], v[32:47]
	v_mfma_f32_32x32x16_bf16 v[0:15], v[64:67], v[72:75], v[0:15]

; DEV int stage_next(int s) { return (s == 2 * GS_STAGE) ? 0 : s + GS_STAGE; }
; template <int WAIT0>
; DEV void gk_main(f32x16 (&acc)[2][2], const GTile& t, int s0) {
;     ...
;   vm_wait_bar<WAIT0>();
;   int stc = s0, std_ = stage_next(stage_next(s0));
; #pragma nounroll
;   for (int kt = 0; kt < nk - 2; ++kt) {
;     GK_DMA(std_, kt + 2);
;     GK_COMPUTE(stc);
;     vm_wait_bar<6>();
;     stc = stage_next(stc); std_ = stage_next(std_);
;   }
.LBB0_280:
	s_add_i32 s12, s10, s11
	v_lshl_add_u64 v[84:85], v[74:75], 0, s[6:7]
	s_mov_b32 m0, s12
	s_nop 0
	global_load_lds_dwordx4 v[84:85], off
	v_lshl_add_u64 v[84:85], v[72:73], 0, s[6:7]
	s_add_i32 m0, s12, 0x2000
	s_nop 0
	global_load_lds_dwordx4 v[84:85], off
	s_add_i32 m0, s12, 0x4000
	v_lshl_add_u64 v[84:85], v[70:71], 0, s[6:7]
	global_load_lds_dwordx4 v[84:85], off
	v_lshl_add_u64 v[84:85], v[68:69], 0, s[6:7]
	s_add_i32 m0, s12, 0x6000
	s_nop 0
	global_load_lds_dwordx4 v[84:85], off
	v_lshl_add_u64 v[84:85], v[66:67], 0, s[6:7]
	s_add_i32 m0, s12, 0x8000
	s_nop 0
	global_load_lds_dwordx4 v[84:85], off
	v_lshl_add_u64 v[84:85], v[64:65], 0, s[6:7]
	s_add_i32 m0, s12, 0xa000
	s_add_i32 s12, s3, 0
	global_load_lds_dwordx4 v[84:85], off
	v_add_u32_e32 v252, s12, v82
	v_add_u32_e32 v253, s12, v83
	ds_read_b128 v[84:87], v252
	ds_read_b128 v[88:91], v252 offset:4096
	ds_read_b128 v[92:95], v253 offset:16384
	ds_read_b128 v[96:99], v253 offset:20480
	s_waitcnt lgkmcnt(0)
	v_add_u32_e32 v252, s12, v80
	v_add_u32_e32 v253, s12, v81
	ds_read_b128 v[236:239], v252
	ds_read_b128 v[240:243], v252 offset:4096
	ds_read_b128 v[244:247], v253 offset:16384
	ds_read_b128 v[248:251], v253 offset:20480
	v_mfma_f32_32x32x16_bf16 v[48:63], v[92:95], v[84:87], v[48:63]
	v_mfma_f32_32x32x16_bf16 v[16:31], v[92:95], v[88:91], v[16:31]
	v_mfma_f32_32x32x16_bf16 v[32:47], v[96:99], v[84:87], v[32:47]
	v_mfma_f32_32x32x16_bf16 v[0:15], v[96:99], v[88:91], v[0:15]
	s_waitcnt lgkmcnt(0)
	v_add_u32_e32 v252, s12, v78
	v_add_u32_e32 v253, s12, v79
	ds_read_b128 v[84:87], v252
	ds_read_b128 v[88:91], v252 offset:4096
	ds_read_b128 v[92:95], v253 offset:16384
	ds_read_b128 v[96:99], v253 offset:20480
	v_mfma_f32_32x32x16_bf16 v[48:63], v[244:247], v[236:239], v[48:63]
	v_mfma_f32_32x32x16_bf16 v[16:31], v[244:247], v[240:243], v[16:31]
	v_mfma_f32_32x32x16_bf16 v[32:47], v[248:251], v[236:239], v[32:47]
	v_mfma_f32_32x32x16_bf16 v[0:15], v[248:251], v[240:243], v[0:15]
	s_waitcnt lgkmcnt(0)
	v_add_u32_e32 v252, s12, v76
	v_add_u32_e32 v253, s12, v77
	ds_read_b128 v[236:239], v252
	ds_read_b128 v[240:243], v252 offset:4096
	ds_read_b128 v[244:247], v253 offset:16384
	ds_read_b128 v[248:251], v253 offset:20480
	v_mfma_f32_32x32x16_bf16 v[48:63], v[92:95], v[84:87], v[48:63]
	v_mfma_f32_32x32x16_bf16 v[16:31], v[92:95], v[88:91], v[16:31]
	v_mfma_f32_32x32x16_bf16 v[32:47], v[96:99], v[84:87], v[32:47]
	v_mfma_f32_32x32x16_bf16 v[0:15], v[96:99], v[88:91], v[0:15]
	s_add_i32 s12, s3, 0xc000
	s_cmp_lg_u32 s3, 0x18000
	s_cselect_b32 s3, s12, 0
	s_waitcnt lgkmcnt(0)
	v_mfma_f32_32x32x16_bf16 v[48:63], v[244:247], v[236:239], v[48:63]
	s_add_i32 s12, s11, 0xc000
	s_cmp_lg_u32 s11, 0x18000
	s_waitcnt vmcnt(6) lgkmcnt(0)
	s_barrier
	s_cselect_b32 s11, s12, 0
	s_add_u32 s6, s6, 0x80
	v_mfma_f32_32x32x16_bf16 v[16:31], v[244:247], v[240:243], v[16:31]
	s_addc_u32 s7, s7, 0
	s_cmpk_lg_i32 s6, 0x700
	v_mfma_f32_32x32x16_bf16 v[32:47], v[248:251], v[236:239], v[32:47]
	v_mfma_f32_32x32x16_bf16 v[0:15], v[248:251], v[240:243], v[0:15]
	s_cbranch_scc1 .LBB0_280
; DEV int stage_next(int s) { return (s == 2 * GS_STAGE) ? 0 : s + GS_STAGE; }
; template <int WAIT0>
; DEV void gk_main(f32x16 (&acc)[2][2], const GTile& t, int s0) {
;     ...
;   GK_COMPUTE(stc);
;   vm_wait_bar<0>();
;   stc = stage_next(stc);
;   GK_COMPUTE(stc);
;   vm_wait_bar<0>();
	s_add_i32 s6, s3, 0
	v_add_u32_e32 v84, s6, v83
	ds_read_b128 v[64:67], v84 offset:16384
	v_add_u32_e32 v72, s6, v82
	ds_read_b128 v[68:71], v72
	ds_read_b128 v[72:75], v72 offset:4096
	s_waitcnt lgkmcnt(0)
	v_mfma_f32_32x32x16_bf16 v[48:63], v[64:67], v[68:71], v[48:63]
	v_mfma_f32_32x32x16_bf16 v[16:31], v[64:67], v[72:75], v[16:31]
	ds_read_b128 v[64:67], v84 offset:20480
	v_add_u32_e32 v84, s6, v81
	s_waitcnt lgkmcnt(0)
	v_mfma_f32_32x32x16_bf16 v[32:47], v[64:67], v[68:71], v[32:47]
	v_mfma_f32_32x32x16_bf16 v[0:15], v[64:67], v[72:75], v[0:15]
	ds_read_b128 v[64:67], v84 offset:16384
	v_add_u32_e32 v72, s6, v80
	ds_read_b128 v[68:71], v72
	ds_read_b128 v[72:75], v72 offset:4096
	s_waitcnt lgkmcnt(0)
	v_mfma_f32_32x32x16_bf16 v[48:63], v[64:67], v[68:71], v[48:63]
	v_mfma_f32_32x32x16_bf16 v[16:31], v[64:67], v[72:75], v[16:31]
	ds_read_b128 v[64:67], v84 offset:20480
	v_add_u32_e32 v84, s6, v79
	s_waitcnt lgkmcnt(0)
	v_mfma_f32_32x32x16_bf16 v[32:47], v[64:67], v[68:71], v[32:47]
	v_mfma_f32_32x32x16_bf16 v[0:15], v[64:67], v[72:75], v[0:15]
	ds_read_b128 v[64:67], v84 offset:16384
	v_add_u32_e32 v72, s6, v78
	ds_read_b128 v[68:71], v72
	ds_read_b128 v[72:75], v72 offset:4096
	s_waitcnt lgkmcnt(0)
	v_mfma_f32_32x32x16_bf16 v[48:63], v[64:67], v[68:71], v[48:63]
	v_mfma_f32_32x32x16_bf16 v[16:31], v[64:67], v[72:75], v[16:31]
	ds_read_b128 v[64:67], v84 offset:20480
	v_add_u32_e32 v84, s6, v77
	s_waitcnt lgkmcnt(0)
	v_mfma_f32_32x32x16_bf16 v[32:47], v[64:67], v[68:71], v[32:47]
	v_mfma_f32_32x32x16_bf16 v[0:15], v[64:67], v[72:75], v[0:15]
	ds_read_b128 v[64:67], v84 offset:16384
	v_add_u32_e32 v72, s6, v76
	ds_read_b128 v[68:71], v72
	ds_read_b128 v[72:75], v72 offset:4096
	s_add_i32 s6, s3, 0xc000
	s_cmp_lg_u32 s3, 0x18000
	s_cselect_b32 s3, s6, 0
	s_waitcnt lgkmcnt(0)
	v_mfma_f32_32x32x16_bf16 v[48:63], v[64:67], v[68:71], v[48:63]
	s_add_i32 s3, s3, 0
	v_add_u32_e32 v83, s3, v83
	v_add_u32_e32 v81, s3, v81
	v_add_u32_e32 v79, s3, v79
	v_add_u32_e32 v77, s3, v77
	v_mfma_f32_32x32x16_bf16 v[16:31], v[64:67], v[72:75], v[16:31]
	ds_read_b128 v[64:67], v84 offset:20480
	s_waitcnt vmcnt(0) lgkmcnt(0)
	s_barrier
	s_waitcnt lgkmcnt(0)
	v_mfma_f32_32x32x16_bf16 v[32:47], v[64:67], v[68:71], v[32:47]
	v_mfma_f32_32x32x16_bf16 v[0:15], v[64:67], v[72:75], v[0:15]
	ds_read_b128 v[64:67], v83 offset:16384
	v_add_u32_e32 v72, s3, v82
	ds_read_b128 v[68:71], v72
	ds_read_b128 v[72:75], v72 offset:4096
	s_waitcnt lgkmcnt(0)
	v_mfma_f32_32x32x16_bf16 v[48:63], v[64:67], v[68:71], v[48:63]
	v_mfma_f32_32x32x16_bf16 v[16:31], v[64:67], v[72:75], v[16:31]
	ds_read_b128 v[64:67], v83 offset:20480
	s_waitcnt lgkmcnt(0)
	v_mfma_f32_32x32x16_bf16 v[32:47], v[64:67], v[68:71], v[32:47]
	v_mfma_f32_32x32x16_bf16 v[0:15], v[64:67], v[72:75], v[0:15]
	ds_read_b128 v[64:67], v81 offset:16384
	v_add_u32_e32 v72, s3, v80
	ds_read_b128 v[68:71], v72
	ds_read_b128 v[72:75], v72 offset:4096
	s_waitcnt lgkmcnt(0)
	v_mfma_f32_32x32x16_bf16 v[48:63], v[64:67], v[68:71], v[48:63]
	v_mfma_f32_32x32x16_bf16 v[16:31], v[64:67], v[72:75], v[16:31]
	ds_read_b128 v[64:67], v81 offset:20480
	s_waitcnt lgkmcnt(0)
	v_mfma_f32_32x32x16_bf16 v[32:47], v[64:67], v[68:71], v[32:47]
	v_mfma_f32_32x32x16_bf16 v[0:15], v[64:67], v[72:75], v[0:15]
	ds_read_b128 v[64:67], v79 offset:16384
	v_add_u32_e32 v72, s3, v78
	ds_read_b128 v[68:71], v72
	ds_read_b128 v[72:75], v72 offset:4096
	s_waitcnt lgkmcnt(0)
	v_mfma_f32_32x32x16_bf16 v[48:63], v[64:67], v[68:71], v[48:63]
	v_mfma_f32_32x32x16_bf16 v[16:31], v[64:67], v[72:75], v[16:31]
	ds_read_b128 v[64:67], v79 offset:20480
	s_waitcnt lgkmcnt(0)
	v_mfma_f32_32x32x16_bf16 v[32:47], v[64:67], v[68:71], v[32:47]
	v_mfma_f32_32x32x16_bf16 v[0:15], v[64:67], v[72:75], v[0:15]
	ds_read_b128 v[64:67], v77 offset:16384
	v_add_u32_e32 v72, s3, v76
	ds_read_b128 v[68:71], v72
	ds_read_b128 v[72:75], v72 offset:4096
	s_waitcnt lgkmcnt(0)
	v_mfma_f32_32x32x16_bf16 v[48:63], v[64:67], v[68:71], v[48:63]
	v_mfma_f32_32x32x16_bf16 v[16:31], v[64:67], v[72:75], v[16:31]
	ds_read_b128 v[64:67], v77 offset:20480
	s_waitcnt vmcnt(0) lgkmcnt(0)
	s_barrier
	s_waitcnt lgkmcnt(0)
	v_mfma_f32_32x32x16_bf16 v[32:47], v[64:67], v[68:71], v[32:47]
	v_mfma_f32_32x32x16_bf16 v[0:15], v[64:67], v[72:75], v[0:15]

; DEV int stage_next(int s) { return (s == 2 * GS_STAGE) ? 0 : s + GS_STAGE; }
; template <int WAIT0>
; DEV void gk_main(f32x16 (&acc)[2][2], const GTile& t, int s0) {
;     ...
;   vm_wait_bar<WAIT0>();
;   int stc = s0, std_ = stage_next(stage_next(s0));
; #pragma nounroll
;   for (int kt = 0; kt < nk - 2; ++kt) {
;     GK_DMA(std_, kt + 2);
;     GK_COMPUTE(stc);
;     vm_wait_bar<6>();
;     stc = stage_next(stc); std_ = stage_next(std_);
;   }
.LBB0_286:
	s_add_i32 s12, s10, s11
	v_lshl_add_u64 v[84:85], v[74:75], 0, s[6:7]
	s_mov_b32 m0, s12
	s_nop 0
	global_load_lds_dwordx4 v[84:85], off
	v_lshl_add_u64 v[84:85], v[72:73], 0, s[6:7]
	s_add_i32 m0, s12, 0x2000
	s_nop 0
	global_load_lds_dwordx4 v[84:85], off
	s_add_i32 m0, s12, 0x4000
	v_lshl_add_u64 v[84:85], v[70:71], 0, s[6:7]
	global_load_lds_dwordx4 v[84:85], off
	v_lshl_add_u64 v[84:85], v[68:69], 0, s[6:7]
	s_add_i32 m0, s12, 0x6000
	s_nop 0
	global_load_lds_dwordx4 v[84:85], off
	v_lshl_add_u64 v[84:85], v[66:67], 0, s[6:7]
	s_add_i32 m0, s12, 0x8000
	s_nop 0
	global_load_lds_dwordx4 v[84:85], off
	v_lshl_add_u64 v[84:85], v[64:65], 0, s[6:7]
	s_add_i32 m0, s12, 0xa000
	s_add_i32 s12, s3, 0
	global_load_lds_dwordx4 v[84:85], off
	v_add_u32_e32 v252, s12, v82
	v_add_u32_e32 v253, s12, v83
	ds_read_b128 v[84:87], v252
	ds_read_b128 v[88:91], v252 offset:4096
	ds_read_b128 v[92:95], v253 offset:16384
	ds_read_b128 v[96:99], v253 offset:20480
	s_waitcnt lgkmcnt(0)
	v_add_u32_e32 v252, s12, v80
	v_add_u32_e32 v253, s12, v81
	ds_read_b128 v[236:239], v252
	ds_read_b128 v[240:243], v252 offset:4096
	ds_read_b128 v[244:247], v253 offset:16384
	ds_read_b128 v[248:251], v253 offset:20480
	v_mfma_f32_32x32x16_bf16 v[48:63], v[92:95], v[84:87], v[48:63]
	v_mfma_f32_32x32x16_bf16 v[16:31], v[92:95], v[88:91], v[16:31]
	v_mfma_f32_32x32x16_bf16 v[32:47], v[96:99], v[84:87], v[32:47]
	v_mfma_f32_32x32x16_bf16 v[0:15], v[96:99], v[88:91], v[0:15]
	s_waitcnt lgkmcnt(0)
	v_add_u32_e32 v252, s12, v78
	v_add_u32_e32 v253, s12, v79
	ds_read_b128 v[84:87], v252
	ds_read_b128 v[88:91], v252 offset:4096
	ds_read_b128 v[92:95], v253 offset:16384
	ds_read_b128 v[96:99], v253 offset:20480
	v_mfma_f32_32x32x16_bf16 v[48:63], v[244:247], v[236:239], v[48:63]
	v_mfma_f32_32x32x16_bf16 v[16:31], v[244:247], v[240:243], v[16:31]
	v_mfma_f32_32x32x16_bf16 v[32:47], v[248:251], v[236:239], v[32:47]
	v_mfma_f32_32x32x16_bf16 v[0:15], v[248:251], v[240:243], v[0:15]
	s_waitcnt lgkmcnt(0)
	v_add_u32_e32 v252, s12, v76
	v_add_u32_e32 v253, s12, v77
	ds_read_b128 v[236:239], v252
	ds_read_b128 v[240:243], v252 offset:4096
	ds_read_b128 v[244:247], v253 offset:16384
	ds_read_b128 v[248:251], v253 offset:20480
	v_mfma_f32_32x32x16_bf16 v[48:63], v[92:95], v[84:87], v[48:63]
	v_mfma_f32_32x32x16_bf16 v[16:31], v[92:95], v[88:91], v[16:31]
	v_mfma_f32_32x32x16_bf16 v[32:47], v[96:99], v[84:87], v[32:47]
	v_mfma_f32_32x32x16_bf16 v[0:15], v[96:99], v[88:91], v[0:15]
	s_add_i32 s12, s3, 0xc000
	s_cmp_lg_u32 s3, 0x18000
	s_cselect_b32 s3, s12, 0
	s_waitcnt lgkmcnt(0)
	v_mfma_f32_32x32x16_bf16 v[48:63], v[244:247], v[236:239], v[48:63]
	s_add_i32 s12, s11, 0xc000
	s_cmp_lg_u32 s11, 0x18000
	s_waitcnt vmcnt(6) lgkmcnt(0)
	s_barrier
	s_cselect_b32 s11, s12, 0
	s_add_u32 s6, s6, 0x80
	v_mfma_f32_32x32x16_bf16 v[16:31], v[244:247], v[240:243], v[16:31]
	s_addc_u32 s7, s7, 0
	s_cmpk_lg_i32 s6, 0x700
	v_mfma_f32_32x32x16_bf16 v[32:47], v[248:251], v[236:239], v[32:47]
	v_mfma_f32_32x32x16_bf16 v[0:15], v[248:251], v[240:243], v[0:15]
	s_cbranch_scc1 .LBB0_286
; DEV int stage_next(int s) { return (s == 2 * GS_STAGE) ? 0 : s + GS_STAGE; }
; template <int WAIT0>
; DEV void gk_main(f32x16 (&acc)[2][2], const GTile& t, int s0) {
;     ...
;   GK_COMPUTE(stc);
;   vm_wait_bar<0>();
;   stc = stage_next(stc);
;   GK_COMPUTE(stc);
;   vm_wait_bar<0>();
; template <int WAIT_E, int WAIT_O, class TileFn, class EpiFn>
; DEV void gemm_seq(int ntiles, TileFn tf, EpiFn epi) {
;     ...
;   for (int i = 0; i < ntiles; ++i) {
;     f32x16 acc[2][2]; acc_zero(acc);
;     if (i == 0) gk_main<6>(acc, cur, s0);
;     else if (i & 1) gk_main<WAIT_O>(acc, cur, s0);
;     else gk_main<WAIT_E>(acc, cur, s0);
;     const int sn = stage_next(s0);
;     if (i + 1 < ntiles) { cur = tf(i + 1); gk_issue2(cur, sn); }
;     epi(i, acc, s0);
;     s0 = sn;
;   }
	s_add_i32 s6, s3, 0
	v_add_u32_e32 v84, s6, v83
	ds_read_b128 v[64:67], v84 offset:16384
	v_add_u32_e32 v72, s6, v82
	ds_read_b128 v[68:71], v72
	ds_read_b128 v[72:75], v72 offset:4096
	s_waitcnt lgkmcnt(0)
	v_mfma_f32_32x32x16_bf16 v[48:63], v[64:67], v[68:71], v[48:63]
	v_mfma_f32_32x32x16_bf16 v[16:31], v[64:67], v[72:75], v[16:31]
	ds_read_b128 v[64:67], v84 offset:20480
	v_add_u32_e32 v84, s6, v81
	s_waitcnt lgkmcnt(0)
	v_mfma_f32_32x32x16_bf16 v[32:47], v[64:67], v[68:71], v[32:47]
	v_mfma_f32_32x32x16_bf16 v[0:15], v[64:67], v[72:75], v[0:15]
	ds_read_b128 v[64:67], v84 offset:16384
	v_add_u32_e32 v72, s6, v80
	ds_read_b128 v[68:71], v72
	ds_read_b128 v[72:75], v72 offset:4096
	s_waitcnt lgkmcnt(0)
	v_mfma_f32_32x32x16_bf16 v[48:63], v[64:67], v[68:71], v[48:63]
	v_mfma_f32_32x32x16_bf16 v[16:31], v[64:67], v[72:75], v[16:31]
	ds_read_b128 v[64:67], v84 offset:20480
	v_add_u32_e32 v84, s6, v79
	s_waitcnt lgkmcnt(0)
	v_mfma_f32_32x32x16_bf16 v[32:47], v[64:67], v[68:71], v[32:47]
	v_mfma_f32_32x32x16_bf16 v[0:15], v[64:67], v[72:75], v[0:15]
	ds_read_b128 v[64:67], v84 offset:16384
	v_add_u32_e32 v72, s6, v78
	ds_read_b128 v[68:71], v72
	ds_read_b128 v[72:75], v72 offset:4096
	s_waitcnt lgkmcnt(0)
	v_mfma_f32_32x32x16_bf16 v[48:63], v[64:67], v[68:71], v[48:63]
	v_mfma_f32_32x32x16_bf16 v[16:31], v[64:67], v[72:75], v[16:31]
	ds_read_b128 v[64:67], v84 offset:20480
	v_add_u32_e32 v84, s6, v77
	s_waitcnt lgkmcnt(0)
	v_mfma_f32_32x32x16_bf16 v[32:47], v[64:67], v[68:71], v[32:47]
	v_mfma_f32_32x32x16_bf16 v[0:15], v[64:67], v[72:75], v[0:15]
	ds_read_b128 v[64:67], v84 offset:16384
	v_add_u32_e32 v72, s6, v76
	ds_read_b128 v[68:71], v72
	ds_read_b128 v[72:75], v72 offset:4096
	s_add_i32 s6, s3, 0xc000
	s_cmp_lg_u32 s3, 0x18000
	s_cselect_b32 s3, s6, 0
	s_waitcnt lgkmcnt(0)
	v_mfma_f32_32x32x16_bf16 v[48:63], v[64:67], v[68:71], v[48:63]
	s_add_i32 s3, s3, 0
	v_add_u32_e32 v83, s3, v83
	v_add_u32_e32 v81, s3, v81
	v_add_u32_e32 v79, s3, v79
	v_add_u32_e32 v77, s3, v77
	v_mfma_f32_32x32x16_bf16 v[16:31], v[64:67], v[72:75], v[16:31]
	ds_read_b128 v[64:67], v84 offset:20480
	s_waitcnt vmcnt(0) lgkmcnt(0)
	s_barrier
	s_waitcnt lgkmcnt(0)
	v_mfma_f32_32x32x16_bf16 v[32:47], v[64:67], v[68:71], v[32:47]
	v_mfma_f32_32x32x16_bf16 v[0:15], v[64:67], v[72:75], v[0:15]
	ds_read_b128 v[64:67], v83 offset:16384
	v_add_u32_e32 v72, s3, v82
	ds_read_b128 v[68:71], v72
	ds_read_b128 v[72:75], v72 offset:4096
	s_waitcnt lgkmcnt(0)
	v_mfma_f32_32x32x16_bf16 v[48:63], v[64:67], v[68:71], v[48:63]
	v_mfma_f32_32x32x16_bf16 v[16:31], v[64:67], v[72:75], v[16:31]
	ds_read_b128 v[64:67], v83 offset:20480
	s_waitcnt lgkmcnt(0)
	v_mfma_f32_32x32x16_bf16 v[32:47], v[64:67], v[68:71], v[32:47]
	v_mfma_f32_32x32x16_bf16 v[0:15], v[64:67], v[72:75], v[0:15]
	ds_read_b128 v[64:67], v81 offset:16384
	v_add_u32_e32 v72, s3, v80
	ds_read_b128 v[68:71], v72
	ds_read_b128 v[72:75], v72 offset:4096
	s_waitcnt lgkmcnt(0)
	v_mfma_f32_32x32x16_bf16 v[48:63], v[64:67], v[68:71], v[48:63]
	v_mfma_f32_32x32x16_bf16 v[16:31], v[64:67], v[72:75], v[16:31]
	ds_read_b128 v[64:67], v81 offset:20480
	s_waitcnt lgkmcnt(0)
	v_mfma_f32_32x32x16_bf16 v[32:47], v[64:67], v[68:71], v[32:47]
	v_mfma_f32_32x32x16_bf16 v[0:15], v[64:67], v[72:75], v[0:15]
	ds_read_b128 v[64:67], v79 offset:16384
	v_add_u32_e32 v72, s3, v78
	ds_read_b128 v[68:71], v72
	ds_read_b128 v[72:75], v72 offset:4096
	s_waitcnt lgkmcnt(0)
	v_mfma_f32_32x32x16_bf16 v[48:63], v[64:67], v[68:71], v[48:63]
	v_mfma_f32_32x32x16_bf16 v[16:31], v[64:67], v[72:75], v[16:31]
	ds_read_b128 v[64:67], v79 offset:20480
	s_waitcnt lgkmcnt(0)
	v_mfma_f32_32x32x16_bf16 v[32:47], v[64:67], v[68:71], v[32:47]
	v_mfma_f32_32x32x16_bf16 v[0:15], v[64:67], v[72:75], v[0:15]
	ds_read_b128 v[64:67], v77 offset:16384
	v_add_u32_e32 v72, s3, v76
	ds_read_b128 v[68:71], v72
	ds_read_b128 v[72:75], v72 offset:4096
	s_waitcnt lgkmcnt(0)
	v_mfma_f32_32x32x16_bf16 v[48:63], v[64:67], v[68:71], v[48:63]
	v_mfma_f32_32x32x16_bf16 v[16:31], v[64:67], v[72:75], v[16:31]
	ds_read_b128 v[64:67], v77 offset:20480
	s_waitcnt vmcnt(0) lgkmcnt(0)
	s_barrier
	s_waitcnt lgkmcnt(0)
	v_mfma_f32_32x32x16_bf16 v[32:47], v[64:67], v[68:71], v[32:47]
	v_mfma_f32_32x32x16_bf16 v[0:15], v[64:67], v[72:75], v[0:15]
	s_add_i32 s3, s2, 1
	s_cmp_eq_u32 s2, 3
	s_cbranch_scc1 .LBB0_272

; DEV int stage_next(int s) { return (s == 2 * GS_STAGE) ? 0 : s + GS_STAGE; }
; template <int WAIT0>
; DEV void gk_main(f32x16 (&acc)[2][2], const GTile& t, int s0) {
;     ...
;   vm_wait_bar<WAIT0>();
;   int stc = s0, std_ = stage_next(stage_next(s0));
; #pragma nounroll
;   for (int kt = 0; kt < nk - 2; ++kt) {
;     GK_DMA(std_, kt + 2);
;     GK_COMPUTE(stc);
;     vm_wait_bar<6>();
;     stc = stage_next(stc); std_ = stage_next(std_);
;   }
.LBB0_298:
	s_add_i32 s16, s1, s3
	v_lshl_add_u64 v[88:89], v[76:77], 0, s[10:11]
	s_mov_b32 m0, s16
	s_nop 0
	global_load_lds_dwordx4 v[88:89], off
	v_lshl_add_u64 v[88:89], v[74:75], 0, s[10:11]
	s_add_i32 m0, s16, 0x2000
	s_nop 0
	global_load_lds_dwordx4 v[88:89], off
	s_add_i32 m0, s16, 0x4000
	v_lshl_add_u64 v[88:89], v[72:73], 0, s[10:11]
	global_load_lds_dwordx4 v[88:89], off
	v_lshl_add_u64 v[88:89], v[70:71], 0, s[10:11]
	s_add_i32 m0, s16, 0x6000
	s_nop 0
	global_load_lds_dwordx4 v[88:89], off
	v_lshl_add_u64 v[88:89], v[68:69], 0, s[10:11]
	s_add_i32 m0, s16, 0x8000
	s_nop 0
	global_load_lds_dwordx4 v[88:89], off
	v_lshl_add_u64 v[88:89], v[66:67], 0, s[10:11]
	s_add_i32 m0, s16, 0xa000
	s_add_i32 s16, s0, 0
	global_load_lds_dwordx4 v[88:89], off
	v_add_u32_e32 v87, s16, v85
	ds_read_b128 v[88:91], v87
	ds_read_b128 v[92:95], v87 offset:4096
	v_add_u32_e32 v87, s16, v86
	ds_read_b128 v[96:99], v87 offset:16384
	ds_read_b128 v[100:103], v87 offset:20480
	s_waitcnt lgkmcnt(0)
	v_add_u32_e32 v87, s16, v83
	ds_read_b128 v[236:239], v87
	ds_read_b128 v[240:243], v87 offset:4096
	v_add_u32_e32 v87, s16, v84
	ds_read_b128 v[244:247], v87 offset:16384
	ds_read_b128 v[248:251], v87 offset:20480
	v_mfma_f32_32x32x16_bf16 v[48:63], v[96:99], v[88:91], v[48:63]
	v_mfma_f32_32x32x16_bf16 v[32:47], v[96:99], v[92:95], v[32:47]
	v_mfma_f32_32x32x16_bf16 v[16:31], v[100:103], v[88:91], v[16:31]
	v_mfma_f32_32x32x16_bf16 v[0:15], v[100:103], v[92:95], v[0:15]
	v_add_u32_e32 v87, s16, v81
	s_waitcnt lgkmcnt(0)
	ds_read_b128 v[88:91], v87
	ds_read_b128 v[92:95], v87 offset:4096
	v_add_u32_e32 v87, s16, v82
	ds_read_b128 v[96:99], v87 offset:16384
	ds_read_b128 v[100:103], v87 offset:20480
	v_mfma_f32_32x32x16_bf16 v[48:63], v[244:247], v[236:239], v[48:63]
	v_mfma_f32_32x32x16_bf16 v[32:47], v[244:247], v[240:243], v[32:47]
	v_mfma_f32_32x32x16_bf16 v[16:31], v[248:251], v[236:239], v[16:31]
	v_mfma_f32_32x32x16_bf16 v[0:15], v[248:251], v[240:243], v[0:15]
	v_add_u32_e32 v87, s16, v79
	s_waitcnt lgkmcnt(0)
	ds_read_b128 v[236:239], v87
	ds_read_b128 v[240:243], v87 offset:4096
	v_add_u32_e32 v87, s16, v80
	ds_read_b128 v[244:247], v87 offset:16384
	ds_read_b128 v[248:251], v87 offset:20480
	v_mfma_f32_32x32x16_bf16 v[48:63], v[96:99], v[88:91], v[48:63]
	v_mfma_f32_32x32x16_bf16 v[32:47], v[96:99], v[92:95], v[32:47]
	v_mfma_f32_32x32x16_bf16 v[16:31], v[100:103], v[88:91], v[16:31]
	v_mfma_f32_32x32x16_bf16 v[0:15], v[100:103], v[92:95], v[0:15]
	s_add_i32 s16, s0, 0xc000
	s_cmp_lg_u32 s0, 0x18000
	s_cselect_b32 s0, s16, 0
	s_add_i32 s16, s3, 0xc000
	s_waitcnt lgkmcnt(0)
	v_mfma_f32_32x32x16_bf16 v[48:63], v[244:247], v[236:239], v[48:63]
	s_cmp_lg_u32 s3, 0x18000
	s_waitcnt vmcnt(6) lgkmcnt(0)
	s_barrier
	s_cselect_b32 s3, s16, 0
	s_add_u32 s10, s10, 0x80
	s_addc_u32 s11, s11, 0
	v_mfma_f32_32x32x16_bf16 v[32:47], v[244:247], v[240:243], v[32:47]
	s_cmpk_lg_i32 s10, 0x700
	v_mfma_f32_32x32x16_bf16 v[16:31], v[248:251], v[236:239], v[16:31]
	v_mfma_f32_32x32x16_bf16 v[0:15], v[248:251], v[240:243], v[0:15]
	s_cbranch_scc1 .LBB0_298
; DEV int stage_next(int s) { return (s == 2 * GS_STAGE) ? 0 : s + GS_STAGE; }
; template <int WAIT0>
; DEV void gk_main(f32x16 (&acc)[2][2], const GTile& t, int s0) {
;     ...
;   GK_COMPUTE(stc);
;   vm_wait_bar<0>();
;   stc = stage_next(stc);
;   GK_COMPUTE(stc);
;   vm_wait_bar<0>();
	s_add_i32 s1, s0, 0
	v_add_u32_e32 v87, s1, v86
	ds_read_b128 v[66:69], v87 offset:16384
	v_add_u32_e32 v74, s1, v85
	ds_read_b128 v[70:73], v74
	ds_read_b128 v[74:77], v74 offset:4096
	s_waitcnt lgkmcnt(0)
	v_mfma_f32_32x32x16_bf16 v[48:63], v[66:69], v[70:73], v[48:63]
	v_mfma_f32_32x32x16_bf16 v[32:47], v[66:69], v[74:77], v[32:47]
	ds_read_b128 v[66:69], v87 offset:20480
	v_add_u32_e32 v87, s1, v84
	s_waitcnt lgkmcnt(0)
	v_mfma_f32_32x32x16_bf16 v[16:31], v[66:69], v[70:73], v[16:31]
	v_mfma_f32_32x32x16_bf16 v[0:15], v[66:69], v[74:77], v[0:15]
	ds_read_b128 v[66:69], v87 offset:16384
	v_add_u32_e32 v74, s1, v83
	ds_read_b128 v[70:73], v74
	ds_read_b128 v[74:77], v74 offset:4096
	s_waitcnt lgkmcnt(0)
	v_mfma_f32_32x32x16_bf16 v[48:63], v[66:69], v[70:73], v[48:63]
	v_mfma_f32_32x32x16_bf16 v[32:47], v[66:69], v[74:77], v[32:47]
	ds_read_b128 v[66:69], v87 offset:20480
	v_add_u32_e32 v87, s1, v82
	s_waitcnt lgkmcnt(0)
	v_mfma_f32_32x32x16_bf16 v[16:31], v[66:69], v[70:73], v[16:31]
	v_mfma_f32_32x32x16_bf16 v[0:15], v[66:69], v[74:77], v[0:15]
	ds_read_b128 v[66:69], v87 offset:16384
	v_add_u32_e32 v74, s1, v81
	ds_read_b128 v[70:73], v74
	ds_read_b128 v[74:77], v74 offset:4096
	s_waitcnt lgkmcnt(0)
	v_mfma_f32_32x32x16_bf16 v[48:63], v[66:69], v[70:73], v[48:63]
	v_mfma_f32_32x32x16_bf16 v[32:47], v[66:69], v[74:77], v[32:47]
	ds_read_b128 v[66:69], v87 offset:20480
	v_add_u32_e32 v87, s1, v80
	s_waitcnt lgkmcnt(0)
	v_mfma_f32_32x32x16_bf16 v[16:31], v[66:69], v[70:73], v[16:31]
	v_mfma_f32_32x32x16_bf16 v[0:15], v[66:69], v[74:77], v[0:15]
	ds_read_b128 v[66:69], v87 offset:16384
	v_add_u32_e32 v74, s1, v79
	ds_read_b128 v[70:73], v74
	ds_read_b128 v[74:77], v74 offset:4096
	s_add_i32 s1, s0, 0xc000
	s_cmp_lg_u32 s0, 0x18000
	s_cselect_b32 s0, s1, 0
	s_waitcnt lgkmcnt(0)
	v_mfma_f32_32x32x16_bf16 v[48:63], v[66:69], v[70:73], v[48:63]
	s_add_i32 s0, s0, 0
	v_add_u32_e32 v86, s0, v86
	v_add_u32_e32 v84, s0, v84
	v_add_u32_e32 v82, s0, v82
	v_add_u32_e32 v80, s0, v80
	v_mfma_f32_32x32x16_bf16 v[32:47], v[66:69], v[74:77], v[32:47]
	ds_read_b128 v[66:69], v87 offset:20480
	s_waitcnt vmcnt(0) lgkmcnt(0)
	s_barrier
	s_waitcnt lgkmcnt(0)
	v_mfma_f32_32x32x16_bf16 v[16:31], v[66:69], v[70:73], v[16:31]
	v_mfma_f32_32x32x16_bf16 v[0:15], v[66:69], v[74:77], v[0:15]
	ds_read_b128 v[66:69], v86 offset:16384
	v_add_u32_e32 v74, s0, v85
	ds_read_b128 v[70:73], v74
	ds_read_b128 v[74:77], v74 offset:4096
	s_waitcnt lgkmcnt(0)
	v_mfma_f32_32x32x16_bf16 v[48:63], v[66:69], v[70:73], v[48:63]
	v_mfma_f32_32x32x16_bf16 v[32:47], v[66:69], v[74:77], v[32:47]
	ds_read_b128 v[66:69], v86 offset:20480
	s_waitcnt lgkmcnt(0)
	v_mfma_f32_32x32x16_bf16 v[16:31], v[66:69], v[70:73], v[16:31]
	v_mfma_f32_32x32x16_bf16 v[0:15], v[66:69], v[74:77], v[0:15]
	ds_read_b128 v[66:69], v84 offset:16384
	v_add_u32_e32 v74, s0, v83
	ds_read_b128 v[70:73], v74
	ds_read_b128 v[74:77], v74 offset:4096
	s_waitcnt lgkmcnt(0)
	v_mfma_f32_32x32x16_bf16 v[48:63], v[66:69], v[70:73], v[48:63]
	v_mfma_f32_32x32x16_bf16 v[32:47], v[66:69], v[74:77], v[32:47]
	ds_read_b128 v[66:69], v84 offset:20480
	s_waitcnt lgkmcnt(0)
	v_mfma_f32_32x32x16_bf16 v[16:31], v[66:69], v[70:73], v[16:31]
	v_mfma_f32_32x32x16_bf16 v[0:15], v[66:69], v[74:77], v[0:15]
	ds_read_b128 v[66:69], v82 offset:16384
	v_add_u32_e32 v74, s0, v81
	ds_read_b128 v[70:73], v74
	ds_read_b128 v[74:77], v74 offset:4096
	s_waitcnt lgkmcnt(0)
	v_mfma_f32_32x32x16_bf16 v[48:63], v[66:69], v[70:73], v[48:63]
	v_mfma_f32_32x32x16_bf16 v[32:47], v[66:69], v[74:77], v[32:47]
	ds_read_b128 v[66:69], v82 offset:20480
	s_waitcnt lgkmcnt(0)
	v_mfma_f32_32x32x16_bf16 v[16:31], v[66:69], v[70:73], v[16:31]
	v_mfma_f32_32x32x16_bf16 v[0:15], v[66:69], v[74:77], v[0:15]
	ds_read_b128 v[66:69], v80 offset:16384
	v_add_u32_e32 v74, s0, v79
	ds_read_b128 v[70:73], v74
	ds_read_b128 v[74:77], v74 offset:4096
	s_mov_b64 s[0:1], 0
	s_waitcnt lgkmcnt(0)
	v_mfma_f32_32x32x16_bf16 v[48:63], v[66:69], v[70:73], v[48:63]
	v_mfma_f32_32x32x16_bf16 v[32:47], v[66:69], v[74:77], v[32:47]
	ds_read_b128 v[66:69], v80 offset:20480
	s_waitcnt vmcnt(0) lgkmcnt(0)
	s_barrier
	s_waitcnt lgkmcnt(0)
	v_mfma_f32_32x32x16_bf16 v[16:31], v[66:69], v[70:73], v[16:31]
	v_mfma_f32_32x32x16_bf16 v[0:15], v[66:69], v[74:77], v[0:15]

; DEV int stage_next(int s) { return (s == 2 * GS_STAGE) ? 0 : s + GS_STAGE; }
; template <int WAIT0>
; DEV void gk_main(f32x16 (&acc)[2][2], const GTile& t, int s0) {
;     ...
;   vm_wait_bar<WAIT0>();
;   int stc = s0, std_ = stage_next(stage_next(s0));
; #pragma nounroll
;   for (int kt = 0; kt < nk - 2; ++kt) {
;     GK_DMA(std_, kt + 2);
;     GK_COMPUTE(stc);
;     vm_wait_bar<6>();
;     stc = stage_next(stc); std_ = stage_next(std_);
;   }
.LBB0_302:
	s_add_i32 s16, s1, s3
	v_lshl_add_u64 v[88:89], v[76:77], 0, s[10:11]
	s_mov_b32 m0, s16
	s_nop 0
	global_load_lds_dwordx4 v[88:89], off
	v_lshl_add_u64 v[88:89], v[74:75], 0, s[10:11]
	s_add_i32 m0, s16, 0x2000
	s_nop 0
	global_load_lds_dwordx4 v[88:89], off
	s_add_i32 m0, s16, 0x4000
	v_lshl_add_u64 v[88:89], v[72:73], 0, s[10:11]
	global_load_lds_dwordx4 v[88:89], off
	v_lshl_add_u64 v[88:89], v[70:71], 0, s[10:11]
	s_add_i32 m0, s16, 0x6000
	s_nop 0
	global_load_lds_dwordx4 v[88:89], off
	v_lshl_add_u64 v[88:89], v[68:69], 0, s[10:11]
	s_add_i32 m0, s16, 0x8000
	s_nop 0
	global_load_lds_dwordx4 v[88:89], off
	v_lshl_add_u64 v[88:89], v[66:67], 0, s[10:11]
	s_add_i32 m0, s16, 0xa000
	s_add_i32 s16, s0, 0
	global_load_lds_dwordx4 v[88:89], off
	v_add_u32_e32 v87, s16, v85
	ds_read_b128 v[88:91], v87
	ds_read_b128 v[92:95], v87 offset:4096
	v_add_u32_e32 v87, s16, v86
	ds_read_b128 v[96:99], v87 offset:16384
	ds_read_b128 v[100:103], v87 offset:20480
	s_waitcnt lgkmcnt(0)
	v_add_u32_e32 v87, s16, v83
	ds_read_b128 v[236:239], v87
	ds_read_b128 v[240:243], v87 offset:4096
	v_add_u32_e32 v87, s16, v84
	ds_read_b128 v[244:247], v87 offset:16384
	ds_read_b128 v[248:251], v87 offset:20480
	v_mfma_f32_32x32x16_bf16 v[48:63], v[96:99], v[88:91], v[48:63]
	v_mfma_f32_32x32x16_bf16 v[32:47], v[96:99], v[92:95], v[32:47]
	v_mfma_f32_32x32x16_bf16 v[16:31], v[100:103], v[88:91], v[16:31]
	v_mfma_f32_32x32x16_bf16 v[0:15], v[100:103], v[92:95], v[0:15]
	v_add_u32_e32 v87, s16, v81
	s_waitcnt lgkmcnt(0)
	ds_read_b128 v[88:91], v87
	ds_read_b128 v[92:95], v87 offset:4096
	v_add_u32_e32 v87, s16, v82
	ds_read_b128 v[96:99], v87 offset:16384
	ds_read_b128 v[100:103], v87 offset:20480
	v_mfma_f32_32x32x16_bf16 v[48:63], v[244:247], v[236:239], v[48:63]
	v_mfma_f32_32x32x16_bf16 v[32:47], v[244:247], v[240:243], v[32:47]
	v_mfma_f32_32x32x16_bf16 v[16:31], v[248:251], v[236:239], v[16:31]
	v_mfma_f32_32x32x16_bf16 v[0:15], v[248:251], v[240:243], v[0:15]
	v_add_u32_e32 v87, s16, v79
	s_waitcnt lgkmcnt(0)
	ds_read_b128 v[236:239], v87
	ds_read_b128 v[240:243], v87 offset:4096
	v_add_u32_e32 v87, s16, v80
	ds_read_b128 v[244:247], v87 offset:16384
	ds_read_b128 v[248:251], v87 offset:20480
	v_mfma_f32_32x32x16_bf16 v[48:63], v[96:99], v[88:91], v[48:63]
	v_mfma_f32_32x32x16_bf16 v[32:47], v[96:99], v[92:95], v[32:47]
	v_mfma_f32_32x32x16_bf16 v[16:31], v[100:103], v[88:91], v[16:31]
	v_mfma_f32_32x32x16_bf16 v[0:15], v[100:103], v[92:95], v[0:15]
	s_add_i32 s16, s0, 0xc000
	s_cmp_lg_u32 s0, 0x18000
	s_cselect_b32 s0, s16, 0
	s_add_i32 s16, s3, 0xc000
	s_waitcnt lgkmcnt(0)
	v_mfma_f32_32x32x16_bf16 v[48:63], v[244:247], v[236:239], v[48:63]
	s_cmp_lg_u32 s3, 0x18000
	s_waitcnt vmcnt(6) lgkmcnt(0)
	s_barrier
	s_cselect_b32 s3, s16, 0
	s_add_u32 s10, s10, 0x80
	s_addc_u32 s11, s11, 0
	v_mfma_f32_32x32x16_bf16 v[32:47], v[244:247], v[240:243], v[32:47]
	s_cmpk_lg_i32 s10, 0x700
	v_mfma_f32_32x32x16_bf16 v[16:31], v[248:251], v[236:239], v[16:31]
	v_mfma_f32_32x32x16_bf16 v[0:15], v[248:251], v[240:243], v[0:15]
	s_cbranch_scc1 .LBB0_302
; DEV int stage_next(int s) { return (s == 2 * GS_STAGE) ? 0 : s + GS_STAGE; }
; template <int WAIT0>
; DEV void gk_main(f32x16 (&acc)[2][2], const GTile& t, int s0) {
;     ...
;   GK_COMPUTE(stc);
;   vm_wait_bar<0>();
;   stc = stage_next(stc);
;   GK_COMPUTE(stc);
;   vm_wait_bar<0>();
	s_add_i32 s1, s0, 0
	v_add_u32_e32 v87, s1, v86
	ds_read_b128 v[66:69], v87 offset:16384
	v_add_u32_e32 v74, s1, v85
	ds_read_b128 v[70:73], v74
	ds_read_b128 v[74:77], v74 offset:4096
	s_waitcnt lgkmcnt(0)
	v_mfma_f32_32x32x16_bf16 v[48:63], v[66:69], v[70:73], v[48:63]
	v_mfma_f32_32x32x16_bf16 v[32:47], v[66:69], v[74:77], v[32:47]
	ds_read_b128 v[66:69], v87 offset:20480
	v_add_u32_e32 v87, s1, v84
	s_waitcnt lgkmcnt(0)
	v_mfma_f32_32x32x16_bf16 v[16:31], v[66:69], v[70:73], v[16:31]
	v_mfma_f32_32x32x16_bf16 v[0:15], v[66:69], v[74:77], v[0:15]
	ds_read_b128 v[66:69], v87 offset:16384
	v_add_u32_e32 v74, s1, v83
	ds_read_b128 v[70:73], v74
	ds_read_b128 v[74:77], v74 offset:4096
	s_waitcnt lgkmcnt(0)
	v_mfma_f32_32x32x16_bf16 v[48:63], v[66:69], v[70:73], v[48:63]
	v_mfma_f32_32x32x16_bf16 v[32:47], v[66:69], v[74:77], v[32:47]
	ds_read_b128 v[66:69], v87 offset:20480
	v_add_u32_e32 v87, s1, v82
	s_waitcnt lgkmcnt(0)
	v_mfma_f32_32x32x16_bf16 v[16:31], v[66:69], v[70:73], v[16:31]
	v_mfma_f32_32x32x16_bf16 v[0:15], v[66:69], v[74:77], v[0:15]
	ds_read_b128 v[66:69], v87 offset:16384
	v_add_u32_e32 v74, s1, v81
	ds_read_b128 v[70:73], v74
	ds_read_b128 v[74:77], v74 offset:4096
	s_waitcnt lgkmcnt(0)
	v_mfma_f32_32x32x16_bf16 v[48:63], v[66:69], v[70:73], v[48:63]
	v_mfma_f32_32x32x16_bf16 v[32:47], v[66:69], v[74:77], v[32:47]
	ds_read_b128 v[66:69], v87 offset:20480
	v_add_u32_e32 v87, s1, v80
	s_waitcnt lgkmcnt(0)
	v_mfma_f32_32x32x16_bf16 v[16:31], v[66:69], v[70:73], v[16:31]
	v_mfma_f32_32x32x16_bf16 v[0:15], v[66:69], v[74:77], v[0:15]
	ds_read_b128 v[66:69], v87 offset:16384
	v_add_u32_e32 v74, s1, v79
	ds_read_b128 v[70:73], v74
	ds_read_b128 v[74:77], v74 offset:4096
	s_add_i32 s1, s0, 0xc000
	s_cmp_lg_u32 s0, 0x18000
	s_cselect_b32 s0, s1, 0
	s_waitcnt lgkmcnt(0)
	v_mfma_f32_32x32x16_bf16 v[48:63], v[66:69], v[70:73], v[48:63]
	s_add_i32 s0, s0, 0
	v_add_u32_e32 v86, s0, v86
	v_add_u32_e32 v84, s0, v84
	v_add_u32_e32 v82, s0, v82
	v_add_u32_e32 v80, s0, v80
	v_mfma_f32_32x32x16_bf16 v[32:47], v[66:69], v[74:77], v[32:47]
	ds_read_b128 v[66:69], v87 offset:20480
	s_waitcnt vmcnt(0) lgkmcnt(0)
	s_barrier
	s_waitcnt lgkmcnt(0)
	v_mfma_f32_32x32x16_bf16 v[16:31], v[66:69], v[70:73], v[16:31]
	v_mfma_f32_32x32x16_bf16 v[0:15], v[66:69], v[74:77], v[0:15]
	ds_read_b128 v[66:69], v86 offset:16384
	v_add_u32_e32 v74, s0, v85
	ds_read_b128 v[70:73], v74
	ds_read_b128 v[74:77], v74 offset:4096
	s_waitcnt lgkmcnt(0)
	v_mfma_f32_32x32x16_bf16 v[48:63], v[66:69], v[70:73], v[48:63]
	v_mfma_f32_32x32x16_bf16 v[32:47], v[66:69], v[74:77], v[32:47]
	ds_read_b128 v[66:69], v86 offset:20480
	s_waitcnt lgkmcnt(0)
	v_mfma_f32_32x32x16_bf16 v[16:31], v[66:69], v[70:73], v[16:31]
	v_mfma_f32_32x32x16_bf16 v[0:15], v[66:69], v[74:77], v[0:15]
	ds_read_b128 v[66:69], v84 offset:16384
	v_add_u32_e32 v74, s0, v83
	ds_read_b128 v[70:73], v74
	ds_read_b128 v[74:77], v74 offset:4096
	s_waitcnt lgkmcnt(0)
	v_mfma_f32_32x32x16_bf16 v[48:63], v[66:69], v[70:73], v[48:63]
	v_mfma_f32_32x32x16_bf16 v[32:47], v[66:69], v[74:77], v[32:47]
	ds_read_b128 v[66:69], v84 offset:20480
	s_waitcnt lgkmcnt(0)
	v_mfma_f32_32x32x16_bf16 v[16:31], v[66:69], v[70:73], v[16:31]
	v_mfma_f32_32x32x16_bf16 v[0:15], v[66:69], v[74:77], v[0:15]
	ds_read_b128 v[66:69], v82 offset:16384
	v_add_u32_e32 v74, s0, v81
	ds_read_b128 v[70:73], v74
	ds_read_b128 v[74:77], v74 offset:4096
	s_waitcnt lgkmcnt(0)
	v_mfma_f32_32x32x16_bf16 v[48:63], v[66:69], v[70:73], v[48:63]
	v_mfma_f32_32x32x16_bf16 v[32:47], v[66:69], v[74:77], v[32:47]
	ds_read_b128 v[66:69], v82 offset:20480
	s_waitcnt lgkmcnt(0)
	v_mfma_f32_32x32x16_bf16 v[16:31], v[66:69], v[70:73], v[16:31]
	v_mfma_f32_32x32x16_bf16 v[0:15], v[66:69], v[74:77], v[0:15]
	ds_read_b128 v[66:69], v80 offset:16384
	v_add_u32_e32 v74, s0, v79
	ds_read_b128 v[70:73], v74
	ds_read_b128 v[74:77], v74 offset:4096
	s_waitcnt lgkmcnt(0)
	v_mfma_f32_32x32x16_bf16 v[48:63], v[66:69], v[70:73], v[48:63]
	v_mfma_f32_32x32x16_bf16 v[32:47], v[66:69], v[74:77], v[32:47]
	ds_read_b128 v[66:69], v80 offset:20480
	s_waitcnt vmcnt(0) lgkmcnt(0)
	s_barrier
	s_waitcnt lgkmcnt(0)
	v_mfma_f32_32x32x16_bf16 v[16:31], v[66:69], v[70:73], v[16:31]
	v_mfma_f32_32x32x16_bf16 v[0:15], v[66:69], v[74:77], v[0:15]

; DEV int stage_next(int s) { return (s == 2 * GS_STAGE) ? 0 : s + GS_STAGE; }
; template <int WAIT0>
; DEV void gk_main(f32x16 (&acc)[2][2], const GTile& t, int s0) {
;     ...
;   vm_wait_bar<WAIT0>();
;   int stc = s0, std_ = stage_next(stage_next(s0));
; #pragma nounroll
;   for (int kt = 0; kt < nk - 2; ++kt) {
;     GK_DMA(std_, kt + 2);
;     GK_COMPUTE(stc);
;     vm_wait_bar<6>();
;     stc = stage_next(stc); std_ = stage_next(std_);
;   }
.LBB0_308:
	s_add_i32 s3, s0, s1
	v_lshl_add_u64 v[88:89], v[76:77], 0, s[10:11]
	s_mov_b32 m0, s3
	s_nop 0
	global_load_lds_dwordx4 v[88:89], off
	v_lshl_add_u64 v[88:89], v[74:75], 0, s[10:11]
	s_add_i32 m0, s3, 0x2000
	s_nop 0
	global_load_lds_dwordx4 v[88:89], off
	s_add_i32 m0, s3, 0x4000
	v_lshl_add_u64 v[88:89], v[72:73], 0, s[10:11]
	global_load_lds_dwordx4 v[88:89], off
	v_lshl_add_u64 v[88:89], v[70:71], 0, s[10:11]
	s_add_i32 m0, s3, 0x6000
	s_nop 0
	global_load_lds_dwordx4 v[88:89], off
	v_lshl_add_u64 v[88:89], v[68:69], 0, s[10:11]
	s_add_i32 m0, s3, 0x8000
	s_nop 0
	global_load_lds_dwordx4 v[88:89], off
	v_lshl_add_u64 v[88:89], v[66:67], 0, s[10:11]
	s_add_i32 m0, s3, 0xa000
	s_add_i32 s3, s14, 0
	global_load_lds_dwordx4 v[88:89], off
	v_add_u32_e32 v87, s3, v85
	ds_read_b128 v[88:91], v87
	ds_read_b128 v[92:95], v87 offset:4096
	v_add_u32_e32 v87, s3, v86
	ds_read_b128 v[96:99], v87 offset:16384
	ds_read_b128 v[100:103], v87 offset:20480
	s_waitcnt lgkmcnt(0)
	v_add_u32_e32 v87, s3, v83
	ds_read_b128 v[236:239], v87
	ds_read_b128 v[240:243], v87 offset:4096
	v_add_u32_e32 v87, s3, v84
	ds_read_b128 v[244:247], v87 offset:16384
	ds_read_b128 v[248:251], v87 offset:20480
	v_mfma_f32_32x32x16_bf16 v[48:63], v[96:99], v[88:91], v[48:63]
	v_mfma_f32_32x32x16_bf16 v[32:47], v[96:99], v[92:95], v[32:47]
	v_mfma_f32_32x32x16_bf16 v[16:31], v[100:103], v[88:91], v[16:31]
	v_mfma_f32_32x32x16_bf16 v[0:15], v[100:103], v[92:95], v[0:15]
	v_add_u32_e32 v87, s3, v81
	s_waitcnt lgkmcnt(0)
	ds_read_b128 v[88:91], v87
	ds_read_b128 v[92:95], v87 offset:4096
	v_add_u32_e32 v87, s3, v82
	ds_read_b128 v[96:99], v87 offset:16384
	ds_read_b128 v[100:103], v87 offset:20480
	v_mfma_f32_32x32x16_bf16 v[48:63], v[244:247], v[236:239], v[48:63]
	v_mfma_f32_32x32x16_bf16 v[32:47], v[244:247], v[240:243], v[32:47]
	v_mfma_f32_32x32x16_bf16 v[16:31], v[248:251], v[236:239], v[16:31]
	v_mfma_f32_32x32x16_bf16 v[0:15], v[248:251], v[240:243], v[0:15]
	v_add_u32_e32 v87, s3, v79
	s_waitcnt lgkmcnt(0)
	ds_read_b128 v[236:239], v87
	ds_read_b128 v[240:243], v87 offset:4096
	v_add_u32_e32 v87, s3, v80
	ds_read_b128 v[244:247], v87 offset:16384
	ds_read_b128 v[248:251], v87 offset:20480
	v_mfma_f32_32x32x16_bf16 v[48:63], v[96:99], v[88:91], v[48:63]
	v_mfma_f32_32x32x16_bf16 v[32:47], v[96:99], v[92:95], v[32:47]
	v_mfma_f32_32x32x16_bf16 v[16:31], v[100:103], v[88:91], v[16:31]
	v_mfma_f32_32x32x16_bf16 v[0:15], v[100:103], v[92:95], v[0:15]
	s_add_i32 s3, s14, 0xc000
	s_cmp_lg_u32 s14, 0x18000
	s_cselect_b32 s14, s3, 0
	s_add_i32 s3, s1, 0xc000
	s_waitcnt lgkmcnt(0)
	v_mfma_f32_32x32x16_bf16 v[48:63], v[244:247], v[236:239], v[48:63]
	s_cmp_lg_u32 s1, 0x18000
	s_waitcnt vmcnt(6) lgkmcnt(0)
	s_barrier
	s_cselect_b32 s1, s3, 0
	s_add_u32 s10, s10, 0x80
	s_addc_u32 s11, s11, 0
	v_mfma_f32_32x32x16_bf16 v[32:47], v[244:247], v[240:243], v[32:47]
	s_cmpk_lg_i32 s10, 0x700
	v_mfma_f32_32x32x16_bf16 v[16:31], v[248:251], v[236:239], v[16:31]
	v_mfma_f32_32x32x16_bf16 v[0:15], v[248:251], v[240:243], v[0:15]
	s_cbranch_scc1 .LBB0_308
; DEV int stage_next(int s) { return (s == 2 * GS_STAGE) ? 0 : s + GS_STAGE; }
; template <int WAIT0>
; DEV void gk_main(f32x16 (&acc)[2][2], const GTile& t, int s0) {
;     ...
;   GK_COMPUTE(stc);
;   vm_wait_bar<0>();
;   stc = stage_next(stc);
;   GK_COMPUTE(stc);
;   vm_wait_bar<0>();
	s_add_i32 s0, s14, 0
	v_add_u32_e32 v87, s0, v86
	ds_read_b128 v[66:69], v87 offset:16384
	v_add_u32_e32 v74, s0, v85
	ds_read_b128 v[70:73], v74
	ds_read_b128 v[74:77], v74 offset:4096
	s_waitcnt lgkmcnt(0)
	v_mfma_f32_32x32x16_bf16 v[48:63], v[66:69], v[70:73], v[48:63]
	v_mfma_f32_32x32x16_bf16 v[32:47], v[66:69], v[74:77], v[32:47]
	ds_read_b128 v[66:69], v87 offset:20480
	v_add_u32_e32 v87, s0, v84
	s_waitcnt lgkmcnt(0)
	v_mfma_f32_32x32x16_bf16 v[16:31], v[66:69], v[70:73], v[16:31]
	v_mfma_f32_32x32x16_bf16 v[0:15], v[66:69], v[74:77], v[0:15]
	ds_read_b128 v[66:69], v87 offset:16384
	v_add_u32_e32 v74, s0, v83
	ds_read_b128 v[70:73], v74
	ds_read_b128 v[74:77], v74 offset:4096
	s_waitcnt lgkmcnt(0)
	v_mfma_f32_32x32x16_bf16 v[48:63], v[66:69], v[70:73], v[48:63]
	v_mfma_f32_32x32x16_bf16 v[32:47], v[66:69], v[74:77], v[32:47]
	ds_read_b128 v[66:69], v87 offset:20480
	v_add_u32_e32 v87, s0, v82
	s_waitcnt lgkmcnt(0)
	v_mfma_f32_32x32x16_bf16 v[16:31], v[66:69], v[70:73], v[16:31]
	v_mfma_f32_32x32x16_bf16 v[0:15], v[66:69], v[74:77], v[0:15]
	ds_read_b128 v[66:69], v87 offset:16384
	v_add_u32_e32 v74, s0, v81
	ds_read_b128 v[70:73], v74
	ds_read_b128 v[74:77], v74 offset:4096
	s_waitcnt lgkmcnt(0)
	v_mfma_f32_32x32x16_bf16 v[48:63], v[66:69], v[70:73], v[48:63]
	v_mfma_f32_32x32x16_bf16 v[32:47], v[66:69], v[74:77], v[32:47]
	ds_read_b128 v[66:69], v87 offset:20480
	v_add_u32_e32 v87, s0, v80
	s_waitcnt lgkmcnt(0)
	v_mfma_f32_32x32x16_bf16 v[16:31], v[66:69], v[70:73], v[16:31]
	v_mfma_f32_32x32x16_bf16 v[0:15], v[66:69], v[74:77], v[0:15]
	ds_read_b128 v[66:69], v87 offset:16384
	v_add_u32_e32 v74, s0, v79
	ds_read_b128 v[70:73], v74
	ds_read_b128 v[74:77], v74 offset:4096
	s_add_i32 s0, s14, 0xc000
	s_cmp_lg_u32 s14, 0x18000
	s_cselect_b32 s0, s0, 0
	s_waitcnt lgkmcnt(0)
	v_mfma_f32_32x32x16_bf16 v[48:63], v[66:69], v[70:73], v[48:63]
	s_add_i32 s0, s0, 0
	v_add_u32_e32 v86, s0, v86
	v_add_u32_e32 v84, s0, v84
	v_add_u32_e32 v82, s0, v82
	v_add_u32_e32 v80, s0, v80
	v_mfma_f32_32x32x16_bf16 v[32:47], v[66:69], v[74:77], v[32:47]
	ds_read_b128 v[66:69], v87 offset:20480
	s_waitcnt vmcnt(0) lgkmcnt(0)
	s_barrier
	s_waitcnt lgkmcnt(0)
	v_mfma_f32_32x32x16_bf16 v[16:31], v[66:69], v[70:73], v[16:31]
	v_mfma_f32_32x32x16_bf16 v[0:15], v[66:69], v[74:77], v[0:15]
	ds_read_b128 v[66:69], v86 offset:16384
	v_add_u32_e32 v74, s0, v85
	ds_read_b128 v[70:73], v74
	ds_read_b128 v[74:77], v74 offset:4096
	s_waitcnt lgkmcnt(0)
	v_mfma_f32_32x32x16_bf16 v[48:63], v[66:69], v[70:73], v[48:63]
	v_mfma_f32_32x32x16_bf16 v[32:47], v[66:69], v[74:77], v[32:47]
	ds_read_b128 v[66:69], v86 offset:20480
	s_waitcnt lgkmcnt(0)
	v_mfma_f32_32x32x16_bf16 v[16:31], v[66:69], v[70:73], v[16:31]
	v_mfma_f32_32x32x16_bf16 v[0:15], v[66:69], v[74:77], v[0:15]
	ds_read_b128 v[66:69], v84 offset:16384
	v_add_u32_e32 v74, s0, v83
	ds_read_b128 v[70:73], v74
	ds_read_b128 v[74:77], v74 offset:4096
	s_waitcnt lgkmcnt(0)
	v_mfma_f32_32x32x16_bf16 v[48:63], v[66:69], v[70:73], v[48:63]
	v_mfma_f32_32x32x16_bf16 v[32:47], v[66:69], v[74:77], v[32:47]
	ds_read_b128 v[66:69], v84 offset:20480
	s_waitcnt lgkmcnt(0)
	v_mfma_f32_32x32x16_bf16 v[16:31], v[66:69], v[70:73], v[16:31]
	v_mfma_f32_32x32x16_bf16 v[0:15], v[66:69], v[74:77], v[0:15]
	ds_read_b128 v[66:69], v82 offset:16384
	v_add_u32_e32 v74, s0, v81
	ds_read_b128 v[70:73], v74
	ds_read_b128 v[74:77], v74 offset:4096
	s_waitcnt lgkmcnt(0)
	v_mfma_f32_32x32x16_bf16 v[48:63], v[66:69], v[70:73], v[48:63]
	v_mfma_f32_32x32x16_bf16 v[32:47], v[66:69], v[74:77], v[32:47]
	ds_read_b128 v[66:69], v82 offset:20480
	s_waitcnt lgkmcnt(0)
	v_mfma_f32_32x32x16_bf16 v[16:31], v[66:69], v[70:73], v[16:31]
	v_mfma_f32_32x32x16_bf16 v[0:15], v[66:69], v[74:77], v[0:15]
	ds_read_b128 v[66:69], v80 offset:16384
	v_add_u32_e32 v74, s0, v79
	ds_read_b128 v[70:73], v74
	ds_read_b128 v[74:77], v74 offset:4096
	s_waitcnt lgkmcnt(0)
	v_mfma_f32_32x32x16_bf16 v[48:63], v[66:69], v[70:73], v[48:63]
	v_mfma_f32_32x32x16_bf16 v[32:47], v[66:69], v[74:77], v[32:47]
	ds_read_b128 v[66:69], v80 offset:20480
	s_waitcnt vmcnt(0) lgkmcnt(0)
	s_barrier
	s_waitcnt lgkmcnt(0)
	v_mfma_f32_32x32x16_bf16 v[16:31], v[66:69], v[70:73], v[16:31]
	v_mfma_f32_32x32x16_bf16 v[0:15], v[66:69], v[74:77], v[0:15]
	s_add_i32 s0, s15, 1
	s_mov_b32 s14, s2
	s_cmp_eq_u32 s15, 3
	s_cbranch_scc1 .LBB0_294

; DEV int stage_next(int s) { return (s == 2 * GS_STAGE) ? 0 : s + GS_STAGE; }
; template <int WAIT0>
; DEV void gk_main(f32x16 (&acc)[2][2], const GTile& t, int s0) {
;     ...
;   vm_wait_bar<WAIT0>();
;   int stc = s0, std_ = stage_next(stage_next(s0));
; #pragma nounroll
;   for (int kt = 0; kt < nk - 2; ++kt) {
;     GK_DMA(std_, kt + 2);
;     GK_COMPUTE(stc);
;     vm_wait_bar<6>();
;     stc = stage_next(stc); std_ = stage_next(std_);
;   }
.LBB0_403:
	s_add_i32 s10, s3, s8
	v_lshl_add_u64 v[84:85], v[74:75], 0, v[120:121]
	s_mov_b32 m0, s10
	v_lshl_add_u64 v[74:75], v[74:75], 0, s[96:97]
	global_load_lds_dwordx4 v[84:85], off
	v_lshl_add_u64 v[84:85], v[72:73], 0, v[120:121]
	s_add_i32 m0, s10, 0x2000
	v_lshl_add_u64 v[72:73], v[72:73], 0, s[96:97]
	global_load_lds_dwordx4 v[84:85], off
	s_add_i32 m0, s10, 0x4000
	v_lshl_add_u64 v[84:85], v[70:71], 0, v[120:121]
	global_load_lds_dwordx4 v[84:85], off
	v_lshl_add_u64 v[84:85], v[68:69], 0, v[120:121]
	s_add_i32 m0, s10, 0x6000
	v_lshl_add_u64 v[68:69], v[68:69], 0, s[96:97]
	global_load_lds_dwordx4 v[84:85], off
	v_lshl_add_u64 v[84:85], v[66:67], 0, v[120:121]
	s_add_i32 m0, s10, 0x8000
	v_lshl_add_u64 v[66:67], v[66:67], 0, s[96:97]
	global_load_lds_dwordx4 v[84:85], off
	v_lshl_add_u64 v[84:85], v[64:65], 0, v[120:121]
	s_add_i32 m0, s10, 0xa000
	s_add_i32 s10, s2, 0
	global_load_lds_dwordx4 v[84:85], off
	v_add_u32_e32 v252, s10, v82
	v_add_u32_e32 v253, s10, v83
	ds_read_b128 v[84:87], v252
	ds_read_b128 v[88:91], v252 offset:4096
	ds_read_b128 v[92:95], v253 offset:16384
	ds_read_b128 v[96:99], v253 offset:20480
	s_waitcnt lgkmcnt(0)
	v_lshl_add_u64 v[64:65], v[64:65], 0, s[96:97]
	v_lshl_add_u64 v[70:71], v[70:71], 0, s[96:97]
	v_add_u32_e32 v252, s10, v80
	v_add_u32_e32 v253, s10, v81
	ds_read_b128 v[236:239], v252
	ds_read_b128 v[240:243], v252 offset:4096
	ds_read_b128 v[244:247], v253 offset:16384
	ds_read_b128 v[248:251], v253 offset:20480
	v_mfma_f32_32x32x16_bf16 v[48:63], v[92:95], v[84:87], v[48:63]
	v_mfma_f32_32x32x16_bf16 v[32:47], v[92:95], v[88:91], v[32:47]
	v_mfma_f32_32x32x16_bf16 v[16:31], v[96:99], v[84:87], v[16:31]
	v_mfma_f32_32x32x16_bf16 v[0:15], v[96:99], v[88:91], v[0:15]
	s_waitcnt lgkmcnt(0)
	v_add_u32_e32 v252, s10, v78
	v_add_u32_e32 v253, s10, v79
	ds_read_b128 v[84:87], v252
	ds_read_b128 v[88:91], v252 offset:4096
	ds_read_b128 v[92:95], v253 offset:16384
	ds_read_b128 v[96:99], v253 offset:20480
	v_mfma_f32_32x32x16_bf16 v[48:63], v[244:247], v[236:239], v[48:63]
	v_mfma_f32_32x32x16_bf16 v[32:47], v[244:247], v[240:243], v[32:47]
	v_mfma_f32_32x32x16_bf16 v[16:31], v[248:251], v[236:239], v[16:31]
	v_mfma_f32_32x32x16_bf16 v[0:15], v[248:251], v[240:243], v[0:15]
	s_waitcnt lgkmcnt(0)
	v_add_u32_e32 v252, s10, v76
	v_add_u32_e32 v253, s10, v77
	ds_read_b128 v[236:239], v252
	ds_read_b128 v[240:243], v252 offset:4096
	ds_read_b128 v[244:247], v253 offset:16384
	ds_read_b128 v[248:251], v253 offset:20480
	v_mfma_f32_32x32x16_bf16 v[48:63], v[92:95], v[84:87], v[48:63]
	v_mfma_f32_32x32x16_bf16 v[32:47], v[92:95], v[88:91], v[32:47]
	v_mfma_f32_32x32x16_bf16 v[16:31], v[96:99], v[84:87], v[16:31]
	v_mfma_f32_32x32x16_bf16 v[0:15], v[96:99], v[88:91], v[0:15]
	s_add_i32 s10, s2, 0xc000
	s_cmp_lg_u32 s2, 0x18000
	s_cselect_b32 s2, s10, 0
	s_waitcnt lgkmcnt(0)
	v_mfma_f32_32x32x16_bf16 v[48:63], v[244:247], v[236:239], v[48:63]
	s_add_i32 s10, s8, 0xc000
	s_waitcnt vmcnt(6) lgkmcnt(0)
	s_barrier
	s_cmp_lg_u32 s8, 0x18000
	s_cselect_b32 s8, s10, 0
	s_add_i32 s9, s9, -1
	v_mfma_f32_32x32x16_bf16 v[32:47], v[244:247], v[240:243], v[32:47]
	s_cmp_lg_u32 s9, 0
	v_mfma_f32_32x32x16_bf16 v[16:31], v[248:251], v[236:239], v[16:31]
	v_mfma_f32_32x32x16_bf16 v[0:15], v[248:251], v[240:243], v[0:15]
	s_cbranch_scc1 .LBB0_403
; DEV int stage_next(int s) { return (s == 2 * GS_STAGE) ? 0 : s + GS_STAGE; }
; template <int WAIT0>
; DEV void gk_main(f32x16 (&acc)[2][2], const GTile& t, int s0) {
;     ...
;   GK_COMPUTE(stc);
;   vm_wait_bar<0>();
;   stc = stage_next(stc);
;   GK_COMPUTE(stc);
;   vm_wait_bar<0>();
	s_add_i32 s3, s2, 0
	v_add_u32_e32 v84, s3, v83
	ds_read_b128 v[64:67], v84 offset:16384
	v_add_u32_e32 v72, s3, v82
	ds_read_b128 v[68:71], v72
	ds_read_b128 v[72:75], v72 offset:4096
	s_mov_b64 s[8:9], 0
	s_waitcnt lgkmcnt(0)
	v_mfma_f32_32x32x16_bf16 v[48:63], v[64:67], v[68:71], v[48:63]
	v_mfma_f32_32x32x16_bf16 v[32:47], v[64:67], v[72:75], v[32:47]
	ds_read_b128 v[64:67], v84 offset:20480
	v_add_u32_e32 v84, s3, v81
	s_waitcnt lgkmcnt(0)
	v_mfma_f32_32x32x16_bf16 v[16:31], v[64:67], v[68:71], v[16:31]
	v_mfma_f32_32x32x16_bf16 v[0:15], v[64:67], v[72:75], v[0:15]
	ds_read_b128 v[64:67], v84 offset:16384
	v_add_u32_e32 v72, s3, v80
	ds_read_b128 v[68:71], v72
	ds_read_b128 v[72:75], v72 offset:4096
	s_waitcnt lgkmcnt(0)
	v_mfma_f32_32x32x16_bf16 v[48:63], v[64:67], v[68:71], v[48:63]
	v_mfma_f32_32x32x16_bf16 v[32:47], v[64:67], v[72:75], v[32:47]
	ds_read_b128 v[64:67], v84 offset:20480
	v_add_u32_e32 v84, s3, v79
	s_waitcnt lgkmcnt(0)
	v_mfma_f32_32x32x16_bf16 v[16:31], v[64:67], v[68:71], v[16:31]
	v_mfma_f32_32x32x16_bf16 v[0:15], v[64:67], v[72:75], v[0:15]
	ds_read_b128 v[64:67], v84 offset:16384
	v_add_u32_e32 v72, s3, v78
	ds_read_b128 v[68:71], v72
	ds_read_b128 v[72:75], v72 offset:4096
	s_waitcnt lgkmcnt(0)
	v_mfma_f32_32x32x16_bf16 v[48:63], v[64:67], v[68:71], v[48:63]
	v_mfma_f32_32x32x16_bf16 v[32:47], v[64:67], v[72:75], v[32:47]
	ds_read_b128 v[64:67], v84 offset:20480
	v_add_u32_e32 v84, s3, v77
	s_waitcnt lgkmcnt(0)
	v_mfma_f32_32x32x16_bf16 v[16:31], v[64:67], v[68:71], v[16:31]
	v_mfma_f32_32x32x16_bf16 v[0:15], v[64:67], v[72:75], v[0:15]
	ds_read_b128 v[64:67], v84 offset:16384
	v_add_u32_e32 v72, s3, v76
	ds_read_b128 v[68:71], v72
	ds_read_b128 v[72:75], v72 offset:4096
	s_add_i32 s3, s2, 0xc000
	s_cmp_lg_u32 s2, 0x18000
	s_cselect_b32 s2, s3, 0
	s_waitcnt lgkmcnt(0)
	v_mfma_f32_32x32x16_bf16 v[48:63], v[64:67], v[68:71], v[48:63]
	s_add_i32 s2, s2, 0
	v_add_u32_e32 v83, s2, v83
	v_add_u32_e32 v81, s2, v81
	v_add_u32_e32 v79, s2, v79
	v_add_u32_e32 v77, s2, v77
	v_mfma_f32_32x32x16_bf16 v[32:47], v[64:67], v[72:75], v[32:47]
	ds_read_b128 v[64:67], v84 offset:20480
	s_waitcnt vmcnt(0) lgkmcnt(0)
	s_barrier
	s_waitcnt lgkmcnt(0)
	v_mfma_f32_32x32x16_bf16 v[16:31], v[64:67], v[68:71], v[16:31]
	v_mfma_f32_32x32x16_bf16 v[0:15], v[64:67], v[72:75], v[0:15]
	ds_read_b128 v[64:67], v83 offset:16384
	v_add_u32_e32 v72, s2, v82
	ds_read_b128 v[68:71], v72
	ds_read_b128 v[72:75], v72 offset:4096
	s_waitcnt lgkmcnt(0)
	v_mfma_f32_32x32x16_bf16 v[48:63], v[64:67], v[68:71], v[48:63]
	v_mfma_f32_32x32x16_bf16 v[32:47], v[64:67], v[72:75], v[32:47]
	ds_read_b128 v[64:67], v83 offset:20480
	s_waitcnt lgkmcnt(0)
	v_mfma_f32_32x32x16_bf16 v[16:31], v[64:67], v[68:71], v[16:31]
	v_mfma_f32_32x32x16_bf16 v[0:15], v[64:67], v[72:75], v[0:15]
	ds_read_b128 v[64:67], v81 offset:16384
	v_add_u32_e32 v72, s2, v80
	ds_read_b128 v[68:71], v72
	ds_read_b128 v[72:75], v72 offset:4096
	s_waitcnt lgkmcnt(0)
	v_mfma_f32_32x32x16_bf16 v[48:63], v[64:67], v[68:71], v[48:63]
	v_mfma_f32_32x32x16_bf16 v[32:47], v[64:67], v[72:75], v[32:47]
	ds_read_b128 v[64:67], v81 offset:20480
	s_waitcnt lgkmcnt(0)
	v_mfma_f32_32x32x16_bf16 v[16:31], v[64:67], v[68:71], v[16:31]
	v_mfma_f32_32x32x16_bf16 v[0:15], v[64:67], v[72:75], v[0:15]
	ds_read_b128 v[64:67], v79 offset:16384
	v_add_u32_e32 v72, s2, v78
	ds_read_b128 v[68:71], v72
	ds_read_b128 v[72:75], v72 offset:4096
	s_waitcnt lgkmcnt(0)
	v_mfma_f32_32x32x16_bf16 v[48:63], v[64:67], v[68:71], v[48:63]
	v_mfma_f32_32x32x16_bf16 v[32:47], v[64:67], v[72:75], v[32:47]
	ds_read_b128 v[64:67], v79 offset:20480
	s_waitcnt lgkmcnt(0)
	v_mfma_f32_32x32x16_bf16 v[16:31], v[64:67], v[68:71], v[16:31]
	v_mfma_f32_32x32x16_bf16 v[0:15], v[64:67], v[72:75], v[0:15]
	ds_read_b128 v[64:67], v77 offset:16384
	v_add_u32_e32 v72, s2, v76
	ds_read_b128 v[68:71], v72
	ds_read_b128 v[72:75], v72 offset:4096
	s_waitcnt lgkmcnt(0)
	v_mfma_f32_32x32x16_bf16 v[48:63], v[64:67], v[68:71], v[48:63]
	v_mfma_f32_32x32x16_bf16 v[32:47], v[64:67], v[72:75], v[32:47]
	ds_read_b128 v[64:67], v77 offset:20480
	s_waitcnt vmcnt(0) lgkmcnt(0)
	s_barrier
	s_waitcnt lgkmcnt(0)
	v_mfma_f32_32x32x16_bf16 v[16:31], v[64:67], v[68:71], v[16:31]
	v_mfma_f32_32x32x16_bf16 v[0:15], v[64:67], v[72:75], v[0:15]

; DEV int stage_next(int s) { return (s == 2 * GS_STAGE) ? 0 : s + GS_STAGE; }
; template <int WAIT0>
; DEV void gk_main(f32x16 (&acc)[2][2], const GTile& t, int s0) {
;     ...
;   vm_wait_bar<WAIT0>();
;   int stc = s0, std_ = stage_next(stage_next(s0));
; #pragma nounroll
;   for (int kt = 0; kt < nk - 2; ++kt) {
;     GK_DMA(std_, kt + 2);
;     GK_COMPUTE(stc);
;     vm_wait_bar<6>();
;     stc = stage_next(stc); std_ = stage_next(std_);
;   }
.LBB0_407:
	s_add_i32 s10, s3, s8
	v_lshl_add_u64 v[84:85], v[74:75], 0, v[120:121]
	s_mov_b32 m0, s10
	v_lshl_add_u64 v[74:75], v[74:75], 0, s[96:97]
	global_load_lds_dwordx4 v[84:85], off
	v_lshl_add_u64 v[84:85], v[72:73], 0, v[120:121]
	s_add_i32 m0, s10, 0x2000
	v_lshl_add_u64 v[72:73], v[72:73], 0, s[96:97]
	global_load_lds_dwordx4 v[84:85], off
	s_add_i32 m0, s10, 0x4000
	v_lshl_add_u64 v[84:85], v[70:71], 0, v[120:121]
	global_load_lds_dwordx4 v[84:85], off
	v_lshl_add_u64 v[84:85], v[68:69], 0, v[120:121]
	s_add_i32 m0, s10, 0x6000
	v_lshl_add_u64 v[68:69], v[68:69], 0, s[96:97]
	global_load_lds_dwordx4 v[84:85], off
	v_lshl_add_u64 v[84:85], v[66:67], 0, v[120:121]
	s_add_i32 m0, s10, 0x8000
	v_lshl_add_u64 v[66:67], v[66:67], 0, s[96:97]
	global_load_lds_dwordx4 v[84:85], off
	v_lshl_add_u64 v[84:85], v[64:65], 0, v[120:121]
	s_add_i32 m0, s10, 0xa000
	s_add_i32 s10, s2, 0
	global_load_lds_dwordx4 v[84:85], off
	v_add_u32_e32 v252, s10, v82
	v_add_u32_e32 v253, s10, v83
	ds_read_b128 v[84:87], v252
	ds_read_b128 v[88:91], v252 offset:4096
	ds_read_b128 v[92:95], v253 offset:16384
	ds_read_b128 v[96:99], v253 offset:20480
	s_waitcnt lgkmcnt(0)
	v_lshl_add_u64 v[64:65], v[64:65], 0, s[96:97]
	v_lshl_add_u64 v[70:71], v[70:71], 0, s[96:97]
	v_add_u32_e32 v252, s10, v80
	v_add_u32_e32 v253, s10, v81
	ds_read_b128 v[236:239], v252
	ds_read_b128 v[240:243], v252 offset:4096
	ds_read_b128 v[244:247], v253 offset:16384
	ds_read_b128 v[248:251], v253 offset:20480
	v_mfma_f32_32x32x16_bf16 v[48:63], v[92:95], v[84:87], v[48:63]
	v_mfma_f32_32x32x16_bf16 v[32:47], v[92:95], v[88:91], v[32:47]
	v_mfma_f32_32x32x16_bf16 v[16:31], v[96:99], v[84:87], v[16:31]
	v_mfma_f32_32x32x16_bf16 v[0:15], v[96:99], v[88:91], v[0:15]
	s_waitcnt lgkmcnt(0)
	v_add_u32_e32 v252, s10, v78
	v_add_u32_e32 v253, s10, v79
	ds_read_b128 v[84:87], v252
	ds_read_b128 v[88:91], v252 offset:4096
	ds_read_b128 v[92:95], v253 offset:16384
	ds_read_b128 v[96:99], v253 offset:20480
	v_mfma_f32_32x32x16_bf16 v[48:63], v[244:247], v[236:239], v[48:63]
	v_mfma_f32_32x32x16_bf16 v[32:47], v[244:247], v[240:243], v[32:47]
	v_mfma_f32_32x32x16_bf16 v[16:31], v[248:251], v[236:239], v[16:31]
	v_mfma_f32_32x32x16_bf16 v[0:15], v[248:251], v[240:243], v[0:15]
	s_waitcnt lgkmcnt(0)
	v_add_u32_e32 v252, s10, v76
	v_add_u32_e32 v253, s10, v77
	ds_read_b128 v[236:239], v252
	ds_read_b128 v[240:243], v252 offset:4096
	ds_read_b128 v[244:247], v253 offset:16384
	ds_read_b128 v[248:251], v253 offset:20480
	v_mfma_f32_32x32x16_bf16 v[48:63], v[92:95], v[84:87], v[48:63]
	v_mfma_f32_32x32x16_bf16 v[32:47], v[92:95], v[88:91], v[32:47]
	v_mfma_f32_32x32x16_bf16 v[16:31], v[96:99], v[84:87], v[16:31]
	v_mfma_f32_32x32x16_bf16 v[0:15], v[96:99], v[88:91], v[0:15]
	s_add_i32 s10, s2, 0xc000
	s_cmp_lg_u32 s2, 0x18000
	s_cselect_b32 s2, s10, 0
	s_waitcnt lgkmcnt(0)
	v_mfma_f32_32x32x16_bf16 v[48:63], v[244:247], v[236:239], v[48:63]
	s_add_i32 s10, s8, 0xc000
	s_waitcnt vmcnt(6) lgkmcnt(0)
	s_barrier
	s_cmp_lg_u32 s8, 0x18000
	s_cselect_b32 s8, s10, 0
	s_add_i32 s9, s9, -1
	v_mfma_f32_32x32x16_bf16 v[32:47], v[244:247], v[240:243], v[32:47]
	s_cmp_lg_u32 s9, 0
	v_mfma_f32_32x32x16_bf16 v[16:31], v[248:251], v[236:239], v[16:31]
	v_mfma_f32_32x32x16_bf16 v[0:15], v[248:251], v[240:243], v[0:15]
	s_cbranch_scc1 .LBB0_407
; DEV int stage_next(int s) { return (s == 2 * GS_STAGE) ? 0 : s + GS_STAGE; }
; template <int WAIT0>
; DEV void gk_main(f32x16 (&acc)[2][2], const GTile& t, int s0) {
;     ...
;   GK_COMPUTE(stc);
;   vm_wait_bar<0>();
;   stc = stage_next(stc);
;   GK_COMPUTE(stc);
;   vm_wait_bar<0>();
	s_add_i32 s3, s2, 0
	v_add_u32_e32 v84, s3, v83
	ds_read_b128 v[64:67], v84 offset:16384
	v_add_u32_e32 v72, s3, v82
	ds_read_b128 v[68:71], v72
	ds_read_b128 v[72:75], v72 offset:4096
	s_waitcnt lgkmcnt(0)
	v_mfma_f32_32x32x16_bf16 v[48:63], v[64:67], v[68:71], v[48:63]
	v_mfma_f32_32x32x16_bf16 v[32:47], v[64:67], v[72:75], v[32:47]
	ds_read_b128 v[64:67], v84 offset:20480
	v_add_u32_e32 v84, s3, v81
	s_waitcnt lgkmcnt(0)
	v_mfma_f32_32x32x16_bf16 v[16:31], v[64:67], v[68:71], v[16:31]
	v_mfma_f32_32x32x16_bf16 v[0:15], v[64:67], v[72:75], v[0:15]
	ds_read_b128 v[64:67], v84 offset:16384
	v_add_u32_e32 v72, s3, v80
	ds_read_b128 v[68:71], v72
	ds_read_b128 v[72:75], v72 offset:4096
	s_waitcnt lgkmcnt(0)
	v_mfma_f32_32x32x16_bf16 v[48:63], v[64:67], v[68:71], v[48:63]
	v_mfma_f32_32x32x16_bf16 v[32:47], v[64:67], v[72:75], v[32:47]
	ds_read_b128 v[64:67], v84 offset:20480
	v_add_u32_e32 v84, s3, v79
	s_waitcnt lgkmcnt(0)
	v_mfma_f32_32x32x16_bf16 v[16:31], v[64:67], v[68:71], v[16:31]
	v_mfma_f32_32x32x16_bf16 v[0:15], v[64:67], v[72:75], v[0:15]
	ds_read_b128 v[64:67], v84 offset:16384
	v_add_u32_e32 v72, s3, v78
	ds_read_b128 v[68:71], v72
	ds_read_b128 v[72:75], v72 offset:4096
	s_waitcnt lgkmcnt(0)
	v_mfma_f32_32x32x16_bf16 v[48:63], v[64:67], v[68:71], v[48:63]
	v_mfma_f32_32x32x16_bf16 v[32:47], v[64:67], v[72:75], v[32:47]
	ds_read_b128 v[64:67], v84 offset:20480
	v_add_u32_e32 v84, s3, v77
	s_waitcnt lgkmcnt(0)
	v_mfma_f32_32x32x16_bf16 v[16:31], v[64:67], v[68:71], v[16:31]
	v_mfma_f32_32x32x16_bf16 v[0:15], v[64:67], v[72:75], v[0:15]
	ds_read_b128 v[64:67], v84 offset:16384
	v_add_u32_e32 v72, s3, v76
	ds_read_b128 v[68:71], v72
	ds_read_b128 v[72:75], v72 offset:4096
	s_add_i32 s3, s2, 0xc000
	s_cmp_lg_u32 s2, 0x18000
	s_cselect_b32 s2, s3, 0
	s_waitcnt lgkmcnt(0)
	v_mfma_f32_32x32x16_bf16 v[48:63], v[64:67], v[68:71], v[48:63]
	s_add_i32 s2, s2, 0
	v_add_u32_e32 v83, s2, v83
	v_add_u32_e32 v81, s2, v81
	v_add_u32_e32 v79, s2, v79
	v_add_u32_e32 v77, s2, v77
	v_mfma_f32_32x32x16_bf16 v[32:47], v[64:67], v[72:75], v[32:47]
	ds_read_b128 v[64:67], v84 offset:20480
	s_waitcnt vmcnt(0) lgkmcnt(0)
	s_barrier
	s_waitcnt lgkmcnt(0)
	v_mfma_f32_32x32x16_bf16 v[16:31], v[64:67], v[68:71], v[16:31]
	v_mfma_f32_32x32x16_bf16 v[0:15], v[64:67], v[72:75], v[0:15]
	ds_read_b128 v[64:67], v83 offset:16384
	v_add_u32_e32 v72, s2, v82
	ds_read_b128 v[68:71], v72
	ds_read_b128 v[72:75], v72 offset:4096
	s_waitcnt lgkmcnt(0)
	v_mfma_f32_32x32x16_bf16 v[48:63], v[64:67], v[68:71], v[48:63]
	v_mfma_f32_32x32x16_bf16 v[32:47], v[64:67], v[72:75], v[32:47]
	ds_read_b128 v[64:67], v83 offset:20480
	s_waitcnt lgkmcnt(0)
	v_mfma_f32_32x32x16_bf16 v[16:31], v[64:67], v[68:71], v[16:31]
	v_mfma_f32_32x32x16_bf16 v[0:15], v[64:67], v[72:75], v[0:15]
	ds_read_b128 v[64:67], v81 offset:16384
	v_add_u32_e32 v72, s2, v80
	ds_read_b128 v[68:71], v72
	ds_read_b128 v[72:75], v72 offset:4096
	s_waitcnt lgkmcnt(0)
	v_mfma_f32_32x32x16_bf16 v[48:63], v[64:67], v[68:71], v[48:63]
	v_mfma_f32_32x32x16_bf16 v[32:47], v[64:67], v[72:75], v[32:47]
	ds_read_b128 v[64:67], v81 offset:20480
	s_waitcnt lgkmcnt(0)
	v_mfma_f32_32x32x16_bf16 v[16:31], v[64:67], v[68:71], v[16:31]
	v_mfma_f32_32x32x16_bf16 v[0:15], v[64:67], v[72:75], v[0:15]
	ds_read_b128 v[64:67], v79 offset:16384
	v_add_u32_e32 v72, s2, v78
	ds_read_b128 v[68:71], v72
	ds_read_b128 v[72:75], v72 offset:4096
	s_waitcnt lgkmcnt(0)
	v_mfma_f32_32x32x16_bf16 v[48:63], v[64:67], v[68:71], v[48:63]
	v_mfma_f32_32x32x16_bf16 v[32:47], v[64:67], v[72:75], v[32:47]
	ds_read_b128 v[64:67], v79 offset:20480
	s_waitcnt lgkmcnt(0)
	v_mfma_f32_32x32x16_bf16 v[16:31], v[64:67], v[68:71], v[16:31]
	v_mfma_f32_32x32x16_bf16 v[0:15], v[64:67], v[72:75], v[0:15]
	ds_read_b128 v[64:67], v77 offset:16384
	v_add_u32_e32 v72, s2, v76
	ds_read_b128 v[68:71], v72
	ds_read_b128 v[72:75], v72 offset:4096
	s_waitcnt lgkmcnt(0)
	v_mfma_f32_32x32x16_bf16 v[48:63], v[64:67], v[68:71], v[48:63]
	v_mfma_f32_32x32x16_bf16 v[32:47], v[64:67], v[72:75], v[32:47]
	ds_read_b128 v[64:67], v77 offset:20480
	s_waitcnt vmcnt(0) lgkmcnt(0)
	s_barrier
	s_waitcnt lgkmcnt(0)
	v_mfma_f32_32x32x16_bf16 v[16:31], v[64:67], v[68:71], v[16:31]
	v_mfma_f32_32x32x16_bf16 v[0:15], v[64:67], v[72:75], v[0:15]

; DEV int stage_next(int s) { return (s == 2 * GS_STAGE) ? 0 : s + GS_STAGE; }
; template <int WAIT0>
; DEV void gk_main(f32x16 (&acc)[2][2], const GTile& t, int s0) {
;     ...
;   vm_wait_bar<WAIT0>();
;   int stc = s0, std_ = stage_next(stage_next(s0));
; #pragma nounroll
;   for (int kt = 0; kt < nk - 2; ++kt) {
;     GK_DMA(std_, kt + 2);
;     GK_COMPUTE(stc);
;     vm_wait_bar<6>();
;     stc = stage_next(stc); std_ = stage_next(std_);
;   }
.LBB0_415:
	s_add_i32 s10, s3, s8
	v_lshl_add_u64 v[84:85], v[74:75], 0, v[120:121]
	s_mov_b32 m0, s10
	v_lshl_add_u64 v[74:75], v[74:75], 0, s[96:97]
	global_load_lds_dwordx4 v[84:85], off
	v_lshl_add_u64 v[84:85], v[72:73], 0, v[120:121]
	s_add_i32 m0, s10, 0x2000
	v_lshl_add_u64 v[72:73], v[72:73], 0, s[96:97]
	global_load_lds_dwordx4 v[84:85], off
	s_add_i32 m0, s10, 0x4000
	v_lshl_add_u64 v[84:85], v[70:71], 0, v[120:121]
	global_load_lds_dwordx4 v[84:85], off
	v_lshl_add_u64 v[84:85], v[68:69], 0, v[120:121]
	s_add_i32 m0, s10, 0x6000
	v_lshl_add_u64 v[68:69], v[68:69], 0, s[96:97]
	global_load_lds_dwordx4 v[84:85], off
	v_lshl_add_u64 v[84:85], v[66:67], 0, v[120:121]
	s_add_i32 m0, s10, 0x8000
	v_lshl_add_u64 v[66:67], v[66:67], 0, s[96:97]
	global_load_lds_dwordx4 v[84:85], off
	v_lshl_add_u64 v[84:85], v[64:65], 0, v[120:121]
	s_add_i32 m0, s10, 0xa000
	s_add_i32 s10, s2, 0
	global_load_lds_dwordx4 v[84:85], off
	v_add_u32_e32 v252, s10, v82
	v_add_u32_e32 v253, s10, v83
	ds_read_b128 v[84:87], v252
	ds_read_b128 v[88:91], v252 offset:4096
	ds_read_b128 v[92:95], v253 offset:16384
	ds_read_b128 v[96:99], v253 offset:20480
	s_waitcnt lgkmcnt(0)
	v_lshl_add_u64 v[64:65], v[64:65], 0, s[96:97]
	v_lshl_add_u64 v[70:71], v[70:71], 0, s[96:97]
	v_add_u32_e32 v252, s10, v80
	v_add_u32_e32 v253, s10, v81
	ds_read_b128 v[236:239], v252
	ds_read_b128 v[240:243], v252 offset:4096
	ds_read_b128 v[244:247], v253 offset:16384
	ds_read_b128 v[248:251], v253 offset:20480
	v_mfma_f32_32x32x16_bf16 v[48:63], v[92:95], v[84:87], v[48:63]
	v_mfma_f32_32x32x16_bf16 v[32:47], v[92:95], v[88:91], v[32:47]
	v_mfma_f32_32x32x16_bf16 v[16:31], v[96:99], v[84:87], v[16:31]
	v_mfma_f32_32x32x16_bf16 v[0:15], v[96:99], v[88:91], v[0:15]
	s_waitcnt lgkmcnt(0)
	v_add_u32_e32 v252, s10, v78
	v_add_u32_e32 v253, s10, v79
	ds_read_b128 v[84:87], v252
	ds_read_b128 v[88:91], v252 offset:4096
	ds_read_b128 v[92:95], v253 offset:16384
	ds_read_b128 v[96:99], v253 offset:20480
	v_mfma_f32_32x32x16_bf16 v[48:63], v[244:247], v[236:239], v[48:63]
	v_mfma_f32_32x32x16_bf16 v[32:47], v[244:247], v[240:243], v[32:47]
	v_mfma_f32_32x32x16_bf16 v[16:31], v[248:251], v[236:239], v[16:31]
	v_mfma_f32_32x32x16_bf16 v[0:15], v[248:251], v[240:243], v[0:15]
	s_waitcnt lgkmcnt(0)
	v_add_u32_e32 v252, s10, v76
	v_add_u32_e32 v253, s10, v77
	ds_read_b128 v[236:239], v252
	ds_read_b128 v[240:243], v252 offset:4096
	ds_read_b128 v[244:247], v253 offset:16384
	ds_read_b128 v[248:251], v253 offset:20480
	v_mfma_f32_32x32x16_bf16 v[48:63], v[92:95], v[84:87], v[48:63]
	v_mfma_f32_32x32x16_bf16 v[32:47], v[92:95], v[88:91], v[32:47]
	v_mfma_f32_32x32x16_bf16 v[16:31], v[96:99], v[84:87], v[16:31]
	v_mfma_f32_32x32x16_bf16 v[0:15], v[96:99], v[88:91], v[0:15]
	s_add_i32 s10, s2, 0xc000
	s_cmp_lg_u32 s2, 0x18000
	s_cselect_b32 s2, s10, 0
	s_waitcnt lgkmcnt(0)
	v_mfma_f32_32x32x16_bf16 v[48:63], v[244:247], v[236:239], v[48:63]
	s_add_i32 s10, s8, 0xc000
	s_waitcnt vmcnt(6) lgkmcnt(0)
	s_barrier
	s_cmp_lg_u32 s8, 0x18000
	s_cselect_b32 s8, s10, 0
	s_add_i32 s9, s9, -1
	v_mfma_f32_32x32x16_bf16 v[32:47], v[244:247], v[240:243], v[32:47]
	s_cmp_lg_u32 s9, 0
	v_mfma_f32_32x32x16_bf16 v[16:31], v[248:251], v[236:239], v[16:31]
	v_mfma_f32_32x32x16_bf16 v[0:15], v[248:251], v[240:243], v[0:15]
	s_cbranch_scc1 .LBB0_415
; DEV int stage_next(int s) { return (s == 2 * GS_STAGE) ? 0 : s + GS_STAGE; }
; template <int WAIT0>
; DEV void gk_main(f32x16 (&acc)[2][2], const GTile& t, int s0) {
;     ...
;   GK_COMPUTE(stc);
;   vm_wait_bar<0>();
;   stc = stage_next(stc);
;   GK_COMPUTE(stc);
;   vm_wait_bar<0>();
	s_add_i32 s3, s2, 0
	v_add_u32_e32 v84, s3, v83
	ds_read_b128 v[64:67], v84 offset:16384
	v_add_u32_e32 v72, s3, v82
	ds_read_b128 v[68:71], v72
	ds_read_b128 v[72:75], v72 offset:4096
	s_waitcnt lgkmcnt(0)
	v_mfma_f32_32x32x16_bf16 v[48:63], v[64:67], v[68:71], v[48:63]
	v_mfma_f32_32x32x16_bf16 v[32:47], v[64:67], v[72:75], v[32:47]
	ds_read_b128 v[64:67], v84 offset:20480
	v_add_u32_e32 v84, s3, v81
	s_waitcnt lgkmcnt(0)
	v_mfma_f32_32x32x16_bf16 v[16:31], v[64:67], v[68:71], v[16:31]
	v_mfma_f32_32x32x16_bf16 v[0:15], v[64:67], v[72:75], v[0:15]
	ds_read_b128 v[64:67], v84 offset:16384
	v_add_u32_e32 v72, s3, v80
	ds_read_b128 v[68:71], v72
	ds_read_b128 v[72:75], v72 offset:4096
	s_waitcnt lgkmcnt(0)
	v_mfma_f32_32x32x16_bf16 v[48:63], v[64:67], v[68:71], v[48:63]
	v_mfma_f32_32x32x16_bf16 v[32:47], v[64:67], v[72:75], v[32:47]
	ds_read_b128 v[64:67], v84 offset:20480
	v_add_u32_e32 v84, s3, v79
	s_waitcnt lgkmcnt(0)
	v_mfma_f32_32x32x16_bf16 v[16:31], v[64:67], v[68:71], v[16:31]
	v_mfma_f32_32x32x16_bf16 v[0:15], v[64:67], v[72:75], v[0:15]
	ds_read_b128 v[64:67], v84 offset:16384
	v_add_u32_e32 v72, s3, v78
	ds_read_b128 v[68:71], v72
	ds_read_b128 v[72:75], v72 offset:4096
	s_waitcnt lgkmcnt(0)
	v_mfma_f32_32x32x16_bf16 v[48:63], v[64:67], v[68:71], v[48:63]
	v_mfma_f32_32x32x16_bf16 v[32:47], v[64:67], v[72:75], v[32:47]
	ds_read_b128 v[64:67], v84 offset:20480
	v_add_u32_e32 v84, s3, v77
	s_waitcnt lgkmcnt(0)
	v_mfma_f32_32x32x16_bf16 v[16:31], v[64:67], v[68:71], v[16:31]
	v_mfma_f32_32x32x16_bf16 v[0:15], v[64:67], v[72:75], v[0:15]
	ds_read_b128 v[64:67], v84 offset:16384
	v_add_u32_e32 v72, s3, v76
	ds_read_b128 v[68:71], v72
	ds_read_b128 v[72:75], v72 offset:4096
	s_add_i32 s3, s2, 0xc000
	s_cmp_lg_u32 s2, 0x18000
	s_cselect_b32 s2, s3, 0
	s_waitcnt lgkmcnt(0)
	v_mfma_f32_32x32x16_bf16 v[48:63], v[64:67], v[68:71], v[48:63]
	s_add_i32 s2, s2, 0
	v_add_u32_e32 v83, s2, v83
	v_add_u32_e32 v81, s2, v81
	v_add_u32_e32 v79, s2, v79
	v_add_u32_e32 v77, s2, v77
	v_mfma_f32_32x32x16_bf16 v[32:47], v[64:67], v[72:75], v[32:47]
	ds_read_b128 v[64:67], v84 offset:20480
	s_waitcnt vmcnt(0) lgkmcnt(0)
	s_barrier
	s_waitcnt lgkmcnt(0)
	v_mfma_f32_32x32x16_bf16 v[16:31], v[64:67], v[68:71], v[16:31]
	v_mfma_f32_32x32x16_bf16 v[0:15], v[64:67], v[72:75], v[0:15]
	ds_read_b128 v[64:67], v83 offset:16384
	v_add_u32_e32 v72, s2, v82
	ds_read_b128 v[68:71], v72
	ds_read_b128 v[72:75], v72 offset:4096
	s_waitcnt lgkmcnt(0)
	v_mfma_f32_32x32x16_bf16 v[48:63], v[64:67], v[68:71], v[48:63]
	v_mfma_f32_32x32x16_bf16 v[32:47], v[64:67], v[72:75], v[32:47]
	ds_read_b128 v[64:67], v83 offset:20480
	s_waitcnt lgkmcnt(0)
	v_mfma_f32_32x32x16_bf16 v[16:31], v[64:67], v[68:71], v[16:31]
	v_mfma_f32_32x32x16_bf16 v[0:15], v[64:67], v[72:75], v[0:15]
	ds_read_b128 v[64:67], v81 offset:16384
	v_add_u32_e32 v72, s2, v80
	ds_read_b128 v[68:71], v72
	ds_read_b128 v[72:75], v72 offset:4096
	s_waitcnt lgkmcnt(0)
	v_mfma_f32_32x32x16_bf16 v[48:63], v[64:67], v[68:71], v[48:63]
	v_mfma_f32_32x32x16_bf16 v[32:47], v[64:67], v[72:75], v[32:47]
	ds_read_b128 v[64:67], v81 offset:20480
	s_waitcnt lgkmcnt(0)
	v_mfma_f32_32x32x16_bf16 v[16:31], v[64:67], v[68:71], v[16:31]
	v_mfma_f32_32x32x16_bf16 v[0:15], v[64:67], v[72:75], v[0:15]
	ds_read_b128 v[64:67], v79 offset:16384
	v_add_u32_e32 v72, s2, v78
	ds_read_b128 v[68:71], v72
	ds_read_b128 v[72:75], v72 offset:4096
	s_waitcnt lgkmcnt(0)
	v_mfma_f32_32x32x16_bf16 v[48:63], v[64:67], v[68:71], v[48:63]
	v_mfma_f32_32x32x16_bf16 v[32:47], v[64:67], v[72:75], v[32:47]
	ds_read_b128 v[64:67], v79 offset:20480
	s_waitcnt lgkmcnt(0)
	v_mfma_f32_32x32x16_bf16 v[16:31], v[64:67], v[68:71], v[16:31]
	v_mfma_f32_32x32x16_bf16 v[0:15], v[64:67], v[72:75], v[0:15]
	ds_read_b128 v[64:67], v77 offset:16384
	v_add_u32_e32 v72, s2, v76
	ds_read_b128 v[68:71], v72
	ds_read_b128 v[72:75], v72 offset:4096
	s_waitcnt lgkmcnt(0)
	v_mfma_f32_32x32x16_bf16 v[48:63], v[64:67], v[68:71], v[48:63]
	v_mfma_f32_32x32x16_bf16 v[32:47], v[64:67], v[72:75], v[32:47]
	ds_read_b128 v[64:67], v77 offset:20480
	s_waitcnt vmcnt(0) lgkmcnt(0)
	s_barrier
	s_waitcnt lgkmcnt(0)
	v_mfma_f32_32x32x16_bf16 v[16:31], v[64:67], v[68:71], v[16:31]
	v_mfma_f32_32x32x16_bf16 v[0:15], v[64:67], v[72:75], v[0:15]
	s_add_i32 s2, s19, 1
	s_cmp_eq_u32 s19, 7
	s_mov_b64 s[8:9], 0
	s_cbranch_scc1 .LBB0_411

; DEV int stage_next(int s) { return (s == 2 * GS_STAGE) ? 0 : s + GS_STAGE; }
; template <int WAIT0>
; DEV void gk_main(f32x16 (&acc)[2][2], const GTile& t, int s0) {
;     ...
;   vm_wait_bar<WAIT0>();
;   int stc = s0, std_ = stage_next(stage_next(s0));
; #pragma nounroll
;   for (int kt = 0; kt < nk - 2; ++kt) {
;     GK_DMA(std_, kt + 2);
;     GK_COMPUTE(stc);
;     vm_wait_bar<6>();
;     stc = stage_next(stc); std_ = stage_next(std_);
;   }
.LBB0_437:
	s_add_i32 s12, s10, s11
	v_lshl_add_u64 v[84:85], v[74:75], 0, s[6:7]
	s_mov_b32 m0, s12
	s_nop 0
	global_load_lds_dwordx4 v[84:85], off
	v_lshl_add_u64 v[84:85], v[72:73], 0, s[6:7]
	s_add_i32 m0, s12, 0x2000
	s_nop 0
	global_load_lds_dwordx4 v[84:85], off
	s_add_i32 m0, s12, 0x4000
	v_lshl_add_u64 v[84:85], v[70:71], 0, s[6:7]
	global_load_lds_dwordx4 v[84:85], off
	v_lshl_add_u64 v[84:85], v[68:69], 0, s[6:7]
	s_add_i32 m0, s12, 0x6000
	s_nop 0
	global_load_lds_dwordx4 v[84:85], off
	v_lshl_add_u64 v[84:85], v[66:67], 0, s[6:7]
	s_add_i32 m0, s12, 0x8000
	s_nop 0
	global_load_lds_dwordx4 v[84:85], off
	v_lshl_add_u64 v[84:85], v[64:65], 0, s[6:7]
	s_add_i32 m0, s12, 0xa000
	s_add_i32 s12, s3, 0
	global_load_lds_dwordx4 v[84:85], off
	v_add_u32_e32 v252, s12, v82
	v_add_u32_e32 v253, s12, v83
	ds_read_b128 v[84:87], v252
	ds_read_b128 v[88:91], v252 offset:4096
	ds_read_b128 v[92:95], v253 offset:16384
	ds_read_b128 v[96:99], v253 offset:20480
	s_waitcnt lgkmcnt(0)
	v_add_u32_e32 v252, s12, v80
	v_add_u32_e32 v253, s12, v81
	ds_read_b128 v[236:239], v252
	ds_read_b128 v[240:243], v252 offset:4096
	ds_read_b128 v[244:247], v253 offset:16384
	ds_read_b128 v[248:251], v253 offset:20480
	v_mfma_f32_32x32x16_bf16 v[48:63], v[92:95], v[84:87], v[48:63]
	v_mfma_f32_32x32x16_bf16 v[16:31], v[92:95], v[88:91], v[16:31]
	v_mfma_f32_32x32x16_bf16 v[32:47], v[96:99], v[84:87], v[32:47]
	v_mfma_f32_32x32x16_bf16 v[0:15], v[96:99], v[88:91], v[0:15]
	s_waitcnt lgkmcnt(0)
	v_add_u32_e32 v252, s12, v78
	v_add_u32_e32 v253, s12, v79
	ds_read_b128 v[84:87], v252
	ds_read_b128 v[88:91], v252 offset:4096
	ds_read_b128 v[92:95], v253 offset:16384
	ds_read_b128 v[96:99], v253 offset:20480
	v_mfma_f32_32x32x16_bf16 v[48:63], v[244:247], v[236:239], v[48:63]
	v_mfma_f32_32x32x16_bf16 v[16:31], v[244:247], v[240:243], v[16:31]
	v_mfma_f32_32x32x16_bf16 v[32:47], v[248:251], v[236:239], v[32:47]
	v_mfma_f32_32x32x16_bf16 v[0:15], v[248:251], v[240:243], v[0:15]
	s_waitcnt lgkmcnt(0)
	v_add_u32_e32 v252, s12, v76
	v_add_u32_e32 v253, s12, v77
	ds_read_b128 v[236:239], v252
	ds_read_b128 v[240:243], v252 offset:4096
	ds_read_b128 v[244:247], v253 offset:16384
	ds_read_b128 v[248:251], v253 offset:20480
	v_mfma_f32_32x32x16_bf16 v[48:63], v[92:95], v[84:87], v[48:63]
	v_mfma_f32_32x32x16_bf16 v[16:31], v[92:95], v[88:91], v[16:31]
	v_mfma_f32_32x32x16_bf16 v[32:47], v[96:99], v[84:87], v[32:47]
	v_mfma_f32_32x32x16_bf16 v[0:15], v[96:99], v[88:91], v[0:15]
	s_add_i32 s12, s3, 0xc000
	s_cmp_lg_u32 s3, 0x18000
	s_cselect_b32 s3, s12, 0
	s_waitcnt lgkmcnt(0)
	v_mfma_f32_32x32x16_bf16 v[48:63], v[244:247], v[236:239], v[48:63]
	s_add_i32 s12, s11, 0xc000
	s_cmp_lg_u32 s11, 0x18000
	s_waitcnt vmcnt(6) lgkmcnt(0)
	s_barrier
	s_cselect_b32 s11, s12, 0
	s_add_u32 s6, s6, 0x80
	v_mfma_f32_32x32x16_bf16 v[16:31], v[244:247], v[240:243], v[16:31]
	s_addc_u32 s7, s7, 0
	s_cmpk_lg_i32 s6, 0x700
	v_mfma_f32_32x32x16_bf16 v[32:47], v[248:251], v[236:239], v[32:47]
	v_mfma_f32_32x32x16_bf16 v[0:15], v[248:251], v[240:243], v[0:15]
	s_cbranch_scc1 .LBB0_437
; DEV int stage_next(int s) { return (s == 2 * GS_STAGE) ? 0 : s + GS_STAGE; }
; template <int WAIT0>
; DEV void gk_main(f32x16 (&acc)[2][2], const GTile& t, int s0) {
;     ...
;   GK_COMPUTE(stc);
;   vm_wait_bar<0>();
;   stc = stage_next(stc);
;   GK_COMPUTE(stc);
;   vm_wait_bar<0>();
	s_add_i32 s6, s3, 0
	v_add_u32_e32 v84, s6, v83
	ds_read_b128 v[64:67], v84 offset:16384
	v_add_u32_e32 v72, s6, v82
	ds_read_b128 v[68:71], v72
	ds_read_b128 v[72:75], v72 offset:4096
	s_waitcnt lgkmcnt(0)
	v_mfma_f32_32x32x16_bf16 v[48:63], v[64:67], v[68:71], v[48:63]
	v_mfma_f32_32x32x16_bf16 v[16:31], v[64:67], v[72:75], v[16:31]
	ds_read_b128 v[64:67], v84 offset:20480
	v_add_u32_e32 v84, s6, v81
	s_waitcnt lgkmcnt(0)
	v_mfma_f32_32x32x16_bf16 v[32:47], v[64:67], v[68:71], v[32:47]
	v_mfma_f32_32x32x16_bf16 v[0:15], v[64:67], v[72:75], v[0:15]
	ds_read_b128 v[64:67], v84 offset:16384
	v_add_u32_e32 v72, s6, v80
	ds_read_b128 v[68:71], v72
	ds_read_b128 v[72:75], v72 offset:4096
	s_waitcnt lgkmcnt(0)
	v_mfma_f32_32x32x16_bf16 v[48:63], v[64:67], v[68:71], v[48:63]
	v_mfma_f32_32x32x16_bf16 v[16:31], v[64:67], v[72:75], v[16:31]
	ds_read_b128 v[64:67], v84 offset:20480
	v_add_u32_e32 v84, s6, v79
	s_waitcnt lgkmcnt(0)
	v_mfma_f32_32x32x16_bf16 v[32:47], v[64:67], v[68:71], v[32:47]
	v_mfma_f32_32x32x16_bf16 v[0:15], v[64:67], v[72:75], v[0:15]
	ds_read_b128 v[64:67], v84 offset:16384
	v_add_u32_e32 v72, s6, v78
	ds_read_b128 v[68:71], v72
	ds_read_b128 v[72:75], v72 offset:4096
	s_waitcnt lgkmcnt(0)
	v_mfma_f32_32x32x16_bf16 v[48:63], v[64:67], v[68:71], v[48:63]
	v_mfma_f32_32x32x16_bf16 v[16:31], v[64:67], v[72:75], v[16:31]
	ds_read_b128 v[64:67], v84 offset:20480
	v_add_u32_e32 v84, s6, v77
	s_waitcnt lgkmcnt(0)
	v_mfma_f32_32x32x16_bf16 v[32:47], v[64:67], v[68:71], v[32:47]
	v_mfma_f32_32x32x16_bf16 v[0:15], v[64:67], v[72:75], v[0:15]
	ds_read_b128 v[64:67], v84 offset:16384
	v_add_u32_e32 v72, s6, v76
	ds_read_b128 v[68:71], v72
	ds_read_b128 v[72:75], v72 offset:4096
	s_add_i32 s6, s3, 0xc000
	s_cmp_lg_u32 s3, 0x18000
	s_cselect_b32 s3, s6, 0
	s_waitcnt lgkmcnt(0)
	v_mfma_f32_32x32x16_bf16 v[48:63], v[64:67], v[68:71], v[48:63]
	s_add_i32 s3, s3, 0
	v_add_u32_e32 v83, s3, v83
	v_add_u32_e32 v81, s3, v81
	v_add_u32_e32 v79, s3, v79
	v_add_u32_e32 v77, s3, v77
	v_mfma_f32_32x32x16_bf16 v[16:31], v[64:67], v[72:75], v[16:31]
	ds_read_b128 v[64:67], v84 offset:20480
	s_waitcnt vmcnt(0) lgkmcnt(0)
	s_barrier
	s_waitcnt lgkmcnt(0)
	v_mfma_f32_32x32x16_bf16 v[32:47], v[64:67], v[68:71], v[32:47]
	v_mfma_f32_32x32x16_bf16 v[0:15], v[64:67], v[72:75], v[0:15]
	ds_read_b128 v[64:67], v83 offset:16384
	v_add_u32_e32 v72, s3, v82
	ds_read_b128 v[68:71], v72
	ds_read_b128 v[72:75], v72 offset:4096
	s_waitcnt lgkmcnt(0)
	v_mfma_f32_32x32x16_bf16 v[48:63], v[64:67], v[68:71], v[48:63]
	v_mfma_f32_32x32x16_bf16 v[16:31], v[64:67], v[72:75], v[16:31]
	ds_read_b128 v[64:67], v83 offset:20480
	s_waitcnt lgkmcnt(0)
	v_mfma_f32_32x32x16_bf16 v[32:47], v[64:67], v[68:71], v[32:47]
	v_mfma_f32_32x32x16_bf16 v[0:15], v[64:67], v[72:75], v[0:15]
	ds_read_b128 v[64:67], v81 offset:16384
	v_add_u32_e32 v72, s3, v80
	ds_read_b128 v[68:71], v72
	ds_read_b128 v[72:75], v72 offset:4096
	s_waitcnt lgkmcnt(0)
	v_mfma_f32_32x32x16_bf16 v[48:63], v[64:67], v[68:71], v[48:63]
	v_mfma_f32_32x32x16_bf16 v[16:31], v[64:67], v[72:75], v[16:31]
	ds_read_b128 v[64:67], v81 offset:20480
	s_waitcnt lgkmcnt(0)
	v_mfma_f32_32x32x16_bf16 v[32:47], v[64:67], v[68:71], v[32:47]
	v_mfma_f32_32x32x16_bf16 v[0:15], v[64:67], v[72:75], v[0:15]
	ds_read_b128 v[64:67], v79 offset:16384
	v_add_u32_e32 v72, s3, v78
	ds_read_b128 v[68:71], v72
	ds_read_b128 v[72:75], v72 offset:4096
	s_waitcnt lgkmcnt(0)
	v_mfma_f32_32x32x16_bf16 v[48:63], v[64:67], v[68:71], v[48:63]
	v_mfma_f32_32x32x16_bf16 v[16:31], v[64:67], v[72:75], v[16:31]
	ds_read_b128 v[64:67], v79 offset:20480
	s_waitcnt lgkmcnt(0)
	v_mfma_f32_32x32x16_bf16 v[32:47], v[64:67], v[68:71], v[32:47]
	v_mfma_f32_32x32x16_bf16 v[0:15], v[64:67], v[72:75], v[0:15]
	ds_read_b128 v[64:67], v77 offset:16384
	v_add_u32_e32 v72, s3, v76
	ds_read_b128 v[68:71], v72
	ds_read_b128 v[72:75], v72 offset:4096
	s_waitcnt lgkmcnt(0)
	v_mfma_f32_32x32x16_bf16 v[48:63], v[64:67], v[68:71], v[48:63]
	v_mfma_f32_32x32x16_bf16 v[16:31], v[64:67], v[72:75], v[16:31]
	ds_read_b128 v[64:67], v77 offset:20480
	s_waitcnt vmcnt(0) lgkmcnt(0)
	s_barrier
	s_waitcnt lgkmcnt(0)
	v_mfma_f32_32x32x16_bf16 v[32:47], v[64:67], v[68:71], v[32:47]
	v_mfma_f32_32x32x16_bf16 v[0:15], v[64:67], v[72:75], v[0:15]
	s_add_i32 s3, s2, 1
	s_cmp_eq_u32 s2, 7
	s_cbranch_scc1 .LBB0_423

; DEV int stage_next(int s) { return (s == 2 * GS_STAGE) ? 0 : s + GS_STAGE; }
; template <int WAIT0>
; DEV void gk_main(f32x16 (&acc)[2][2], const GTile& t, int s0) {
;     ...
;   vm_wait_bar<WAIT0>();
;   int stc = s0, std_ = stage_next(stage_next(s0));
; #pragma nounroll
;   for (int kt = 0; kt < nk - 2; ++kt) {
;     GK_DMA(std_, kt + 2);
;     GK_COMPUTE(stc);
;     vm_wait_bar<6>();
;     stc = stage_next(stc); std_ = stage_next(std_);
;   }
.LBB0_715:
	s_add_i32 s14, s3, s13
	v_lshl_add_u64 v[84:85], v[74:75], 0, s[6:7]
	s_mov_b32 m0, s14
	v_lshl_add_u64 v[86:87], v[72:73], 0, s[6:7]
	global_load_lds_dwordx4 v[84:85], off
	s_add_i32 m0, s14, 0x2000
	v_lshl_add_u64 v[88:89], v[70:71], 0, s[6:7]
	global_load_lds_dwordx4 v[86:87], off
	s_add_i32 m0, s14, 0x4000
	v_lshl_add_u64 v[90:91], v[68:69], 0, s[6:7]
	global_load_lds_dwordx4 v[88:89], off
	s_add_i32 m0, s14, 0x6000
	v_lshl_add_u64 v[92:93], v[66:67], 0, s[6:7]
	global_load_lds_dwordx4 v[90:91], off
	s_add_i32 m0, s14, 0x8000
	v_lshl_add_u64 v[94:95], v[64:65], 0, s[6:7]
	global_load_lds_dwordx4 v[92:93], off
	s_add_i32 m0, s14, 0xa000
	s_add_i32 s15, s2, 0
	global_load_lds_dwordx4 v[94:95], off
	v_add_u32_e32 v253, s15, v81
	v_add_u32_e32 v252, s15, v83
	ds_read_b128 v[84:87], v252 offset:16384
	ds_read_b128 v[88:91], v253
	ds_read_b128 v[92:95], v253 offset:4096
	ds_read_b128 v[96:99], v252 offset:20480
	s_waitcnt lgkmcnt(0)
	v_add_u32_e32 v101, s15, v82
	v_add_u32_e32 v100, s15, v79
	s_add_i32 s14, s2, 0xc000
	s_cmp_lg_u32 s2, 0x18000
	s_cselect_b32 s2, s14, 0
	s_add_i32 s14, s13, 0xc000
	s_cmp_lg_u32 s13, 0x18000
	s_cselect_b32 s13, s14, 0
	s_add_u32 s6, s6, 0x80
	s_addc_u32 s7, s7, 0
	s_cmpk_lg_i32 s6, 0x700
	ds_read_b128 v[236:239], v101 offset:16384
	ds_read_b128 v[240:243], v100
	ds_read_b128 v[244:247], v100 offset:4096
	ds_read_b128 v[248:251], v101 offset:20480
	v_mfma_f32_32x32x16_bf16 v[48:63], v[84:87], v[88:91], v[48:63]
	v_mfma_f32_32x32x16_bf16 v[16:31], v[84:87], v[92:95], v[16:31]
	v_mfma_f32_32x32x16_bf16 v[32:47], v[96:99], v[88:91], v[32:47]
	v_mfma_f32_32x32x16_bf16 v[0:15], v[96:99], v[92:95], v[0:15]
	v_add_u32_e32 v101, s15, v80
	v_add_u32_e32 v100, s15, v77
	s_waitcnt lgkmcnt(0)
	ds_read_b128 v[84:87], v101 offset:16384
	ds_read_b128 v[88:91], v100
	ds_read_b128 v[92:95], v100 offset:4096
	ds_read_b128 v[96:99], v101 offset:20480
	v_mfma_f32_32x32x16_bf16 v[48:63], v[236:239], v[240:243], v[48:63]
	v_mfma_f32_32x32x16_bf16 v[16:31], v[236:239], v[244:247], v[16:31]
	v_mfma_f32_32x32x16_bf16 v[32:47], v[248:251], v[240:243], v[32:47]
	v_mfma_f32_32x32x16_bf16 v[0:15], v[248:251], v[244:247], v[0:15]
	v_add_u32_e32 v101, s15, v78
	v_add_u32_e32 v100, s15, v76
	s_waitcnt lgkmcnt(0)
	ds_read_b128 v[236:239], v101 offset:16384
	ds_read_b128 v[240:243], v100
	ds_read_b128 v[244:247], v100 offset:4096
	ds_read_b128 v[248:251], v101 offset:20480
	v_mfma_f32_32x32x16_bf16 v[48:63], v[84:87], v[88:91], v[48:63]
	v_mfma_f32_32x32x16_bf16 v[16:31], v[84:87], v[92:95], v[16:31]
	v_mfma_f32_32x32x16_bf16 v[32:47], v[96:99], v[88:91], v[32:47]
	v_mfma_f32_32x32x16_bf16 v[0:15], v[96:99], v[92:95], v[0:15]
	s_waitcnt vmcnt(6) lgkmcnt(0)
	s_barrier
	s_waitcnt lgkmcnt(0)
	v_mfma_f32_32x32x16_bf16 v[48:63], v[236:239], v[240:243], v[48:63]
	v_mfma_f32_32x32x16_bf16 v[16:31], v[236:239], v[244:247], v[16:31]
	v_mfma_f32_32x32x16_bf16 v[32:47], v[248:251], v[240:243], v[32:47]
	v_mfma_f32_32x32x16_bf16 v[0:15], v[248:251], v[244:247], v[0:15]
	s_cbranch_scc1 .LBB0_715
; DEV int stage_next(int s) { return (s == 2 * GS_STAGE) ? 0 : s + GS_STAGE; }
; template <int WAIT0>
; DEV void gk_main(f32x16 (&acc)[2][2], const GTile& t, int s0) {
;     ...
;   GK_COMPUTE(stc);
;   vm_wait_bar<0>();
;   stc = stage_next(stc);
;   GK_COMPUTE(stc);
;   vm_wait_bar<0>();
	s_add_i32 s3, s2, 0
	v_add_u32_e32 v84, s3, v83
	ds_read_b128 v[64:67], v84 offset:16384
	v_add_u32_e32 v72, s3, v81
	ds_read_b128 v[68:71], v72
	ds_read_b128 v[72:75], v72 offset:4096
	ds_read_b128 v[84:87], v84 offset:20480
	s_mov_b64 s[6:7], 0
	s_waitcnt lgkmcnt(0)
	v_mfma_f32_32x32x16_bf16 v[32:47], v[84:87], v[68:71], v[32:47]
	v_mfma_f32_32x32x16_bf16 v[0:15], v[84:87], v[72:75], v[0:15]
	v_add_u32_e32 v84, s3, v82
	v_mfma_f32_32x32x16_bf16 v[48:63], v[64:67], v[68:71], v[48:63]
	v_mfma_f32_32x32x16_bf16 v[16:31], v[64:67], v[72:75], v[16:31]
	ds_read_b128 v[64:67], v84 offset:16384
	v_add_u32_e32 v72, s3, v79
	ds_read_b128 v[68:71], v72
	ds_read_b128 v[72:75], v72 offset:4096
	ds_read_b128 v[84:87], v84 offset:20480
	s_waitcnt lgkmcnt(0)
	v_mfma_f32_32x32x16_bf16 v[32:47], v[84:87], v[68:71], v[32:47]
	v_mfma_f32_32x32x16_bf16 v[0:15], v[84:87], v[72:75], v[0:15]
	v_add_u32_e32 v84, s3, v80
	v_mfma_f32_32x32x16_bf16 v[48:63], v[64:67], v[68:71], v[48:63]
	v_mfma_f32_32x32x16_bf16 v[16:31], v[64:67], v[72:75], v[16:31]
	ds_read_b128 v[64:67], v84 offset:16384
	v_add_u32_e32 v72, s3, v77
	ds_read_b128 v[68:71], v72
	ds_read_b128 v[72:75], v72 offset:4096
	ds_read_b128 v[84:87], v84 offset:20480
	s_waitcnt lgkmcnt(0)
	v_mfma_f32_32x32x16_bf16 v[32:47], v[84:87], v[68:71], v[32:47]
	v_mfma_f32_32x32x16_bf16 v[0:15], v[84:87], v[72:75], v[0:15]
	v_add_u32_e32 v84, s3, v78
	v_mfma_f32_32x32x16_bf16 v[48:63], v[64:67], v[68:71], v[48:63]
	v_mfma_f32_32x32x16_bf16 v[16:31], v[64:67], v[72:75], v[16:31]
	ds_read_b128 v[64:67], v84 offset:16384
	v_add_u32_e32 v72, s3, v76
	s_add_i32 s3, s2, 0xc000
	ds_read_b128 v[68:71], v72
	ds_read_b128 v[72:75], v72 offset:4096
	ds_read_b128 v[84:87], v84 offset:20480
	s_cmp_lg_u32 s2, 0x18000
	s_cselect_b32 s2, s3, 0
	s_add_i32 s2, s2, 0
	s_waitcnt vmcnt(0) lgkmcnt(0)
	s_barrier
	v_add_u32_e32 v83, s2, v83
	s_waitcnt lgkmcnt(0)
	v_mfma_f32_32x32x16_bf16 v[48:63], v[64:67], v[68:71], v[48:63]
	v_mfma_f32_32x32x16_bf16 v[16:31], v[64:67], v[72:75], v[16:31]
	ds_read_b128 v[64:67], v83 offset:16384
	v_mfma_f32_32x32x16_bf16 v[32:47], v[84:87], v[68:71], v[32:47]
	v_mfma_f32_32x32x16_bf16 v[0:15], v[84:87], v[72:75], v[0:15]
	v_add_u32_e32 v72, s2, v81
	ds_read_b128 v[68:71], v72
	ds_read_b128 v[72:75], v72 offset:4096
	ds_read_b128 v[84:87], v83 offset:20480
	v_add_u32_e32 v81, s2, v82
	s_waitcnt lgkmcnt(0)
	v_mfma_f32_32x32x16_bf16 v[48:63], v[64:67], v[68:71], v[48:63]
	v_mfma_f32_32x32x16_bf16 v[16:31], v[64:67], v[72:75], v[16:31]
	ds_read_b128 v[64:67], v81 offset:16384
	v_mfma_f32_32x32x16_bf16 v[32:47], v[84:87], v[68:71], v[32:47]
	v_mfma_f32_32x32x16_bf16 v[0:15], v[84:87], v[72:75], v[0:15]
	v_add_u32_e32 v72, s2, v79
	ds_read_b128 v[68:71], v72
	ds_read_b128 v[72:75], v72 offset:4096
	ds_read_b128 v[82:85], v81 offset:20480
	v_add_u32_e32 v79, s2, v80
	s_waitcnt lgkmcnt(0)
	v_mfma_f32_32x32x16_bf16 v[48:63], v[64:67], v[68:71], v[48:63]
	v_mfma_f32_32x32x16_bf16 v[16:31], v[64:67], v[72:75], v[16:31]
	ds_read_b128 v[64:67], v79 offset:16384
	v_mfma_f32_32x32x16_bf16 v[32:47], v[82:85], v[68:71], v[32:47]
	v_mfma_f32_32x32x16_bf16 v[0:15], v[82:85], v[72:75], v[0:15]
	v_add_u32_e32 v72, s2, v77
	ds_read_b128 v[68:71], v72
	ds_read_b128 v[72:75], v72 offset:4096
	ds_read_b128 v[80:83], v79 offset:20480
	v_add_u32_e32 v77, s2, v78
	s_waitcnt lgkmcnt(0)
	v_mfma_f32_32x32x16_bf16 v[48:63], v[64:67], v[68:71], v[48:63]
	v_mfma_f32_32x32x16_bf16 v[16:31], v[64:67], v[72:75], v[16:31]
	ds_read_b128 v[64:67], v77 offset:16384
	v_mfma_f32_32x32x16_bf16 v[32:47], v[80:83], v[68:71], v[32:47]
	v_mfma_f32_32x32x16_bf16 v[0:15], v[80:83], v[72:75], v[0:15]
	v_add_u32_e32 v72, s2, v76
	ds_read_b128 v[68:71], v72
	ds_read_b128 v[72:75], v72 offset:4096
	ds_read_b128 v[76:79], v77 offset:20480
	s_waitcnt vmcnt(0) lgkmcnt(0)
	s_barrier
	s_waitcnt lgkmcnt(0)
	v_mfma_f32_32x32x16_bf16 v[48:63], v[64:67], v[68:71], v[48:63]
	v_mfma_f32_32x32x16_bf16 v[16:31], v[64:67], v[72:75], v[16:31]
	v_mfma_f32_32x32x16_bf16 v[32:47], v[76:79], v[68:71], v[32:47]
	v_mfma_f32_32x32x16_bf16 v[0:15], v[76:79], v[72:75], v[0:15]

; DEV int stage_next(int s) { return (s == 2 * GS_STAGE) ? 0 : s + GS_STAGE; }
; template <int WAIT0>
; DEV void gk_main(f32x16 (&acc)[2][2], const GTile& t, int s0) {
;     ...
;   vm_wait_bar<WAIT0>();
;   int stc = s0, std_ = stage_next(stage_next(s0));
; #pragma nounroll
;   for (int kt = 0; kt < nk - 2; ++kt) {
;     GK_DMA(std_, kt + 2);
;     GK_COMPUTE(stc);
;     vm_wait_bar<6>();
;     stc = stage_next(stc); std_ = stage_next(std_);
;   }
.LBB0_719:
	s_add_i32 s14, s3, s13
	v_lshl_add_u64 v[84:85], v[74:75], 0, s[6:7]
	s_mov_b32 m0, s14
	v_lshl_add_u64 v[86:87], v[72:73], 0, s[6:7]
	global_load_lds_dwordx4 v[84:85], off
	s_add_i32 m0, s14, 0x2000
	v_lshl_add_u64 v[88:89], v[70:71], 0, s[6:7]
	global_load_lds_dwordx4 v[86:87], off
	s_add_i32 m0, s14, 0x4000
	v_lshl_add_u64 v[90:91], v[68:69], 0, s[6:7]
	global_load_lds_dwordx4 v[88:89], off
	s_add_i32 m0, s14, 0x6000
	v_lshl_add_u64 v[92:93], v[66:67], 0, s[6:7]
	global_load_lds_dwordx4 v[90:91], off
	s_add_i32 m0, s14, 0x8000
	v_lshl_add_u64 v[94:95], v[64:65], 0, s[6:7]
	global_load_lds_dwordx4 v[92:93], off
	s_add_i32 m0, s14, 0xa000
	s_add_i32 s15, s2, 0
	global_load_lds_dwordx4 v[94:95], off
	v_add_u32_e32 v253, s15, v81
	v_add_u32_e32 v252, s15, v83
	ds_read_b128 v[84:87], v252 offset:16384
	ds_read_b128 v[88:91], v253
	ds_read_b128 v[92:95], v253 offset:4096
	ds_read_b128 v[96:99], v252 offset:20480
	s_waitcnt lgkmcnt(0)
	v_add_u32_e32 v101, s15, v82
	v_add_u32_e32 v100, s15, v79
	s_add_i32 s14, s2, 0xc000
	s_cmp_lg_u32 s2, 0x18000
	s_cselect_b32 s2, s14, 0
	s_add_i32 s14, s13, 0xc000
	s_cmp_lg_u32 s13, 0x18000
	s_cselect_b32 s13, s14, 0
	s_add_u32 s6, s6, 0x80
	s_addc_u32 s7, s7, 0
	s_cmpk_lg_i32 s6, 0x700
	ds_read_b128 v[236:239], v101 offset:16384
	ds_read_b128 v[240:243], v100
	ds_read_b128 v[244:247], v100 offset:4096
	ds_read_b128 v[248:251], v101 offset:20480
	v_mfma_f32_32x32x16_bf16 v[48:63], v[84:87], v[88:91], v[48:63]
	v_mfma_f32_32x32x16_bf16 v[16:31], v[84:87], v[92:95], v[16:31]
	v_mfma_f32_32x32x16_bf16 v[32:47], v[96:99], v[88:91], v[32:47]
	v_mfma_f32_32x32x16_bf16 v[0:15], v[96:99], v[92:95], v[0:15]
	v_add_u32_e32 v101, s15, v80
	v_add_u32_e32 v100, s15, v77
	s_waitcnt lgkmcnt(0)
	ds_read_b128 v[84:87], v101 offset:16384
	ds_read_b128 v[88:91], v100
	ds_read_b128 v[92:95], v100 offset:4096
	ds_read_b128 v[96:99], v101 offset:20480
	v_mfma_f32_32x32x16_bf16 v[48:63], v[236:239], v[240:243], v[48:63]
	v_mfma_f32_32x32x16_bf16 v[16:31], v[236:239], v[244:247], v[16:31]
	v_mfma_f32_32x32x16_bf16 v[32:47], v[248:251], v[240:243], v[32:47]
	v_mfma_f32_32x32x16_bf16 v[0:15], v[248:251], v[244:247], v[0:15]
	v_add_u32_e32 v101, s15, v78
	v_add_u32_e32 v100, s15, v76
	s_waitcnt lgkmcnt(0)
	ds_read_b128 v[236:239], v101 offset:16384
	ds_read_b128 v[240:243], v100
	ds_read_b128 v[244:247], v100 offset:4096
	ds_read_b128 v[248:251], v101 offset:20480
	v_mfma_f32_32x32x16_bf16 v[48:63], v[84:87], v[88:91], v[48:63]
	v_mfma_f32_32x32x16_bf16 v[16:31], v[84:87], v[92:95], v[16:31]
	v_mfma_f32_32x32x16_bf16 v[32:47], v[96:99], v[88:91], v[32:47]
	v_mfma_f32_32x32x16_bf16 v[0:15], v[96:99], v[92:95], v[0:15]
	s_waitcnt vmcnt(6) lgkmcnt(0)
	s_barrier
	s_waitcnt lgkmcnt(0)
	v_mfma_f32_32x32x16_bf16 v[48:63], v[236:239], v[240:243], v[48:63]
	v_mfma_f32_32x32x16_bf16 v[16:31], v[236:239], v[244:247], v[16:31]
	v_mfma_f32_32x32x16_bf16 v[32:47], v[248:251], v[240:243], v[32:47]
	v_mfma_f32_32x32x16_bf16 v[0:15], v[248:251], v[244:247], v[0:15]
	s_cbranch_scc1 .LBB0_719
; DEV int stage_next(int s) { return (s == 2 * GS_STAGE) ? 0 : s + GS_STAGE; }
; template <int WAIT0>
; DEV void gk_main(f32x16 (&acc)[2][2], const GTile& t, int s0) {
;     ...
;   GK_COMPUTE(stc);
;   vm_wait_bar<0>();
;   stc = stage_next(stc);
;   GK_COMPUTE(stc);
;   vm_wait_bar<0>();
	s_add_i32 s3, s2, 0
	v_add_u32_e32 v84, s3, v83
	ds_read_b128 v[64:67], v84 offset:16384
	v_add_u32_e32 v72, s3, v81
	ds_read_b128 v[68:71], v72
	ds_read_b128 v[72:75], v72 offset:4096
	ds_read_b128 v[84:87], v84 offset:20480
	s_waitcnt lgkmcnt(0)
	v_mfma_f32_32x32x16_bf16 v[32:47], v[84:87], v[68:71], v[32:47]
	v_mfma_f32_32x32x16_bf16 v[0:15], v[84:87], v[72:75], v[0:15]
	v_add_u32_e32 v84, s3, v82
	v_mfma_f32_32x32x16_bf16 v[48:63], v[64:67], v[68:71], v[48:63]
	v_mfma_f32_32x32x16_bf16 v[16:31], v[64:67], v[72:75], v[16:31]
	ds_read_b128 v[64:67], v84 offset:16384
	v_add_u32_e32 v72, s3, v79
	ds_read_b128 v[68:71], v72
	ds_read_b128 v[72:75], v72 offset:4096
	ds_read_b128 v[84:87], v84 offset:20480
	s_waitcnt lgkmcnt(0)
	v_mfma_f32_32x32x16_bf16 v[32:47], v[84:87], v[68:71], v[32:47]
	v_mfma_f32_32x32x16_bf16 v[0:15], v[84:87], v[72:75], v[0:15]
	v_add_u32_e32 v84, s3, v80
	v_mfma_f32_32x32x16_bf16 v[48:63], v[64:67], v[68:71], v[48:63]
	v_mfma_f32_32x32x16_bf16 v[16:31], v[64:67], v[72:75], v[16:31]
	ds_read_b128 v[64:67], v84 offset:16384
	v_add_u32_e32 v72, s3, v77
	ds_read_b128 v[68:71], v72
	ds_read_b128 v[72:75], v72 offset:4096
	ds_read_b128 v[84:87], v84 offset:20480
	s_waitcnt lgkmcnt(0)
	v_mfma_f32_32x32x16_bf16 v[32:47], v[84:87], v[68:71], v[32:47]
	v_mfma_f32_32x32x16_bf16 v[0:15], v[84:87], v[72:75], v[0:15]
	v_add_u32_e32 v84, s3, v78
	v_mfma_f32_32x32x16_bf16 v[48:63], v[64:67], v[68:71], v[48:63]
	v_mfma_f32_32x32x16_bf16 v[16:31], v[64:67], v[72:75], v[16:31]
	ds_read_b128 v[64:67], v84 offset:16384
	v_add_u32_e32 v72, s3, v76
	s_add_i32 s3, s2, 0xc000
	ds_read_b128 v[68:71], v72
	ds_read_b128 v[72:75], v72 offset:4096
	ds_read_b128 v[84:87], v84 offset:20480
	s_cmp_lg_u32 s2, 0x18000
	s_cselect_b32 s2, s3, 0
	s_add_i32 s2, s2, 0
	s_waitcnt vmcnt(0) lgkmcnt(0)
	s_barrier
	v_add_u32_e32 v83, s2, v83
	s_waitcnt lgkmcnt(0)
	v_mfma_f32_32x32x16_bf16 v[48:63], v[64:67], v[68:71], v[48:63]
	v_mfma_f32_32x32x16_bf16 v[16:31], v[64:67], v[72:75], v[16:31]
	ds_read_b128 v[64:67], v83 offset:16384
	v_mfma_f32_32x32x16_bf16 v[32:47], v[84:87], v[68:71], v[32:47]
	v_mfma_f32_32x32x16_bf16 v[0:15], v[84:87], v[72:75], v[0:15]
	v_add_u32_e32 v72, s2, v81
	ds_read_b128 v[68:71], v72
	ds_read_b128 v[72:75], v72 offset:4096
	ds_read_b128 v[84:87], v83 offset:20480
	v_add_u32_e32 v81, s2, v82
	s_waitcnt lgkmcnt(0)
	v_mfma_f32_32x32x16_bf16 v[48:63], v[64:67], v[68:71], v[48:63]
	v_mfma_f32_32x32x16_bf16 v[16:31], v[64:67], v[72:75], v[16:31]
	ds_read_b128 v[64:67], v81 offset:16384
	v_mfma_f32_32x32x16_bf16 v[32:47], v[84:87], v[68:71], v[32:47]
	v_mfma_f32_32x32x16_bf16 v[0:15], v[84:87], v[72:75], v[0:15]
	v_add_u32_e32 v72, s2, v79
	ds_read_b128 v[68:71], v72
	ds_read_b128 v[72:75], v72 offset:4096
	ds_read_b128 v[82:85], v81 offset:20480
	v_add_u32_e32 v79, s2, v80
	s_waitcnt lgkmcnt(0)
	v_mfma_f32_32x32x16_bf16 v[48:63], v[64:67], v[68:71], v[48:63]
	v_mfma_f32_32x32x16_bf16 v[16:31], v[64:67], v[72:75], v[16:31]
	ds_read_b128 v[64:67], v79 offset:16384
	v_mfma_f32_32x32x16_bf16 v[32:47], v[82:85], v[68:71], v[32:47]
	v_mfma_f32_32x32x16_bf16 v[0:15], v[82:85], v[72:75], v[0:15]
	v_add_u32_e32 v72, s2, v77
	ds_read_b128 v[68:71], v72
	ds_read_b128 v[72:75], v72 offset:4096
	ds_read_b128 v[80:83], v79 offset:20480
	v_add_u32_e32 v77, s2, v78
	s_waitcnt lgkmcnt(0)
	v_mfma_f32_32x32x16_bf16 v[48:63], v[64:67], v[68:71], v[48:63]
	v_mfma_f32_32x32x16_bf16 v[16:31], v[64:67], v[72:75], v[16:31]
	ds_read_b128 v[64:67], v77 offset:16384
	v_mfma_f32_32x32x16_bf16 v[32:47], v[80:83], v[68:71], v[32:47]
	v_mfma_f32_32x32x16_bf16 v[0:15], v[80:83], v[72:75], v[0:15]
	v_add_u32_e32 v72, s2, v76
	ds_read_b128 v[68:71], v72
	ds_read_b128 v[72:75], v72 offset:4096
	ds_read_b128 v[76:79], v77 offset:20480
	s_waitcnt vmcnt(0) lgkmcnt(0)
	s_barrier
	s_waitcnt lgkmcnt(0)
	v_mfma_f32_32x32x16_bf16 v[48:63], v[64:67], v[68:71], v[48:63]
	v_mfma_f32_32x32x16_bf16 v[16:31], v[64:67], v[72:75], v[16:31]
	v_mfma_f32_32x32x16_bf16 v[32:47], v[76:79], v[68:71], v[32:47]
	v_mfma_f32_32x32x16_bf16 v[0:15], v[76:79], v[72:75], v[0:15]

; DEV int stage_next(int s) { return (s == 2 * GS_STAGE) ? 0 : s + GS_STAGE; }
; template <int WAIT0>
; DEV void gk_main(f32x16 (&acc)[2][2], const GTile& t, int s0) {
;     ...
;   vm_wait_bar<WAIT0>();
;   int stc = s0, std_ = stage_next(stage_next(s0));
; #pragma nounroll
;   for (int kt = 0; kt < nk - 2; ++kt) {
;     GK_DMA(std_, kt + 2);
;     GK_COMPUTE(stc);
;     vm_wait_bar<6>();
;     stc = stage_next(stc); std_ = stage_next(std_);
;   }
.LBB0_725:
	s_add_i32 s14, s3, s13
	v_lshl_add_u64 v[84:85], v[74:75], 0, s[6:7]
	s_mov_b32 m0, s14
	v_lshl_add_u64 v[86:87], v[72:73], 0, s[6:7]
	global_load_lds_dwordx4 v[84:85], off
	s_add_i32 m0, s14, 0x2000
	v_lshl_add_u64 v[88:89], v[70:71], 0, s[6:7]
	global_load_lds_dwordx4 v[86:87], off
	s_add_i32 m0, s14, 0x4000
	v_lshl_add_u64 v[90:91], v[68:69], 0, s[6:7]
	global_load_lds_dwordx4 v[88:89], off
	s_add_i32 m0, s14, 0x6000
	v_lshl_add_u64 v[92:93], v[66:67], 0, s[6:7]
	global_load_lds_dwordx4 v[90:91], off
	s_add_i32 m0, s14, 0x8000
	v_lshl_add_u64 v[94:95], v[64:65], 0, s[6:7]
	global_load_lds_dwordx4 v[92:93], off
	s_add_i32 m0, s14, 0xa000
	s_add_i32 s15, s2, 0
	global_load_lds_dwordx4 v[94:95], off
	v_add_u32_e32 v253, s15, v81
	v_add_u32_e32 v252, s15, v83
	ds_read_b128 v[84:87], v252 offset:16384
	ds_read_b128 v[88:91], v253
	ds_read_b128 v[92:95], v253 offset:4096
	ds_read_b128 v[96:99], v252 offset:20480
	s_waitcnt lgkmcnt(0)
	v_add_u32_e32 v101, s15, v82
	v_add_u32_e32 v100, s15, v79
	s_add_i32 s14, s2, 0xc000
	s_cmp_lg_u32 s2, 0x18000
	s_cselect_b32 s2, s14, 0
	s_add_i32 s14, s13, 0xc000
	s_cmp_lg_u32 s13, 0x18000
	s_cselect_b32 s13, s14, 0
	s_add_u32 s6, s6, 0x80
	s_addc_u32 s7, s7, 0
	s_cmpk_lg_i32 s6, 0x700
	ds_read_b128 v[236:239], v101 offset:16384
	ds_read_b128 v[240:243], v100
	ds_read_b128 v[244:247], v100 offset:4096
	ds_read_b128 v[248:251], v101 offset:20480
	v_mfma_f32_32x32x16_bf16 v[48:63], v[84:87], v[88:91], v[48:63]
	v_mfma_f32_32x32x16_bf16 v[16:31], v[84:87], v[92:95], v[16:31]
	v_mfma_f32_32x32x16_bf16 v[32:47], v[96:99], v[88:91], v[32:47]
	v_mfma_f32_32x32x16_bf16 v[0:15], v[96:99], v[92:95], v[0:15]
	v_add_u32_e32 v101, s15, v80
	v_add_u32_e32 v100, s15, v77
	s_waitcnt lgkmcnt(0)
	ds_read_b128 v[84:87], v101 offset:16384
	ds_read_b128 v[88:91], v100
	ds_read_b128 v[92:95], v100 offset:4096
	ds_read_b128 v[96:99], v101 offset:20480
	v_mfma_f32_32x32x16_bf16 v[48:63], v[236:239], v[240:243], v[48:63]
	v_mfma_f32_32x32x16_bf16 v[16:31], v[236:239], v[244:247], v[16:31]
	v_mfma_f32_32x32x16_bf16 v[32:47], v[248:251], v[240:243], v[32:47]
	v_mfma_f32_32x32x16_bf16 v[0:15], v[248:251], v[244:247], v[0:15]
	v_add_u32_e32 v101, s15, v78
	v_add_u32_e32 v100, s15, v76
	s_waitcnt lgkmcnt(0)
	ds_read_b128 v[236:239], v101 offset:16384
	ds_read_b128 v[240:243], v100
	ds_read_b128 v[244:247], v100 offset:4096
	ds_read_b128 v[248:251], v101 offset:20480
	v_mfma_f32_32x32x16_bf16 v[48:63], v[84:87], v[88:91], v[48:63]
	v_mfma_f32_32x32x16_bf16 v[16:31], v[84:87], v[92:95], v[16:31]
	v_mfma_f32_32x32x16_bf16 v[32:47], v[96:99], v[88:91], v[32:47]
	v_mfma_f32_32x32x16_bf16 v[0:15], v[96:99], v[92:95], v[0:15]
	s_waitcnt vmcnt(6) lgkmcnt(0)
	s_barrier
	s_waitcnt lgkmcnt(0)
	v_mfma_f32_32x32x16_bf16 v[48:63], v[236:239], v[240:243], v[48:63]
	v_mfma_f32_32x32x16_bf16 v[16:31], v[236:239], v[244:247], v[16:31]
	v_mfma_f32_32x32x16_bf16 v[32:47], v[248:251], v[240:243], v[32:47]
	v_mfma_f32_32x32x16_bf16 v[0:15], v[248:251], v[244:247], v[0:15]
	s_cbranch_scc1 .LBB0_725
; DEV int stage_next(int s) { return (s == 2 * GS_STAGE) ? 0 : s + GS_STAGE; }
; template <int WAIT0>
; DEV void gk_main(f32x16 (&acc)[2][2], const GTile& t, int s0) {
;     ...
;   GK_COMPUTE(stc);
;   vm_wait_bar<0>();
;   stc = stage_next(stc);
;   GK_COMPUTE(stc);
;   vm_wait_bar<0>();
	s_add_i32 s3, s2, 0
	v_add_u32_e32 v84, s3, v83
	ds_read_b128 v[64:67], v84 offset:16384
	v_add_u32_e32 v72, s3, v81
	ds_read_b128 v[68:71], v72
	ds_read_b128 v[72:75], v72 offset:4096
	ds_read_b128 v[84:87], v84 offset:20480
	s_waitcnt lgkmcnt(0)
	v_mfma_f32_32x32x16_bf16 v[32:47], v[84:87], v[68:71], v[32:47]
	v_mfma_f32_32x32x16_bf16 v[0:15], v[84:87], v[72:75], v[0:15]
	v_add_u32_e32 v84, s3, v82
	v_mfma_f32_32x32x16_bf16 v[48:63], v[64:67], v[68:71], v[48:63]
	v_mfma_f32_32x32x16_bf16 v[16:31], v[64:67], v[72:75], v[16:31]
	ds_read_b128 v[64:67], v84 offset:16384
	v_add_u32_e32 v72, s3, v79
	ds_read_b128 v[68:71], v72
	ds_read_b128 v[72:75], v72 offset:4096
	ds_read_b128 v[84:87], v84 offset:20480
	s_waitcnt lgkmcnt(0)
	v_mfma_f32_32x32x16_bf16 v[32:47], v[84:87], v[68:71], v[32:47]
	v_mfma_f32_32x32x16_bf16 v[0:15], v[84:87], v[72:75], v[0:15]
	v_add_u32_e32 v84, s3, v80
	v_mfma_f32_32x32x16_bf16 v[48:63], v[64:67], v[68:71], v[48:63]
	v_mfma_f32_32x32x16_bf16 v[16:31], v[64:67], v[72:75], v[16:31]
	ds_read_b128 v[64:67], v84 offset:16384
	v_add_u32_e32 v72, s3, v77
	ds_read_b128 v[68:71], v72
	ds_read_b128 v[72:75], v72 offset:4096
	ds_read_b128 v[84:87], v84 offset:20480
	s_waitcnt lgkmcnt(0)
	v_mfma_f32_32x32x16_bf16 v[32:47], v[84:87], v[68:71], v[32:47]
	v_mfma_f32_32x32x16_bf16 v[0:15], v[84:87], v[72:75], v[0:15]
	v_add_u32_e32 v84, s3, v78
	v_mfma_f32_32x32x16_bf16 v[48:63], v[64:67], v[68:71], v[48:63]
	v_mfma_f32_32x32x16_bf16 v[16:31], v[64:67], v[72:75], v[16:31]
	ds_read_b128 v[64:67], v84 offset:16384
	v_add_u32_e32 v72, s3, v76
	s_add_i32 s3, s2, 0xc000
	ds_read_b128 v[68:71], v72
	ds_read_b128 v[72:75], v72 offset:4096
	ds_read_b128 v[84:87], v84 offset:20480
	s_cmp_lg_u32 s2, 0x18000
	s_cselect_b32 s2, s3, 0
	s_add_i32 s2, s2, 0
	s_waitcnt vmcnt(0) lgkmcnt(0)
	s_barrier
	v_add_u32_e32 v83, s2, v83
	s_waitcnt lgkmcnt(0)
	v_mfma_f32_32x32x16_bf16 v[48:63], v[64:67], v[68:71], v[48:63]
	v_mfma_f32_32x32x16_bf16 v[16:31], v[64:67], v[72:75], v[16:31]
	ds_read_b128 v[64:67], v83 offset:16384
	v_mfma_f32_32x32x16_bf16 v[32:47], v[84:87], v[68:71], v[32:47]
	v_mfma_f32_32x32x16_bf16 v[0:15], v[84:87], v[72:75], v[0:15]
	v_add_u32_e32 v72, s2, v81
	ds_read_b128 v[68:71], v72
	ds_read_b128 v[72:75], v72 offset:4096
	ds_read_b128 v[84:87], v83 offset:20480
	v_add_u32_e32 v81, s2, v82
	s_waitcnt lgkmcnt(0)
	v_mfma_f32_32x32x16_bf16 v[48:63], v[64:67], v[68:71], v[48:63]
	v_mfma_f32_32x32x16_bf16 v[16:31], v[64:67], v[72:75], v[16:31]
	ds_read_b128 v[64:67], v81 offset:16384
	v_mfma_f32_32x32x16_bf16 v[32:47], v[84:87], v[68:71], v[32:47]
	v_mfma_f32_32x32x16_bf16 v[0:15], v[84:87], v[72:75], v[0:15]
	v_add_u32_e32 v72, s2, v79
	ds_read_b128 v[68:71], v72
	ds_read_b128 v[72:75], v72 offset:4096
	ds_read_b128 v[82:85], v81 offset:20480
	v_add_u32_e32 v79, s2, v80
	s_waitcnt lgkmcnt(0)
	v_mfma_f32_32x32x16_bf16 v[48:63], v[64:67], v[68:71], v[48:63]
	v_mfma_f32_32x32x16_bf16 v[16:31], v[64:67], v[72:75], v[16:31]
	ds_read_b128 v[64:67], v79 offset:16384
	v_mfma_f32_32x32x16_bf16 v[32:47], v[82:85], v[68:71], v[32:47]
	v_mfma_f32_32x32x16_bf16 v[0:15], v[82:85], v[72:75], v[0:15]
	v_add_u32_e32 v72, s2, v77
	ds_read_b128 v[68:71], v72
	ds_read_b128 v[72:75], v72 offset:4096
	ds_read_b128 v[80:83], v79 offset:20480
	v_add_u32_e32 v77, s2, v78
	s_waitcnt lgkmcnt(0)
	v_mfma_f32_32x32x16_bf16 v[48:63], v[64:67], v[68:71], v[48:63]
	v_mfma_f32_32x32x16_bf16 v[16:31], v[64:67], v[72:75], v[16:31]
	ds_read_b128 v[64:67], v77 offset:16384
	v_mfma_f32_32x32x16_bf16 v[32:47], v[80:83], v[68:71], v[32:47]
	v_mfma_f32_32x32x16_bf16 v[0:15], v[80:83], v[72:75], v[0:15]
	v_add_u32_e32 v72, s2, v76
	ds_read_b128 v[68:71], v72
	ds_read_b128 v[72:75], v72 offset:4096
	ds_read_b128 v[76:79], v77 offset:20480
	s_waitcnt vmcnt(0) lgkmcnt(0)
	s_barrier
	s_waitcnt lgkmcnt(0)
	v_mfma_f32_32x32x16_bf16 v[48:63], v[64:67], v[68:71], v[48:63]
	v_mfma_f32_32x32x16_bf16 v[16:31], v[64:67], v[72:75], v[16:31]
	v_mfma_f32_32x32x16_bf16 v[32:47], v[76:79], v[68:71], v[32:47]
	v_mfma_f32_32x32x16_bf16 v[0:15], v[76:79], v[72:75], v[0:15]
	s_add_i32 s2, s12, 1
	s_cmp_eq_u32 s12, 3
	s_cbranch_scc1 .LBB0_711

; DEV int stage_next(int s) { return (s == 2 * GS_STAGE) ? 0 : s + GS_STAGE; }
; template <int WAIT0>
; DEV void gk_main(f32x16 (&acc)[2][2], const GTile& t, int s0) {
;     ...
;   vm_wait_bar<WAIT0>();
;   int stc = s0, std_ = stage_next(stage_next(s0));
; #pragma nounroll
;   for (int kt = 0; kt < nk - 2; ++kt) {
;     GK_DMA(std_, kt + 2);
;     GK_COMPUTE(stc);
;     vm_wait_bar<6>();
;     stc = stage_next(stc); std_ = stage_next(std_);
;   }
.LBB0_737:
	s_add_i32 s20, s3, s19
	v_lshl_add_u64 v[88:89], v[76:77], 0, s[10:11]
	s_mov_b32 m0, s20
	v_lshl_add_u64 v[90:91], v[74:75], 0, s[10:11]
	global_load_lds_dwordx4 v[88:89], off
	s_add_i32 m0, s20, 0x2000
	v_lshl_add_u64 v[92:93], v[72:73], 0, s[10:11]
	global_load_lds_dwordx4 v[90:91], off
	s_add_i32 m0, s20, 0x4000
	v_lshl_add_u64 v[94:95], v[70:71], 0, s[10:11]
	global_load_lds_dwordx4 v[92:93], off
	s_add_i32 m0, s20, 0x6000
	v_lshl_add_u64 v[96:97], v[68:69], 0, s[10:11]
	global_load_lds_dwordx4 v[94:95], off
	s_add_i32 m0, s20, 0x8000
	v_lshl_add_u64 v[98:99], v[66:67], 0, s[10:11]
	global_load_lds_dwordx4 v[96:97], off
	s_add_i32 m0, s20, 0xa000
	s_add_i32 s21, s2, 0
	global_load_lds_dwordx4 v[98:99], off
	v_add_u32_e32 v252, s21, v86
	v_add_u32_e32 v87, s21, v84
	ds_read_b128 v[88:91], v252 offset:16384
	ds_read_b128 v[92:95], v87
	ds_read_b128 v[96:99], v87 offset:4096
	ds_read_b128 v[100:103], v252 offset:20480
	s_waitcnt lgkmcnt(0)
	v_add_u32_e32 v104, s21, v85
	v_add_u32_e32 v87, s21, v82
	s_add_i32 s20, s2, 0xc000
	s_cmp_lg_u32 s2, 0x18000
	s_cselect_b32 s2, s20, 0
	s_add_i32 s20, s19, 0xc000
	s_cmp_lg_u32 s19, 0x18000
	s_cselect_b32 s19, s20, 0
	s_add_u32 s10, s10, 0x80
	s_addc_u32 s11, s11, 0
	s_cmpk_lg_i32 s10, 0x700
	ds_read_b128 v[236:239], v104 offset:16384
	ds_read_b128 v[240:243], v87
	ds_read_b128 v[244:247], v87 offset:4096
	ds_read_b128 v[248:251], v104 offset:20480
	v_mfma_f32_32x32x16_bf16 v[48:63], v[88:91], v[92:95], v[48:63]
	v_mfma_f32_32x32x16_bf16 v[32:47], v[88:91], v[96:99], v[32:47]
	v_mfma_f32_32x32x16_bf16 v[16:31], v[100:103], v[92:95], v[16:31]
	v_mfma_f32_32x32x16_bf16 v[0:15], v[100:103], v[96:99], v[0:15]
	v_add_u32_e32 v104, s21, v83
	v_add_u32_e32 v87, s21, v80
	s_waitcnt lgkmcnt(0)
	ds_read_b128 v[88:91], v104 offset:16384
	ds_read_b128 v[92:95], v87
	ds_read_b128 v[96:99], v87 offset:4096
	ds_read_b128 v[100:103], v104 offset:20480
	v_mfma_f32_32x32x16_bf16 v[48:63], v[236:239], v[240:243], v[48:63]
	v_mfma_f32_32x32x16_bf16 v[32:47], v[236:239], v[244:247], v[32:47]
	v_mfma_f32_32x32x16_bf16 v[16:31], v[248:251], v[240:243], v[16:31]
	v_mfma_f32_32x32x16_bf16 v[0:15], v[248:251], v[244:247], v[0:15]
	v_add_u32_e32 v104, s21, v81
	v_add_u32_e32 v87, s21, v79
	s_waitcnt lgkmcnt(0)
	ds_read_b128 v[236:239], v104 offset:16384
	ds_read_b128 v[240:243], v87
	ds_read_b128 v[244:247], v87 offset:4096
	ds_read_b128 v[248:251], v104 offset:20480
	v_mfma_f32_32x32x16_bf16 v[48:63], v[88:91], v[92:95], v[48:63]
	v_mfma_f32_32x32x16_bf16 v[32:47], v[88:91], v[96:99], v[32:47]
	v_mfma_f32_32x32x16_bf16 v[16:31], v[100:103], v[92:95], v[16:31]
	v_mfma_f32_32x32x16_bf16 v[0:15], v[100:103], v[96:99], v[0:15]
	s_waitcnt vmcnt(6) lgkmcnt(0)
	s_barrier
	s_waitcnt lgkmcnt(0)
	v_mfma_f32_32x32x16_bf16 v[48:63], v[236:239], v[240:243], v[48:63]
	v_mfma_f32_32x32x16_bf16 v[32:47], v[236:239], v[244:247], v[32:47]
	v_mfma_f32_32x32x16_bf16 v[16:31], v[248:251], v[240:243], v[16:31]
	v_mfma_f32_32x32x16_bf16 v[0:15], v[248:251], v[244:247], v[0:15]
	s_cbranch_scc1 .LBB0_737
; DEV int stage_next(int s) { return (s == 2 * GS_STAGE) ? 0 : s + GS_STAGE; }
; template <int WAIT0>
; DEV void gk_main(f32x16 (&acc)[2][2], const GTile& t, int s0) {
;     ...
;   GK_COMPUTE(stc);
;   vm_wait_bar<0>();
;   stc = stage_next(stc);
;   GK_COMPUTE(stc);
;   vm_wait_bar<0>();
	s_add_i32 s3, s2, 0
	v_add_u32_e32 v87, s3, v86
	ds_read_b128 v[66:69], v87 offset:16384
	v_add_u32_e32 v74, s3, v84
	ds_read_b128 v[70:73], v74
	ds_read_b128 v[74:77], v74 offset:4096
	ds_read_b128 v[88:91], v87 offset:20480
	v_add_u32_e32 v87, s3, v85
	s_mov_b64 s[10:11], 0
	s_waitcnt lgkmcnt(0)
	v_mfma_f32_32x32x16_bf16 v[0:15], v[88:91], v[74:77], v[0:15]
	v_mfma_f32_32x32x16_bf16 v[48:63], v[66:69], v[70:73], v[48:63]
	v_mfma_f32_32x32x16_bf16 v[32:47], v[66:69], v[74:77], v[32:47]
	ds_read_b128 v[66:69], v87 offset:16384
	v_add_u32_e32 v74, s3, v82
	v_mfma_f32_32x32x16_bf16 v[16:31], v[88:91], v[70:73], v[16:31]
	ds_read_b128 v[70:73], v74
	ds_read_b128 v[74:77], v74 offset:4096
	ds_read_b128 v[88:91], v87 offset:20480
	v_add_u32_e32 v87, s3, v83
	s_waitcnt lgkmcnt(0)
	v_mfma_f32_32x32x16_bf16 v[48:63], v[66:69], v[70:73], v[48:63]
	v_mfma_f32_32x32x16_bf16 v[32:47], v[66:69], v[74:77], v[32:47]
	ds_read_b128 v[66:69], v87 offset:16384
	v_mfma_f32_32x32x16_bf16 v[0:15], v[88:91], v[74:77], v[0:15]
	v_add_u32_e32 v74, s3, v80
	v_mfma_f32_32x32x16_bf16 v[16:31], v[88:91], v[70:73], v[16:31]
	ds_read_b128 v[70:73], v74
	ds_read_b128 v[74:77], v74 offset:4096
	ds_read_b128 v[88:91], v87 offset:20480
	v_add_u32_e32 v87, s3, v81
	s_waitcnt lgkmcnt(0)
	v_mfma_f32_32x32x16_bf16 v[48:63], v[66:69], v[70:73], v[48:63]
	v_mfma_f32_32x32x16_bf16 v[32:47], v[66:69], v[74:77], v[32:47]
	ds_read_b128 v[66:69], v87 offset:16384
	v_mfma_f32_32x32x16_bf16 v[0:15], v[88:91], v[74:77], v[0:15]
	v_add_u32_e32 v74, s3, v79
	s_add_i32 s3, s2, 0xc000
	s_cmp_lg_u32 s2, 0x18000
	s_cselect_b32 s2, s3, 0
	s_add_i32 s2, s2, 0
	v_add_u32_e32 v86, s2, v86
	v_mfma_f32_32x32x16_bf16 v[16:31], v[88:91], v[70:73], v[16:31]
	ds_read_b128 v[70:73], v74
	ds_read_b128 v[74:77], v74 offset:4096
	ds_read_b128 v[88:91], v87 offset:20480
	s_waitcnt vmcnt(0) lgkmcnt(0)
	s_barrier
	s_waitcnt lgkmcnt(0)
	v_mfma_f32_32x32x16_bf16 v[48:63], v[66:69], v[70:73], v[48:63]
	v_mfma_f32_32x32x16_bf16 v[32:47], v[66:69], v[74:77], v[32:47]
	ds_read_b128 v[66:69], v86 offset:16384
	v_mfma_f32_32x32x16_bf16 v[16:31], v[88:91], v[70:73], v[16:31]
	v_mfma_f32_32x32x16_bf16 v[0:15], v[88:91], v[74:77], v[0:15]
	v_add_u32_e32 v74, s2, v84
	ds_read_b128 v[70:73], v74
	ds_read_b128 v[74:77], v74 offset:4096
	ds_read_b128 v[86:89], v86 offset:20480
	v_add_u32_e32 v84, s2, v85
	s_waitcnt lgkmcnt(0)
	v_mfma_f32_32x32x16_bf16 v[48:63], v[66:69], v[70:73], v[48:63]
	v_mfma_f32_32x32x16_bf16 v[32:47], v[66:69], v[74:77], v[32:47]
	ds_read_b128 v[66:69], v84 offset:16384
	v_mfma_f32_32x32x16_bf16 v[16:31], v[86:89], v[70:73], v[16:31]
	v_mfma_f32_32x32x16_bf16 v[0:15], v[86:89], v[74:77], v[0:15]
	v_add_u32_e32 v74, s2, v82
	ds_read_b128 v[70:73], v74
	ds_read_b128 v[74:77], v74 offset:4096
	ds_read_b128 v[84:87], v84 offset:20480
	v_add_u32_e32 v82, s2, v83
	s_waitcnt lgkmcnt(0)
	v_mfma_f32_32x32x16_bf16 v[48:63], v[66:69], v[70:73], v[48:63]
	v_mfma_f32_32x32x16_bf16 v[32:47], v[66:69], v[74:77], v[32:47]
	ds_read_b128 v[66:69], v82 offset:16384
	v_mfma_f32_32x32x16_bf16 v[16:31], v[84:87], v[70:73], v[16:31]
	v_mfma_f32_32x32x16_bf16 v[0:15], v[84:87], v[74:77], v[0:15]
	v_add_u32_e32 v74, s2, v80
	ds_read_b128 v[70:73], v74
	ds_read_b128 v[74:77], v74 offset:4096
	ds_read_b128 v[82:85], v82 offset:20480
	v_add_u32_e32 v80, s2, v81
	s_waitcnt lgkmcnt(0)
	v_mfma_f32_32x32x16_bf16 v[48:63], v[66:69], v[70:73], v[48:63]
	v_mfma_f32_32x32x16_bf16 v[32:47], v[66:69], v[74:77], v[32:47]
	ds_read_b128 v[66:69], v80 offset:16384
	v_mfma_f32_32x32x16_bf16 v[16:31], v[82:85], v[70:73], v[16:31]
	v_mfma_f32_32x32x16_bf16 v[0:15], v[82:85], v[74:77], v[0:15]
	v_add_u32_e32 v74, s2, v79
	ds_read_b128 v[70:73], v74
	ds_read_b128 v[74:77], v74 offset:4096
	ds_read_b128 v[80:83], v80 offset:20480
	s_waitcnt vmcnt(0) lgkmcnt(0)
	s_barrier
	s_waitcnt lgkmcnt(0)
	v_mfma_f32_32x32x16_bf16 v[48:63], v[66:69], v[70:73], v[48:63]
	v_mfma_f32_32x32x16_bf16 v[32:47], v[66:69], v[74:77], v[32:47]
	v_mfma_f32_32x32x16_bf16 v[16:31], v[80:83], v[70:73], v[16:31]
	v_mfma_f32_32x32x16_bf16 v[0:15], v[80:83], v[74:77], v[0:15]

; DEV int stage_next(int s) { return (s == 2 * GS_STAGE) ? 0 : s + GS_STAGE; }
; template <int WAIT0>
; DEV void gk_main(f32x16 (&acc)[2][2], const GTile& t, int s0) {
;     ...
;   vm_wait_bar<WAIT0>();
;   int stc = s0, std_ = stage_next(stage_next(s0));
; #pragma nounroll
;   for (int kt = 0; kt < nk - 2; ++kt) {
;     GK_DMA(std_, kt + 2);
;     GK_COMPUTE(stc);
;     vm_wait_bar<6>();
;     stc = stage_next(stc); std_ = stage_next(std_);
;   }
.LBB0_741:
	s_add_i32 s20, s3, s19
	v_lshl_add_u64 v[88:89], v[76:77], 0, s[10:11]
	s_mov_b32 m0, s20
	v_lshl_add_u64 v[90:91], v[74:75], 0, s[10:11]
	global_load_lds_dwordx4 v[88:89], off
	s_add_i32 m0, s20, 0x2000
	v_lshl_add_u64 v[92:93], v[72:73], 0, s[10:11]
	global_load_lds_dwordx4 v[90:91], off
	s_add_i32 m0, s20, 0x4000
	v_lshl_add_u64 v[94:95], v[70:71], 0, s[10:11]
	global_load_lds_dwordx4 v[92:93], off
	s_add_i32 m0, s20, 0x6000
	v_lshl_add_u64 v[96:97], v[68:69], 0, s[10:11]
	global_load_lds_dwordx4 v[94:95], off
	s_add_i32 m0, s20, 0x8000
	v_lshl_add_u64 v[98:99], v[66:67], 0, s[10:11]
	global_load_lds_dwordx4 v[96:97], off
	s_add_i32 m0, s20, 0xa000
	s_add_i32 s21, s2, 0
	global_load_lds_dwordx4 v[98:99], off
	v_add_u32_e32 v252, s21, v86
	v_add_u32_e32 v87, s21, v84
	ds_read_b128 v[88:91], v252 offset:16384
	ds_read_b128 v[92:95], v87
	ds_read_b128 v[96:99], v87 offset:4096
	ds_read_b128 v[100:103], v252 offset:20480
	s_waitcnt lgkmcnt(0)
	v_add_u32_e32 v104, s21, v85
	v_add_u32_e32 v87, s21, v82
	s_add_i32 s20, s2, 0xc000
	s_cmp_lg_u32 s2, 0x18000
	s_cselect_b32 s2, s20, 0
	s_add_i32 s20, s19, 0xc000
	s_cmp_lg_u32 s19, 0x18000
	s_cselect_b32 s19, s20, 0
	s_add_u32 s10, s10, 0x80
	s_addc_u32 s11, s11, 0
	s_cmpk_lg_i32 s10, 0x700
	ds_read_b128 v[236:239], v104 offset:16384
	ds_read_b128 v[240:243], v87
	ds_read_b128 v[244:247], v87 offset:4096
	ds_read_b128 v[248:251], v104 offset:20480
	v_mfma_f32_32x32x16_bf16 v[48:63], v[88:91], v[92:95], v[48:63]
	v_mfma_f32_32x32x16_bf16 v[32:47], v[88:91], v[96:99], v[32:47]
	v_mfma_f32_32x32x16_bf16 v[16:31], v[100:103], v[92:95], v[16:31]
	v_mfma_f32_32x32x16_bf16 v[0:15], v[100:103], v[96:99], v[0:15]
	v_add_u32_e32 v104, s21, v83
	v_add_u32_e32 v87, s21, v80
	s_waitcnt lgkmcnt(0)
	ds_read_b128 v[88:91], v104 offset:16384
	ds_read_b128 v[92:95], v87
	ds_read_b128 v[96:99], v87 offset:4096
	ds_read_b128 v[100:103], v104 offset:20480
	v_mfma_f32_32x32x16_bf16 v[48:63], v[236:239], v[240:243], v[48:63]
	v_mfma_f32_32x32x16_bf16 v[32:47], v[236:239], v[244:247], v[32:47]
	v_mfma_f32_32x32x16_bf16 v[16:31], v[248:251], v[240:243], v[16:31]
	v_mfma_f32_32x32x16_bf16 v[0:15], v[248:251], v[244:247], v[0:15]
	v_add_u32_e32 v104, s21, v81
	v_add_u32_e32 v87, s21, v79
	s_waitcnt lgkmcnt(0)
	ds_read_b128 v[236:239], v104 offset:16384
	ds_read_b128 v[240:243], v87
	ds_read_b128 v[244:247], v87 offset:4096
	ds_read_b128 v[248:251], v104 offset:20480
	v_mfma_f32_32x32x16_bf16 v[48:63], v[88:91], v[92:95], v[48:63]
	v_mfma_f32_32x32x16_bf16 v[32:47], v[88:91], v[96:99], v[32:47]
	v_mfma_f32_32x32x16_bf16 v[16:31], v[100:103], v[92:95], v[16:31]
	v_mfma_f32_32x32x16_bf16 v[0:15], v[100:103], v[96:99], v[0:15]
	s_waitcnt vmcnt(6) lgkmcnt(0)
	s_barrier
	s_waitcnt lgkmcnt(0)
	v_mfma_f32_32x32x16_bf16 v[48:63], v[236:239], v[240:243], v[48:63]
	v_mfma_f32_32x32x16_bf16 v[32:47], v[236:239], v[244:247], v[32:47]
	v_mfma_f32_32x32x16_bf16 v[16:31], v[248:251], v[240:243], v[16:31]
	v_mfma_f32_32x32x16_bf16 v[0:15], v[248:251], v[244:247], v[0:15]
	s_cbranch_scc1 .LBB0_741
; DEV int stage_next(int s) { return (s == 2 * GS_STAGE) ? 0 : s + GS_STAGE; }
; template <int WAIT0>
; DEV void gk_main(f32x16 (&acc)[2][2], const GTile& t, int s0) {
;     ...
;   GK_COMPUTE(stc);
;   vm_wait_bar<0>();
;   stc = stage_next(stc);
;   GK_COMPUTE(stc);
;   vm_wait_bar<0>();
	s_add_i32 s3, s2, 0
	v_add_u32_e32 v87, s3, v86
	ds_read_b128 v[66:69], v87 offset:16384
	v_add_u32_e32 v74, s3, v84
	ds_read_b128 v[70:73], v74
	ds_read_b128 v[74:77], v74 offset:4096
	ds_read_b128 v[88:91], v87 offset:20480
	v_add_u32_e32 v87, s3, v85
	s_waitcnt lgkmcnt(0)
	v_mfma_f32_32x32x16_bf16 v[0:15], v[88:91], v[74:77], v[0:15]
	v_mfma_f32_32x32x16_bf16 v[48:63], v[66:69], v[70:73], v[48:63]
	v_mfma_f32_32x32x16_bf16 v[32:47], v[66:69], v[74:77], v[32:47]
	ds_read_b128 v[66:69], v87 offset:16384
	v_add_u32_e32 v74, s3, v82
	v_mfma_f32_32x32x16_bf16 v[16:31], v[88:91], v[70:73], v[16:31]
	ds_read_b128 v[70:73], v74
	ds_read_b128 v[74:77], v74 offset:4096
	ds_read_b128 v[88:91], v87 offset:20480
	v_add_u32_e32 v87, s3, v83
	s_waitcnt lgkmcnt(0)
	v_mfma_f32_32x32x16_bf16 v[48:63], v[66:69], v[70:73], v[48:63]
	v_mfma_f32_32x32x16_bf16 v[32:47], v[66:69], v[74:77], v[32:47]
	ds_read_b128 v[66:69], v87 offset:16384
	v_mfma_f32_32x32x16_bf16 v[0:15], v[88:91], v[74:77], v[0:15]
	v_add_u32_e32 v74, s3, v80
	v_mfma_f32_32x32x16_bf16 v[16:31], v[88:91], v[70:73], v[16:31]
	ds_read_b128 v[70:73], v74
	ds_read_b128 v[74:77], v74 offset:4096
	ds_read_b128 v[88:91], v87 offset:20480
	v_add_u32_e32 v87, s3, v81
	s_waitcnt lgkmcnt(0)
	v_mfma_f32_32x32x16_bf16 v[48:63], v[66:69], v[70:73], v[48:63]
	v_mfma_f32_32x32x16_bf16 v[32:47], v[66:69], v[74:77], v[32:47]
	ds_read_b128 v[66:69], v87 offset:16384
	v_mfma_f32_32x32x16_bf16 v[0:15], v[88:91], v[74:77], v[0:15]
	v_add_u32_e32 v74, s3, v79
	s_add_i32 s3, s2, 0xc000
	s_cmp_lg_u32 s2, 0x18000
	s_cselect_b32 s2, s3, 0
	s_add_i32 s2, s2, 0
	v_add_u32_e32 v86, s2, v86
	v_mfma_f32_32x32x16_bf16 v[16:31], v[88:91], v[70:73], v[16:31]
	ds_read_b128 v[70:73], v74
	ds_read_b128 v[74:77], v74 offset:4096
	ds_read_b128 v[88:91], v87 offset:20480
	s_waitcnt vmcnt(0) lgkmcnt(0)
	s_barrier
	s_waitcnt lgkmcnt(0)
	v_mfma_f32_32x32x16_bf16 v[48:63], v[66:69], v[70:73], v[48:63]
	v_mfma_f32_32x32x16_bf16 v[32:47], v[66:69], v[74:77], v[32:47]
	ds_read_b128 v[66:69], v86 offset:16384
	v_mfma_f32_32x32x16_bf16 v[16:31], v[88:91], v[70:73], v[16:31]
	v_mfma_f32_32x32x16_bf16 v[0:15], v[88:91], v[74:77], v[0:15]
	v_add_u32_e32 v74, s2, v84
	ds_read_b128 v[70:73], v74
	ds_read_b128 v[74:77], v74 offset:4096
	ds_read_b128 v[86:89], v86 offset:20480
	v_add_u32_e32 v84, s2, v85
	s_waitcnt lgkmcnt(0)
	v_mfma_f32_32x32x16_bf16 v[48:63], v[66:69], v[70:73], v[48:63]
	v_mfma_f32_32x32x16_bf16 v[32:47], v[66:69], v[74:77], v[32:47]
	ds_read_b128 v[66:69], v84 offset:16384
	v_mfma_f32_32x32x16_bf16 v[16:31], v[86:89], v[70:73], v[16:31]
	v_mfma_f32_32x32x16_bf16 v[0:15], v[86:89], v[74:77], v[0:15]
	v_add_u32_e32 v74, s2, v82
	ds_read_b128 v[70:73], v74
	ds_read_b128 v[74:77], v74 offset:4096
	ds_read_b128 v[84:87], v84 offset:20480
	v_add_u32_e32 v82, s2, v83
	s_waitcnt lgkmcnt(0)
	v_mfma_f32_32x32x16_bf16 v[48:63], v[66:69], v[70:73], v[48:63]
	v_mfma_f32_32x32x16_bf16 v[32:47], v[66:69], v[74:77], v[32:47]
	ds_read_b128 v[66:69], v82 offset:16384
	v_mfma_f32_32x32x16_bf16 v[16:31], v[84:87], v[70:73], v[16:31]
	v_mfma_f32_32x32x16_bf16 v[0:15], v[84:87], v[74:77], v[0:15]
	v_add_u32_e32 v74, s2, v80
	ds_read_b128 v[70:73], v74
	ds_read_b128 v[74:77], v74 offset:4096
	ds_read_b128 v[82:85], v82 offset:20480
	v_add_u32_e32 v80, s2, v81
	s_waitcnt lgkmcnt(0)
	v_mfma_f32_32x32x16_bf16 v[48:63], v[66:69], v[70:73], v[48:63]
	v_mfma_f32_32x32x16_bf16 v[32:47], v[66:69], v[74:77], v[32:47]
	ds_read_b128 v[66:69], v80 offset:16384
	v_mfma_f32_32x32x16_bf16 v[16:31], v[82:85], v[70:73], v[16:31]
	v_mfma_f32_32x32x16_bf16 v[0:15], v[82:85], v[74:77], v[0:15]
	v_add_u32_e32 v74, s2, v79
	ds_read_b128 v[70:73], v74
	ds_read_b128 v[74:77], v74 offset:4096
	ds_read_b128 v[80:83], v80 offset:20480
	s_waitcnt vmcnt(0) lgkmcnt(0)
	s_barrier
	s_waitcnt lgkmcnt(0)
	v_mfma_f32_32x32x16_bf16 v[48:63], v[66:69], v[70:73], v[48:63]
	v_mfma_f32_32x32x16_bf16 v[32:47], v[66:69], v[74:77], v[32:47]
	v_mfma_f32_32x32x16_bf16 v[16:31], v[80:83], v[70:73], v[16:31]
	v_mfma_f32_32x32x16_bf16 v[0:15], v[80:83], v[74:77], v[0:15]

; DEV int stage_next(int s) { return (s == 2 * GS_STAGE) ? 0 : s + GS_STAGE; }
; template <int WAIT0>
; DEV void gk_main(f32x16 (&acc)[2][2], const GTile& t, int s0) {
;     ...
;   vm_wait_bar<WAIT0>();
;   int stc = s0, std_ = stage_next(stage_next(s0));
; #pragma nounroll
;   for (int kt = 0; kt < nk - 2; ++kt) {
;     GK_DMA(std_, kt + 2);
;     GK_COMPUTE(stc);
;     vm_wait_bar<6>();
;     stc = stage_next(stc); std_ = stage_next(std_);
;   }
.LBB0_747:
	s_add_i32 s19, s2, s3
	v_lshl_add_u64 v[88:89], v[76:77], 0, s[10:11]
	s_mov_b32 m0, s19
	v_lshl_add_u64 v[90:91], v[74:75], 0, s[10:11]
	global_load_lds_dwordx4 v[88:89], off
	s_add_i32 m0, s19, 0x2000
	v_lshl_add_u64 v[92:93], v[72:73], 0, s[10:11]
	global_load_lds_dwordx4 v[90:91], off
	s_add_i32 m0, s19, 0x4000
	v_lshl_add_u64 v[94:95], v[70:71], 0, s[10:11]
	global_load_lds_dwordx4 v[92:93], off
	s_add_i32 m0, s19, 0x6000
	v_lshl_add_u64 v[96:97], v[68:69], 0, s[10:11]
	global_load_lds_dwordx4 v[94:95], off
	s_add_i32 m0, s19, 0x8000
	v_lshl_add_u64 v[98:99], v[66:67], 0, s[10:11]
	global_load_lds_dwordx4 v[96:97], off
	s_add_i32 m0, s19, 0xa000
	s_add_i32 s20, s16, 0
	global_load_lds_dwordx4 v[98:99], off
	v_add_u32_e32 v252, s20, v86
	v_add_u32_e32 v87, s20, v84
	ds_read_b128 v[88:91], v252 offset:16384
	ds_read_b128 v[92:95], v87
	ds_read_b128 v[96:99], v87 offset:4096
	ds_read_b128 v[100:103], v252 offset:20480
	s_waitcnt lgkmcnt(0)
	v_add_u32_e32 v104, s20, v85
	v_add_u32_e32 v87, s20, v82
	s_add_i32 s19, s16, 0xc000
	s_cmp_lg_u32 s16, 0x18000
	s_cselect_b32 s16, s19, 0
	s_add_i32 s19, s3, 0xc000
	s_cmp_lg_u32 s3, 0x18000
	s_cselect_b32 s3, s19, 0
	s_add_u32 s10, s10, 0x80
	s_addc_u32 s11, s11, 0
	s_cmpk_lg_i32 s10, 0x700
	ds_read_b128 v[236:239], v104 offset:16384
	ds_read_b128 v[240:243], v87
	ds_read_b128 v[244:247], v87 offset:4096
	ds_read_b128 v[248:251], v104 offset:20480
	v_mfma_f32_32x32x16_bf16 v[48:63], v[88:91], v[92:95], v[48:63]
	v_mfma_f32_32x32x16_bf16 v[32:47], v[88:91], v[96:99], v[32:47]
	v_mfma_f32_32x32x16_bf16 v[16:31], v[100:103], v[92:95], v[16:31]
	v_mfma_f32_32x32x16_bf16 v[0:15], v[100:103], v[96:99], v[0:15]
	v_add_u32_e32 v104, s20, v83
	v_add_u32_e32 v87, s20, v80
	s_waitcnt lgkmcnt(0)
	ds_read_b128 v[88:91], v104 offset:16384
	ds_read_b128 v[92:95], v87
	ds_read_b128 v[96:99], v87 offset:4096
	ds_read_b128 v[100:103], v104 offset:20480
	v_mfma_f32_32x32x16_bf16 v[48:63], v[236:239], v[240:243], v[48:63]
	v_mfma_f32_32x32x16_bf16 v[32:47], v[236:239], v[244:247], v[32:47]
	v_mfma_f32_32x32x16_bf16 v[16:31], v[248:251], v[240:243], v[16:31]
	v_mfma_f32_32x32x16_bf16 v[0:15], v[248:251], v[244:247], v[0:15]
	v_add_u32_e32 v104, s20, v81
	v_add_u32_e32 v87, s20, v79
	s_waitcnt lgkmcnt(0)
	ds_read_b128 v[236:239], v104 offset:16384
	ds_read_b128 v[240:243], v87
	ds_read_b128 v[244:247], v87 offset:4096
	ds_read_b128 v[248:251], v104 offset:20480
	v_mfma_f32_32x32x16_bf16 v[48:63], v[88:91], v[92:95], v[48:63]
	v_mfma_f32_32x32x16_bf16 v[32:47], v[88:91], v[96:99], v[32:47]
	v_mfma_f32_32x32x16_bf16 v[16:31], v[100:103], v[92:95], v[16:31]
	v_mfma_f32_32x32x16_bf16 v[0:15], v[100:103], v[96:99], v[0:15]
	s_waitcnt vmcnt(6) lgkmcnt(0)
	s_barrier
	s_waitcnt lgkmcnt(0)
	v_mfma_f32_32x32x16_bf16 v[48:63], v[236:239], v[240:243], v[48:63]
	v_mfma_f32_32x32x16_bf16 v[32:47], v[236:239], v[244:247], v[32:47]
	v_mfma_f32_32x32x16_bf16 v[16:31], v[248:251], v[240:243], v[16:31]
	v_mfma_f32_32x32x16_bf16 v[0:15], v[248:251], v[244:247], v[0:15]
	s_cbranch_scc1 .LBB0_747
; DEV int stage_next(int s) { return (s == 2 * GS_STAGE) ? 0 : s + GS_STAGE; }
; template <int WAIT0>
; DEV void gk_main(f32x16 (&acc)[2][2], const GTile& t, int s0) {
;     ...
;   GK_COMPUTE(stc);
;   vm_wait_bar<0>();
;   stc = stage_next(stc);
;   GK_COMPUTE(stc);
;   vm_wait_bar<0>();
	s_add_i32 s2, s16, 0
	v_add_u32_e32 v87, s2, v86
	ds_read_b128 v[66:69], v87 offset:16384
	v_add_u32_e32 v74, s2, v84
	ds_read_b128 v[70:73], v74
	ds_read_b128 v[74:77], v74 offset:4096
	ds_read_b128 v[88:91], v87 offset:20480
	v_add_u32_e32 v87, s2, v85
	s_waitcnt lgkmcnt(0)
	v_mfma_f32_32x32x16_bf16 v[0:15], v[88:91], v[74:77], v[0:15]
	v_mfma_f32_32x32x16_bf16 v[48:63], v[66:69], v[70:73], v[48:63]
	v_mfma_f32_32x32x16_bf16 v[32:47], v[66:69], v[74:77], v[32:47]
	ds_read_b128 v[66:69], v87 offset:16384
	v_add_u32_e32 v74, s2, v82
	v_mfma_f32_32x32x16_bf16 v[16:31], v[88:91], v[70:73], v[16:31]
	ds_read_b128 v[70:73], v74
	ds_read_b128 v[74:77], v74 offset:4096
	ds_read_b128 v[88:91], v87 offset:20480
	v_add_u32_e32 v87, s2, v83
	s_waitcnt lgkmcnt(0)
	v_mfma_f32_32x32x16_bf16 v[48:63], v[66:69], v[70:73], v[48:63]
	v_mfma_f32_32x32x16_bf16 v[32:47], v[66:69], v[74:77], v[32:47]
	ds_read_b128 v[66:69], v87 offset:16384
	v_mfma_f32_32x32x16_bf16 v[0:15], v[88:91], v[74:77], v[0:15]
	v_add_u32_e32 v74, s2, v80
	v_mfma_f32_32x32x16_bf16 v[16:31], v[88:91], v[70:73], v[16:31]
	ds_read_b128 v[70:73], v74
	ds_read_b128 v[74:77], v74 offset:4096
	ds_read_b128 v[88:91], v87 offset:20480
	v_add_u32_e32 v87, s2, v81
	s_waitcnt lgkmcnt(0)
	v_mfma_f32_32x32x16_bf16 v[48:63], v[66:69], v[70:73], v[48:63]
	v_mfma_f32_32x32x16_bf16 v[32:47], v[66:69], v[74:77], v[32:47]
	ds_read_b128 v[66:69], v87 offset:16384
	v_mfma_f32_32x32x16_bf16 v[0:15], v[88:91], v[74:77], v[0:15]
	v_add_u32_e32 v74, s2, v79
	s_add_i32 s2, s16, 0xc000
	s_cmp_lg_u32 s16, 0x18000
	s_cselect_b32 s2, s2, 0
	s_add_i32 s2, s2, 0
	v_add_u32_e32 v86, s2, v86
	v_mfma_f32_32x32x16_bf16 v[16:31], v[88:91], v[70:73], v[16:31]
	ds_read_b128 v[70:73], v74
	ds_read_b128 v[74:77], v74 offset:4096
	ds_read_b128 v[88:91], v87 offset:20480
	s_waitcnt vmcnt(0) lgkmcnt(0)
	s_barrier
	s_waitcnt lgkmcnt(0)
	v_mfma_f32_32x32x16_bf16 v[48:63], v[66:69], v[70:73], v[48:63]
	v_mfma_f32_32x32x16_bf16 v[32:47], v[66:69], v[74:77], v[32:47]
	ds_read_b128 v[66:69], v86 offset:16384
	v_mfma_f32_32x32x16_bf16 v[16:31], v[88:91], v[70:73], v[16:31]
	v_mfma_f32_32x32x16_bf16 v[0:15], v[88:91], v[74:77], v[0:15]
	v_add_u32_e32 v74, s2, v84
	ds_read_b128 v[70:73], v74
	ds_read_b128 v[74:77], v74 offset:4096
	ds_read_b128 v[86:89], v86 offset:20480
	v_add_u32_e32 v84, s2, v85
	s_waitcnt lgkmcnt(0)
	v_mfma_f32_32x32x16_bf16 v[48:63], v[66:69], v[70:73], v[48:63]
	v_mfma_f32_32x32x16_bf16 v[32:47], v[66:69], v[74:77], v[32:47]
	ds_read_b128 v[66:69], v84 offset:16384
	v_mfma_f32_32x32x16_bf16 v[16:31], v[86:89], v[70:73], v[16:31]
	v_mfma_f32_32x32x16_bf16 v[0:15], v[86:89], v[74:77], v[0:15]
	v_add_u32_e32 v74, s2, v82
	ds_read_b128 v[70:73], v74
	ds_read_b128 v[74:77], v74 offset:4096
	ds_read_b128 v[84:87], v84 offset:20480
	v_add_u32_e32 v82, s2, v83
	s_waitcnt lgkmcnt(0)
	v_mfma_f32_32x32x16_bf16 v[48:63], v[66:69], v[70:73], v[48:63]
	v_mfma_f32_32x32x16_bf16 v[32:47], v[66:69], v[74:77], v[32:47]
	ds_read_b128 v[66:69], v82 offset:16384
	v_mfma_f32_32x32x16_bf16 v[16:31], v[84:87], v[70:73], v[16:31]
	v_mfma_f32_32x32x16_bf16 v[0:15], v[84:87], v[74:77], v[0:15]
	v_add_u32_e32 v74, s2, v80
	ds_read_b128 v[70:73], v74
	ds_read_b128 v[74:77], v74 offset:4096
	ds_read_b128 v[82:85], v82 offset:20480
	v_add_u32_e32 v80, s2, v81
	s_waitcnt lgkmcnt(0)
	v_mfma_f32_32x32x16_bf16 v[48:63], v[66:69], v[70:73], v[48:63]
	v_mfma_f32_32x32x16_bf16 v[32:47], v[66:69], v[74:77], v[32:47]
	ds_read_b128 v[66:69], v80 offset:16384
	v_mfma_f32_32x32x16_bf16 v[16:31], v[82:85], v[70:73], v[16:31]
	v_mfma_f32_32x32x16_bf16 v[0:15], v[82:85], v[74:77], v[0:15]
	v_add_u32_e32 v74, s2, v79
	ds_read_b128 v[70:73], v74
	ds_read_b128 v[74:77], v74 offset:4096
	ds_read_b128 v[80:83], v80 offset:20480
	s_waitcnt vmcnt(0) lgkmcnt(0)
	s_barrier
	s_waitcnt lgkmcnt(0)
	v_mfma_f32_32x32x16_bf16 v[48:63], v[66:69], v[70:73], v[48:63]
	v_mfma_f32_32x32x16_bf16 v[32:47], v[66:69], v[74:77], v[32:47]
	v_mfma_f32_32x32x16_bf16 v[16:31], v[80:83], v[70:73], v[16:31]
	v_mfma_f32_32x32x16_bf16 v[0:15], v[80:83], v[74:77], v[0:15]
	s_add_i32 s2, s17, 1
	s_mov_b32 s16, s18
	s_cmp_eq_u32 s17, 3
	s_cbranch_scc1 .LBB0_733

; DEV int stage_next(int s) { return (s == 2 * GS_STAGE) ? 0 : s + GS_STAGE; }
; template <int WAIT0>
; DEV void gk_main(f32x16 (&acc)[2][2], const GTile& t, int s0) {
;     ...
;   vm_wait_bar<WAIT0>();
;   int stc = s0, std_ = stage_next(stage_next(s0));
; #pragma nounroll
;   for (int kt = 0; kt < nk - 2; ++kt) {
;     GK_DMA(std_, kt + 2);
;     GK_COMPUTE(stc);
;     vm_wait_bar<6>();
;     stc = stage_next(stc); std_ = stage_next(std_);
;   }
.LBB0_842:
	s_add_i32 s10, s2, s3
	v_lshl_add_u64 v[84:85], v[74:75], 0, v[120:121]
	s_mov_b32 m0, s10
	v_lshl_add_u64 v[86:87], v[72:73], 0, v[120:121]
	global_load_lds_dwordx4 v[84:85], off
	s_add_i32 m0, s10, 0x2000
	v_lshl_add_u64 v[88:89], v[70:71], 0, v[120:121]
	global_load_lds_dwordx4 v[86:87], off
	s_add_i32 m0, s10, 0x4000
	v_lshl_add_u64 v[90:91], v[68:69], 0, v[120:121]
	global_load_lds_dwordx4 v[88:89], off
	s_add_i32 m0, s10, 0x6000
	v_lshl_add_u64 v[92:93], v[66:67], 0, v[120:121]
	global_load_lds_dwordx4 v[90:91], off
	s_add_i32 m0, s10, 0x8000
	v_lshl_add_u64 v[94:95], v[64:65], 0, v[120:121]
	global_load_lds_dwordx4 v[92:93], off
	s_add_i32 m0, s10, 0xa000
	s_add_i32 s11, s9, 0
	global_load_lds_dwordx4 v[94:95], off
	v_add_u32_e32 v253, s11, v81
	v_add_u32_e32 v252, s11, v83
	ds_read_b128 v[84:87], v252 offset:16384
	ds_read_b128 v[88:91], v253
	ds_read_b128 v[92:95], v253 offset:4096
	ds_read_b128 v[96:99], v252 offset:20480
	s_waitcnt lgkmcnt(0)
	v_add_u32_e32 v101, s11, v82
	v_add_u32_e32 v100, s11, v79
	s_add_i32 s10, s9, 0xc000
	s_cmp_lg_u32 s9, 0x18000
	s_cselect_b32 s9, s10, 0
	s_add_i32 s10, s3, 0xc000
	s_cmp_lg_u32 s3, 0x18000
	s_cselect_b32 s3, s10, 0
	s_add_i32 s8, s8, -1
	v_lshl_add_u64 v[64:65], v[64:65], 0, s[94:95]
	v_lshl_add_u64 v[66:67], v[66:67], 0, s[94:95]
	v_lshl_add_u64 v[68:69], v[68:69], 0, s[94:95]
	v_lshl_add_u64 v[70:71], v[70:71], 0, s[94:95]
	v_lshl_add_u64 v[72:73], v[72:73], 0, s[94:95]
	s_cmp_lg_u32 s8, 0
	v_lshl_add_u64 v[74:75], v[74:75], 0, s[94:95]
	ds_read_b128 v[236:239], v101 offset:16384
	ds_read_b128 v[240:243], v100
	ds_read_b128 v[244:247], v100 offset:4096
	ds_read_b128 v[248:251], v101 offset:20480
	v_mfma_f32_32x32x16_bf16 v[48:63], v[84:87], v[88:91], v[48:63]
	v_mfma_f32_32x32x16_bf16 v[32:47], v[84:87], v[92:95], v[32:47]
	v_mfma_f32_32x32x16_bf16 v[16:31], v[96:99], v[88:91], v[16:31]
	v_mfma_f32_32x32x16_bf16 v[0:15], v[96:99], v[92:95], v[0:15]
	v_add_u32_e32 v101, s11, v80
	v_add_u32_e32 v100, s11, v77
	s_waitcnt lgkmcnt(0)
	ds_read_b128 v[84:87], v101 offset:16384
	ds_read_b128 v[88:91], v100
	ds_read_b128 v[92:95], v100 offset:4096
	ds_read_b128 v[96:99], v101 offset:20480
	v_mfma_f32_32x32x16_bf16 v[48:63], v[236:239], v[240:243], v[48:63]
	v_mfma_f32_32x32x16_bf16 v[32:47], v[236:239], v[244:247], v[32:47]
	v_mfma_f32_32x32x16_bf16 v[16:31], v[248:251], v[240:243], v[16:31]
	v_mfma_f32_32x32x16_bf16 v[0:15], v[248:251], v[244:247], v[0:15]
	v_add_u32_e32 v101, s11, v78
	v_add_u32_e32 v100, s11, v76
	s_waitcnt lgkmcnt(0)
	ds_read_b128 v[236:239], v101 offset:16384
	ds_read_b128 v[240:243], v100
	ds_read_b128 v[244:247], v100 offset:4096
	ds_read_b128 v[248:251], v101 offset:20480
	v_mfma_f32_32x32x16_bf16 v[48:63], v[84:87], v[88:91], v[48:63]
	v_mfma_f32_32x32x16_bf16 v[32:47], v[84:87], v[92:95], v[32:47]
	v_mfma_f32_32x32x16_bf16 v[16:31], v[96:99], v[88:91], v[16:31]
	v_mfma_f32_32x32x16_bf16 v[0:15], v[96:99], v[92:95], v[0:15]
	s_waitcnt vmcnt(6) lgkmcnt(0)
	s_barrier
	s_waitcnt lgkmcnt(0)
	v_mfma_f32_32x32x16_bf16 v[48:63], v[236:239], v[240:243], v[48:63]
	v_mfma_f32_32x32x16_bf16 v[32:47], v[236:239], v[244:247], v[32:47]
	v_mfma_f32_32x32x16_bf16 v[16:31], v[248:251], v[240:243], v[16:31]
	v_mfma_f32_32x32x16_bf16 v[0:15], v[248:251], v[244:247], v[0:15]
	s_cbranch_scc1 .LBB0_842
; DEV int stage_next(int s) { return (s == 2 * GS_STAGE) ? 0 : s + GS_STAGE; }
; template <int WAIT0>
; DEV void gk_main(f32x16 (&acc)[2][2], const GTile& t, int s0) {
;     ...
;   GK_COMPUTE(stc);
;   vm_wait_bar<0>();
;   stc = stage_next(stc);
;   GK_COMPUTE(stc);
;   vm_wait_bar<0>();
	s_add_i32 s2, s9, 0
	v_add_u32_e32 v84, s2, v83
	ds_read_b128 v[64:67], v84 offset:16384
	v_add_u32_e32 v72, s2, v81
	ds_read_b128 v[68:71], v72
	ds_read_b128 v[72:75], v72 offset:4096
	ds_read_b128 v[84:87], v84 offset:20480
	s_waitcnt lgkmcnt(0)
	v_mfma_f32_32x32x16_bf16 v[16:31], v[84:87], v[68:71], v[16:31]
	v_mfma_f32_32x32x16_bf16 v[0:15], v[84:87], v[72:75], v[0:15]
	v_add_u32_e32 v84, s2, v82
	v_mfma_f32_32x32x16_bf16 v[48:63], v[64:67], v[68:71], v[48:63]
	v_mfma_f32_32x32x16_bf16 v[32:47], v[64:67], v[72:75], v[32:47]
	ds_read_b128 v[64:67], v84 offset:16384
	v_add_u32_e32 v72, s2, v79
	ds_read_b128 v[68:71], v72
	ds_read_b128 v[72:75], v72 offset:4096
	ds_read_b128 v[84:87], v84 offset:20480
	s_waitcnt lgkmcnt(0)
	v_mfma_f32_32x32x16_bf16 v[16:31], v[84:87], v[68:71], v[16:31]
	v_mfma_f32_32x32x16_bf16 v[0:15], v[84:87], v[72:75], v[0:15]
	v_add_u32_e32 v84, s2, v80
	v_mfma_f32_32x32x16_bf16 v[48:63], v[64:67], v[68:71], v[48:63]
	v_mfma_f32_32x32x16_bf16 v[32:47], v[64:67], v[72:75], v[32:47]
	ds_read_b128 v[64:67], v84 offset:16384
	v_add_u32_e32 v72, s2, v77
	ds_read_b128 v[68:71], v72
	ds_read_b128 v[72:75], v72 offset:4096
	ds_read_b128 v[84:87], v84 offset:20480
	s_waitcnt lgkmcnt(0)
	v_mfma_f32_32x32x16_bf16 v[16:31], v[84:87], v[68:71], v[16:31]
	v_mfma_f32_32x32x16_bf16 v[0:15], v[84:87], v[72:75], v[0:15]
	v_add_u32_e32 v84, s2, v78
	v_mfma_f32_32x32x16_bf16 v[48:63], v[64:67], v[68:71], v[48:63]
	v_mfma_f32_32x32x16_bf16 v[32:47], v[64:67], v[72:75], v[32:47]
	ds_read_b128 v[64:67], v84 offset:16384
	v_add_u32_e32 v72, s2, v76
	s_add_i32 s2, s9, 0xc000
	ds_read_b128 v[68:71], v72
	ds_read_b128 v[72:75], v72 offset:4096
	ds_read_b128 v[84:87], v84 offset:20480
	s_cmp_lg_u32 s9, 0x18000
	s_cselect_b32 s2, s2, 0
	s_add_i32 s2, s2, 0
	s_waitcnt vmcnt(0) lgkmcnt(0)
	s_barrier
	v_add_u32_e32 v83, s2, v83
	s_waitcnt lgkmcnt(0)
	v_mfma_f32_32x32x16_bf16 v[48:63], v[64:67], v[68:71], v[48:63]
	s_mov_b64 s[8:9], 0
	v_mfma_f32_32x32x16_bf16 v[32:47], v[64:67], v[72:75], v[32:47]
	ds_read_b128 v[64:67], v83 offset:16384
	v_mfma_f32_32x32x16_bf16 v[16:31], v[84:87], v[68:71], v[16:31]
	v_mfma_f32_32x32x16_bf16 v[0:15], v[84:87], v[72:75], v[0:15]
	v_add_u32_e32 v72, s2, v81
	ds_read_b128 v[68:71], v72
	ds_read_b128 v[72:75], v72 offset:4096
	ds_read_b128 v[84:87], v83 offset:20480
	v_add_u32_e32 v81, s2, v82
	s_waitcnt lgkmcnt(0)
	v_mfma_f32_32x32x16_bf16 v[48:63], v[64:67], v[68:71], v[48:63]
	v_mfma_f32_32x32x16_bf16 v[32:47], v[64:67], v[72:75], v[32:47]
	ds_read_b128 v[64:67], v81 offset:16384
	v_mfma_f32_32x32x16_bf16 v[16:31], v[84:87], v[68:71], v[16:31]
	v_mfma_f32_32x32x16_bf16 v[0:15], v[84:87], v[72:75], v[0:15]
	v_add_u32_e32 v72, s2, v79
	ds_read_b128 v[68:71], v72
	ds_read_b128 v[72:75], v72 offset:4096
	ds_read_b128 v[82:85], v81 offset:20480
	v_add_u32_e32 v79, s2, v80
	s_waitcnt lgkmcnt(0)
	v_mfma_f32_32x32x16_bf16 v[48:63], v[64:67], v[68:71], v[48:63]
	v_mfma_f32_32x32x16_bf16 v[32:47], v[64:67], v[72:75], v[32:47]
	ds_read_b128 v[64:67], v79 offset:16384
	v_mfma_f32_32x32x16_bf16 v[16:31], v[82:85], v[68:71], v[16:31]
	v_mfma_f32_32x32x16_bf16 v[0:15], v[82:85], v[72:75], v[0:15]
	v_add_u32_e32 v72, s2, v77
	ds_read_b128 v[68:71], v72
	ds_read_b128 v[72:75], v72 offset:4096
	ds_read_b128 v[80:83], v79 offset:20480
	v_add_u32_e32 v77, s2, v78
	s_waitcnt lgkmcnt(0)
	v_mfma_f32_32x32x16_bf16 v[48:63], v[64:67], v[68:71], v[48:63]
	v_mfma_f32_32x32x16_bf16 v[32:47], v[64:67], v[72:75], v[32:47]
	ds_read_b128 v[64:67], v77 offset:16384
	v_mfma_f32_32x32x16_bf16 v[16:31], v[80:83], v[68:71], v[16:31]
	v_mfma_f32_32x32x16_bf16 v[0:15], v[80:83], v[72:75], v[0:15]
	v_add_u32_e32 v72, s2, v76
	ds_read_b128 v[68:71], v72
	ds_read_b128 v[72:75], v72 offset:4096
	ds_read_b128 v[76:79], v77 offset:20480
	s_waitcnt vmcnt(0) lgkmcnt(0)
	s_barrier
	s_waitcnt lgkmcnt(0)
	v_mfma_f32_32x32x16_bf16 v[48:63], v[64:67], v[68:71], v[48:63]
	v_mfma_f32_32x32x16_bf16 v[32:47], v[64:67], v[72:75], v[32:47]
	v_mfma_f32_32x32x16_bf16 v[16:31], v[76:79], v[68:71], v[16:31]
	v_mfma_f32_32x32x16_bf16 v[0:15], v[76:79], v[72:75], v[0:15]

; DEV int stage_next(int s) { return (s == 2 * GS_STAGE) ? 0 : s + GS_STAGE; }
; template <int WAIT0>
; DEV void gk_main(f32x16 (&acc)[2][2], const GTile& t, int s0) {
;     ...
;   vm_wait_bar<WAIT0>();
;   int stc = s0, std_ = stage_next(stage_next(s0));
; #pragma nounroll
;   for (int kt = 0; kt < nk - 2; ++kt) {
;     GK_DMA(std_, kt + 2);
;     GK_COMPUTE(stc);
;     vm_wait_bar<6>();
;     stc = stage_next(stc); std_ = stage_next(std_);
;   }
.LBB0_846:
	s_add_i32 s10, s2, s3
	v_lshl_add_u64 v[84:85], v[74:75], 0, v[120:121]
	s_mov_b32 m0, s10
	v_lshl_add_u64 v[86:87], v[72:73], 0, v[120:121]
	global_load_lds_dwordx4 v[84:85], off
	s_add_i32 m0, s10, 0x2000
	v_lshl_add_u64 v[88:89], v[70:71], 0, v[120:121]
	global_load_lds_dwordx4 v[86:87], off
	s_add_i32 m0, s10, 0x4000
	v_lshl_add_u64 v[90:91], v[68:69], 0, v[120:121]
	global_load_lds_dwordx4 v[88:89], off
	s_add_i32 m0, s10, 0x6000
	v_lshl_add_u64 v[92:93], v[66:67], 0, v[120:121]
	global_load_lds_dwordx4 v[90:91], off
	s_add_i32 m0, s10, 0x8000
	v_lshl_add_u64 v[94:95], v[64:65], 0, v[120:121]
	global_load_lds_dwordx4 v[92:93], off
	s_add_i32 m0, s10, 0xa000
	s_add_i32 s11, s9, 0
	global_load_lds_dwordx4 v[94:95], off
	v_add_u32_e32 v253, s11, v81
	v_add_u32_e32 v252, s11, v83
	ds_read_b128 v[84:87], v252 offset:16384
	ds_read_b128 v[88:91], v253
	ds_read_b128 v[92:95], v253 offset:4096
	ds_read_b128 v[96:99], v252 offset:20480
	s_waitcnt lgkmcnt(0)
	v_add_u32_e32 v101, s11, v82
	v_add_u32_e32 v100, s11, v79
	s_add_i32 s10, s9, 0xc000
	s_cmp_lg_u32 s9, 0x18000
	s_cselect_b32 s9, s10, 0
	s_add_i32 s10, s3, 0xc000
	s_cmp_lg_u32 s3, 0x18000
	s_cselect_b32 s3, s10, 0
	s_add_i32 s8, s8, -1
	v_lshl_add_u64 v[64:65], v[64:65], 0, s[94:95]
	v_lshl_add_u64 v[66:67], v[66:67], 0, s[94:95]
	v_lshl_add_u64 v[68:69], v[68:69], 0, s[94:95]
	v_lshl_add_u64 v[70:71], v[70:71], 0, s[94:95]
	v_lshl_add_u64 v[72:73], v[72:73], 0, s[94:95]
	s_cmp_lg_u32 s8, 0
	v_lshl_add_u64 v[74:75], v[74:75], 0, s[94:95]
	ds_read_b128 v[236:239], v101 offset:16384
	ds_read_b128 v[240:243], v100
	ds_read_b128 v[244:247], v100 offset:4096
	ds_read_b128 v[248:251], v101 offset:20480
	v_mfma_f32_32x32x16_bf16 v[48:63], v[84:87], v[88:91], v[48:63]
	v_mfma_f32_32x32x16_bf16 v[32:47], v[84:87], v[92:95], v[32:47]
	v_mfma_f32_32x32x16_bf16 v[16:31], v[96:99], v[88:91], v[16:31]
	v_mfma_f32_32x32x16_bf16 v[0:15], v[96:99], v[92:95], v[0:15]
	v_add_u32_e32 v101, s11, v80
	v_add_u32_e32 v100, s11, v77
	s_waitcnt lgkmcnt(0)
	ds_read_b128 v[84:87], v101 offset:16384
	ds_read_b128 v[88:91], v100
	ds_read_b128 v[92:95], v100 offset:4096
	ds_read_b128 v[96:99], v101 offset:20480
	v_mfma_f32_32x32x16_bf16 v[48:63], v[236:239], v[240:243], v[48:63]
	v_mfma_f32_32x32x16_bf16 v[32:47], v[236:239], v[244:247], v[32:47]
	v_mfma_f32_32x32x16_bf16 v[16:31], v[248:251], v[240:243], v[16:31]
	v_mfma_f32_32x32x16_bf16 v[0:15], v[248:251], v[244:247], v[0:15]
	v_add_u32_e32 v101, s11, v78
	v_add_u32_e32 v100, s11, v76
	s_waitcnt lgkmcnt(0)
	ds_read_b128 v[236:239], v101 offset:16384
	ds_read_b128 v[240:243], v100
	ds_read_b128 v[244:247], v100 offset:4096
	ds_read_b128 v[248:251], v101 offset:20480
	v_mfma_f32_32x32x16_bf16 v[48:63], v[84:87], v[88:91], v[48:63]
	v_mfma_f32_32x32x16_bf16 v[32:47], v[84:87], v[92:95], v[32:47]
	v_mfma_f32_32x32x16_bf16 v[16:31], v[96:99], v[88:91], v[16:31]
	v_mfma_f32_32x32x16_bf16 v[0:15], v[96:99], v[92:95], v[0:15]
	s_waitcnt vmcnt(6) lgkmcnt(0)
	s_barrier
	s_waitcnt lgkmcnt(0)
	v_mfma_f32_32x32x16_bf16 v[48:63], v[236:239], v[240:243], v[48:63]
	v_mfma_f32_32x32x16_bf16 v[32:47], v[236:239], v[244:247], v[32:47]
	v_mfma_f32_32x32x16_bf16 v[16:31], v[248:251], v[240:243], v[16:31]
	v_mfma_f32_32x32x16_bf16 v[0:15], v[248:251], v[244:247], v[0:15]
	s_cbranch_scc1 .LBB0_846
; DEV int stage_next(int s) { return (s == 2 * GS_STAGE) ? 0 : s + GS_STAGE; }
; template <int WAIT0>
; DEV void gk_main(f32x16 (&acc)[2][2], const GTile& t, int s0) {
;     ...
;   GK_COMPUTE(stc);
;   vm_wait_bar<0>();
;   stc = stage_next(stc);
;   GK_COMPUTE(stc);
;   vm_wait_bar<0>();
	s_add_i32 s2, s9, 0
	v_add_u32_e32 v84, s2, v83
	ds_read_b128 v[64:67], v84 offset:16384
	v_add_u32_e32 v72, s2, v81
	ds_read_b128 v[68:71], v72
	ds_read_b128 v[72:75], v72 offset:4096
	ds_read_b128 v[84:87], v84 offset:20480
	s_waitcnt lgkmcnt(0)
	v_mfma_f32_32x32x16_bf16 v[16:31], v[84:87], v[68:71], v[16:31]
	v_mfma_f32_32x32x16_bf16 v[0:15], v[84:87], v[72:75], v[0:15]
	v_add_u32_e32 v84, s2, v82
	v_mfma_f32_32x32x16_bf16 v[48:63], v[64:67], v[68:71], v[48:63]
	v_mfma_f32_32x32x16_bf16 v[32:47], v[64:67], v[72:75], v[32:47]
	ds_read_b128 v[64:67], v84 offset:16384
	v_add_u32_e32 v72, s2, v79
	ds_read_b128 v[68:71], v72
	ds_read_b128 v[72:75], v72 offset:4096
	ds_read_b128 v[84:87], v84 offset:20480
	s_waitcnt lgkmcnt(0)
	v_mfma_f32_32x32x16_bf16 v[16:31], v[84:87], v[68:71], v[16:31]
	v_mfma_f32_32x32x16_bf16 v[0:15], v[84:87], v[72:75], v[0:15]
	v_add_u32_e32 v84, s2, v80
	v_mfma_f32_32x32x16_bf16 v[48:63], v[64:67], v[68:71], v[48:63]
	v_mfma_f32_32x32x16_bf16 v[32:47], v[64:67], v[72:75], v[32:47]
	ds_read_b128 v[64:67], v84 offset:16384
	v_add_u32_e32 v72, s2, v77
	ds_read_b128 v[68:71], v72
	ds_read_b128 v[72:75], v72 offset:4096
	ds_read_b128 v[84:87], v84 offset:20480
	s_waitcnt lgkmcnt(0)
	v_mfma_f32_32x32x16_bf16 v[16:31], v[84:87], v[68:71], v[16:31]
	v_mfma_f32_32x32x16_bf16 v[0:15], v[84:87], v[72:75], v[0:15]
	v_add_u32_e32 v84, s2, v78
	v_mfma_f32_32x32x16_bf16 v[48:63], v[64:67], v[68:71], v[48:63]
	v_mfma_f32_32x32x16_bf16 v[32:47], v[64:67], v[72:75], v[32:47]
	ds_read_b128 v[64:67], v84 offset:16384
	v_add_u32_e32 v72, s2, v76
	s_add_i32 s2, s9, 0xc000
	ds_read_b128 v[68:71], v72
	ds_read_b128 v[72:75], v72 offset:4096
	ds_read_b128 v[84:87], v84 offset:20480
	s_cmp_lg_u32 s9, 0x18000
	s_cselect_b32 s2, s2, 0
	s_add_i32 s2, s2, 0
	s_waitcnt vmcnt(0) lgkmcnt(0)
	s_barrier
	v_add_u32_e32 v83, s2, v83
	s_waitcnt lgkmcnt(0)
	v_mfma_f32_32x32x16_bf16 v[48:63], v[64:67], v[68:71], v[48:63]
	v_mfma_f32_32x32x16_bf16 v[32:47], v[64:67], v[72:75], v[32:47]
	ds_read_b128 v[64:67], v83 offset:16384
	v_mfma_f32_32x32x16_bf16 v[16:31], v[84:87], v[68:71], v[16:31]
	v_mfma_f32_32x32x16_bf16 v[0:15], v[84:87], v[72:75], v[0:15]
	v_add_u32_e32 v72, s2, v81
	ds_read_b128 v[68:71], v72
	ds_read_b128 v[72:75], v72 offset:4096
	ds_read_b128 v[84:87], v83 offset:20480
	v_add_u32_e32 v81, s2, v82
	s_waitcnt lgkmcnt(0)
	v_mfma_f32_32x32x16_bf16 v[48:63], v[64:67], v[68:71], v[48:63]
	v_mfma_f32_32x32x16_bf16 v[32:47], v[64:67], v[72:75], v[32:47]
	ds_read_b128 v[64:67], v81 offset:16384
	v_mfma_f32_32x32x16_bf16 v[16:31], v[84:87], v[68:71], v[16:31]
	v_mfma_f32_32x32x16_bf16 v[0:15], v[84:87], v[72:75], v[0:15]
	v_add_u32_e32 v72, s2, v79
	ds_read_b128 v[68:71], v72
	ds_read_b128 v[72:75], v72 offset:4096
	ds_read_b128 v[82:85], v81 offset:20480
	v_add_u32_e32 v79, s2, v80
	s_waitcnt lgkmcnt(0)
	v_mfma_f32_32x32x16_bf16 v[48:63], v[64:67], v[68:71], v[48:63]
	v_mfma_f32_32x32x16_bf16 v[32:47], v[64:67], v[72:75], v[32:47]
	ds_read_b128 v[64:67], v79 offset:16384
	v_mfma_f32_32x32x16_bf16 v[16:31], v[82:85], v[68:71], v[16:31]
	v_mfma_f32_32x32x16_bf16 v[0:15], v[82:85], v[72:75], v[0:15]
	v_add_u32_e32 v72, s2, v77
	ds_read_b128 v[68:71], v72
	ds_read_b128 v[72:75], v72 offset:4096
	ds_read_b128 v[80:83], v79 offset:20480
	v_add_u32_e32 v77, s2, v78
	s_waitcnt lgkmcnt(0)
	v_mfma_f32_32x32x16_bf16 v[48:63], v[64:67], v[68:71], v[48:63]
	v_mfma_f32_32x32x16_bf16 v[32:47], v[64:67], v[72:75], v[32:47]
	ds_read_b128 v[64:67], v77 offset:16384
	v_mfma_f32_32x32x16_bf16 v[16:31], v[80:83], v[68:71], v[16:31]
	v_mfma_f32_32x32x16_bf16 v[0:15], v[80:83], v[72:75], v[0:15]
	v_add_u32_e32 v72, s2, v76
	ds_read_b128 v[68:71], v72
	ds_read_b128 v[72:75], v72 offset:4096
	ds_read_b128 v[76:79], v77 offset:20480
	s_waitcnt vmcnt(0) lgkmcnt(0)
	s_barrier
	s_waitcnt lgkmcnt(0)
	v_mfma_f32_32x32x16_bf16 v[48:63], v[64:67], v[68:71], v[48:63]
	v_mfma_f32_32x32x16_bf16 v[32:47], v[64:67], v[72:75], v[32:47]
	v_mfma_f32_32x32x16_bf16 v[16:31], v[76:79], v[68:71], v[16:31]
	v_mfma_f32_32x32x16_bf16 v[0:15], v[76:79], v[72:75], v[0:15]

; DEV int stage_next(int s) { return (s == 2 * GS_STAGE) ? 0 : s + GS_STAGE; }
; template <int WAIT0>
; DEV void gk_main(f32x16 (&acc)[2][2], const GTile& t, int s0) {
;     ...
;   vm_wait_bar<WAIT0>();
;   int stc = s0, std_ = stage_next(stage_next(s0));
; #pragma nounroll
;   for (int kt = 0; kt < nk - 2; ++kt) {
;     GK_DMA(std_, kt + 2);
;     GK_COMPUTE(stc);
;     vm_wait_bar<6>();
;     stc = stage_next(stc); std_ = stage_next(std_);
;   }
.LBB0_854:
	s_add_i32 s10, s2, s3
	v_lshl_add_u64 v[84:85], v[74:75], 0, v[120:121]
	s_mov_b32 m0, s10
	v_lshl_add_u64 v[86:87], v[72:73], 0, v[120:121]
	global_load_lds_dwordx4 v[84:85], off
	s_add_i32 m0, s10, 0x2000
	v_lshl_add_u64 v[88:89], v[70:71], 0, v[120:121]
	global_load_lds_dwordx4 v[86:87], off
	s_add_i32 m0, s10, 0x4000
	v_lshl_add_u64 v[90:91], v[68:69], 0, v[120:121]
	global_load_lds_dwordx4 v[88:89], off
	s_add_i32 m0, s10, 0x6000
	v_lshl_add_u64 v[92:93], v[66:67], 0, v[120:121]
	global_load_lds_dwordx4 v[90:91], off
	s_add_i32 m0, s10, 0x8000
	v_lshl_add_u64 v[94:95], v[64:65], 0, v[120:121]
	global_load_lds_dwordx4 v[92:93], off
	s_add_i32 m0, s10, 0xa000
	s_add_i32 s11, s9, 0
	global_load_lds_dwordx4 v[94:95], off
	v_add_u32_e32 v253, s11, v81
	v_add_u32_e32 v252, s11, v83
	ds_read_b128 v[84:87], v252 offset:16384
	ds_read_b128 v[88:91], v253
	ds_read_b128 v[92:95], v253 offset:4096
	ds_read_b128 v[96:99], v252 offset:20480
	s_waitcnt lgkmcnt(0)
	v_add_u32_e32 v101, s11, v82
	v_add_u32_e32 v100, s11, v79
	s_add_i32 s10, s9, 0xc000
	s_cmp_lg_u32 s9, 0x18000
	s_cselect_b32 s9, s10, 0
	s_add_i32 s10, s3, 0xc000
	s_cmp_lg_u32 s3, 0x18000
	s_cselect_b32 s3, s10, 0
	s_add_i32 s8, s8, -1
	v_lshl_add_u64 v[64:65], v[64:65], 0, s[94:95]
	v_lshl_add_u64 v[66:67], v[66:67], 0, s[94:95]
	v_lshl_add_u64 v[68:69], v[68:69], 0, s[94:95]
	v_lshl_add_u64 v[70:71], v[70:71], 0, s[94:95]
	v_lshl_add_u64 v[72:73], v[72:73], 0, s[94:95]
	s_cmp_lg_u32 s8, 0
	v_lshl_add_u64 v[74:75], v[74:75], 0, s[94:95]
	ds_read_b128 v[236:239], v101 offset:16384
	ds_read_b128 v[240:243], v100
	ds_read_b128 v[244:247], v100 offset:4096
	ds_read_b128 v[248:251], v101 offset:20480
	v_mfma_f32_32x32x16_bf16 v[48:63], v[84:87], v[88:91], v[48:63]
	v_mfma_f32_32x32x16_bf16 v[32:47], v[84:87], v[92:95], v[32:47]
	v_mfma_f32_32x32x16_bf16 v[16:31], v[96:99], v[88:91], v[16:31]
	v_mfma_f32_32x32x16_bf16 v[0:15], v[96:99], v[92:95], v[0:15]
	v_add_u32_e32 v101, s11, v80
	v_add_u32_e32 v100, s11, v77
	s_waitcnt lgkmcnt(0)
	ds_read_b128 v[84:87], v101 offset:16384
	ds_read_b128 v[88:91], v100
	ds_read_b128 v[92:95], v100 offset:4096
	ds_read_b128 v[96:99], v101 offset:20480
	v_mfma_f32_32x32x16_bf16 v[48:63], v[236:239], v[240:243], v[48:63]
	v_mfma_f32_32x32x16_bf16 v[32:47], v[236:239], v[244:247], v[32:47]
	v_mfma_f32_32x32x16_bf16 v[16:31], v[248:251], v[240:243], v[16:31]
	v_mfma_f32_32x32x16_bf16 v[0:15], v[248:251], v[244:247], v[0:15]
	v_add_u32_e32 v101, s11, v78
	v_add_u32_e32 v100, s11, v76
	s_waitcnt lgkmcnt(0)
	ds_read_b128 v[236:239], v101 offset:16384
	ds_read_b128 v[240:243], v100
	ds_read_b128 v[244:247], v100 offset:4096
	ds_read_b128 v[248:251], v101 offset:20480
	v_mfma_f32_32x32x16_bf16 v[48:63], v[84:87], v[88:91], v[48:63]
	v_mfma_f32_32x32x16_bf16 v[32:47], v[84:87], v[92:95], v[32:47]
	v_mfma_f32_32x32x16_bf16 v[16:31], v[96:99], v[88:91], v[16:31]
	v_mfma_f32_32x32x16_bf16 v[0:15], v[96:99], v[92:95], v[0:15]
	s_waitcnt vmcnt(6) lgkmcnt(0)
	s_barrier
	s_waitcnt lgkmcnt(0)
	v_mfma_f32_32x32x16_bf16 v[48:63], v[236:239], v[240:243], v[48:63]
	v_mfma_f32_32x32x16_bf16 v[32:47], v[236:239], v[244:247], v[32:47]
	v_mfma_f32_32x32x16_bf16 v[16:31], v[248:251], v[240:243], v[16:31]
	v_mfma_f32_32x32x16_bf16 v[0:15], v[248:251], v[244:247], v[0:15]
	s_cbranch_scc1 .LBB0_854
; DEV int stage_next(int s) { return (s == 2 * GS_STAGE) ? 0 : s + GS_STAGE; }
; template <int WAIT0>
; DEV void gk_main(f32x16 (&acc)[2][2], const GTile& t, int s0) {
;     ...
;   vm_wait_bar<WAIT0>();
;   int stc = s0, std_ = stage_next(stage_next(s0));
; #pragma nounroll
;   for (int kt = 0; kt < nk - 2; ++kt) {
;     GK_DMA(std_, kt + 2);
;     GK_COMPUTE(stc);
;     vm_wait_bar<6>();
;     stc = stage_next(stc); std_ = stage_next(std_);
;   }
;   GK_COMPUTE(stc);
;   vm_wait_bar<0>();
;   stc = stage_next(stc);
;   GK_COMPUTE(stc);
;   vm_wait_bar<0>();
	s_add_i32 s2, s9, 0
	v_add_u32_e32 v84, s2, v83
	ds_read_b128 v[64:67], v84 offset:16384
	v_add_u32_e32 v72, s2, v81
	ds_read_b128 v[68:71], v72
	ds_read_b128 v[72:75], v72 offset:4096
	ds_read_b128 v[84:87], v84 offset:20480
	s_waitcnt lgkmcnt(0)
	v_mfma_f32_32x32x16_bf16 v[16:31], v[84:87], v[68:71], v[16:31]
	v_mfma_f32_32x32x16_bf16 v[0:15], v[84:87], v[72:75], v[0:15]
	v_add_u32_e32 v84, s2, v82
	v_mfma_f32_32x32x16_bf16 v[48:63], v[64:67], v[68:71], v[48:63]
	v_mfma_f32_32x32x16_bf16 v[32:47], v[64:67], v[72:75], v[32:47]
	ds_read_b128 v[64:67], v84 offset:16384
	v_add_u32_e32 v72, s2, v79
	ds_read_b128 v[68:71], v72
	ds_read_b128 v[72:75], v72 offset:4096
	ds_read_b128 v[84:87], v84 offset:20480
	s_waitcnt lgkmcnt(0)
	v_mfma_f32_32x32x16_bf16 v[16:31], v[84:87], v[68:71], v[16:31]
	v_mfma_f32_32x32x16_bf16 v[0:15], v[84:87], v[72:75], v[0:15]
	v_add_u32_e32 v84, s2, v80
	v_mfma_f32_32x32x16_bf16 v[48:63], v[64:67], v[68:71], v[48:63]
	v_mfma_f32_32x32x16_bf16 v[32:47], v[64:67], v[72:75], v[32:47]
	ds_read_b128 v[64:67], v84 offset:16384
	v_add_u32_e32 v72, s2, v77
	ds_read_b128 v[68:71], v72
	ds_read_b128 v[72:75], v72 offset:4096
	ds_read_b128 v[84:87], v84 offset:20480
	s_waitcnt lgkmcnt(0)
	v_mfma_f32_32x32x16_bf16 v[16:31], v[84:87], v[68:71], v[16:31]
	v_mfma_f32_32x32x16_bf16 v[0:15], v[84:87], v[72:75], v[0:15]
	v_add_u32_e32 v84, s2, v78
	v_mfma_f32_32x32x16_bf16 v[48:63], v[64:67], v[68:71], v[48:63]
	v_mfma_f32_32x32x16_bf16 v[32:47], v[64:67], v[72:75], v[32:47]
	ds_read_b128 v[64:67], v84 offset:16384
	v_add_u32_e32 v72, s2, v76
	s_add_i32 s2, s9, 0xc000
	ds_read_b128 v[68:71], v72
	ds_read_b128 v[72:75], v72 offset:4096
	ds_read_b128 v[84:87], v84 offset:20480
	s_cmp_lg_u32 s9, 0x18000
	s_cselect_b32 s2, s2, 0
	s_add_i32 s2, s2, 0
	s_waitcnt vmcnt(0) lgkmcnt(0)
	s_barrier
	v_add_u32_e32 v83, s2, v83
	s_waitcnt lgkmcnt(0)
	v_mfma_f32_32x32x16_bf16 v[48:63], v[64:67], v[68:71], v[48:63]
	v_mfma_f32_32x32x16_bf16 v[32:47], v[64:67], v[72:75], v[32:47]
	ds_read_b128 v[64:67], v83 offset:16384
	v_mfma_f32_32x32x16_bf16 v[16:31], v[84:87], v[68:71], v[16:31]
	v_mfma_f32_32x32x16_bf16 v[0:15], v[84:87], v[72:75], v[0:15]
	v_add_u32_e32 v72, s2, v81
	ds_read_b128 v[68:71], v72
	ds_read_b128 v[72:75], v72 offset:4096
	ds_read_b128 v[84:87], v83 offset:20480
	v_add_u32_e32 v81, s2, v82
	s_waitcnt lgkmcnt(0)
	v_mfma_f32_32x32x16_bf16 v[48:63], v[64:67], v[68:71], v[48:63]
	v_mfma_f32_32x32x16_bf16 v[32:47], v[64:67], v[72:75], v[32:47]
	ds_read_b128 v[64:67], v81 offset:16384
	v_mfma_f32_32x32x16_bf16 v[16:31], v[84:87], v[68:71], v[16:31]
	v_mfma_f32_32x32x16_bf16 v[0:15], v[84:87], v[72:75], v[0:15]
	v_add_u32_e32 v72, s2, v79
	ds_read_b128 v[68:71], v72
	ds_read_b128 v[72:75], v72 offset:4096
	ds_read_b128 v[82:85], v81 offset:20480
	v_add_u32_e32 v79, s2, v80
	s_waitcnt lgkmcnt(0)
	v_mfma_f32_32x32x16_bf16 v[48:63], v[64:67], v[68:71], v[48:63]
	v_mfma_f32_32x32x16_bf16 v[32:47], v[64:67], v[72:75], v[32:47]
	ds_read_b128 v[64:67], v79 offset:16384
	v_mfma_f32_32x32x16_bf16 v[16:31], v[82:85], v[68:71], v[16:31]
	v_mfma_f32_32x32x16_bf16 v[0:15], v[82:85], v[72:75], v[0:15]
	v_add_u32_e32 v72, s2, v77
	ds_read_b128 v[68:71], v72
	ds_read_b128 v[72:75], v72 offset:4096
	ds_read_b128 v[80:83], v79 offset:20480
	v_add_u32_e32 v77, s2, v78
	s_waitcnt lgkmcnt(0)
	v_mfma_f32_32x32x16_bf16 v[48:63], v[64:67], v[68:71], v[48:63]
	v_mfma_f32_32x32x16_bf16 v[32:47], v[64:67], v[72:75], v[32:47]
	ds_read_b128 v[64:67], v77 offset:16384
	v_mfma_f32_32x32x16_bf16 v[16:31], v[80:83], v[68:71], v[16:31]
	v_mfma_f32_32x32x16_bf16 v[0:15], v[80:83], v[72:75], v[0:15]
	v_add_u32_e32 v72, s2, v76
	ds_read_b128 v[68:71], v72
	ds_read_b128 v[72:75], v72 offset:4096
	ds_read_b128 v[76:79], v77 offset:20480
	s_waitcnt vmcnt(0) lgkmcnt(0)
	s_barrier
	s_waitcnt lgkmcnt(0)
	v_mfma_f32_32x32x16_bf16 v[48:63], v[64:67], v[68:71], v[48:63]
	v_mfma_f32_32x32x16_bf16 v[32:47], v[64:67], v[72:75], v[32:47]
	v_mfma_f32_32x32x16_bf16 v[16:31], v[76:79], v[68:71], v[16:31]
	v_mfma_f32_32x32x16_bf16 v[0:15], v[76:79], v[72:75], v[0:15]
	s_add_i32 s2, s19, 1
	s_cmp_eq_u32 s19, 7
	s_mov_b64 s[8:9], 0
	s_cbranch_scc1 .LBB0_850
